# K-loops: mid-segment 's_setprio 0; s_setprio 1' pair removed (priority stays raised over the 32 MFMAs), on top of previous edits
# baseline (speedup 1.0000x reference)
.LBB0_153:
	ds_read_b128 v[0:3], v145
	ds_read_b128 v[4:7], v145 offset:1024
	ds_read_b128 v[8:11], v145 offset:2048
	ds_read_b128 v[12:15], v145 offset:3072
	ds_read_b128 v[16:19], v146
	ds_read_b128 v[20:23], v146 offset:1024
	ds_read_b128 v[24:27], v146 offset:2048
	ds_read_b128 v[28:31], v146 offset:3072
	s_ashr_i32 s37, s36, 31
	s_lshl_b64 s[46:47], s[36:37], 17
	s_add_u32 s46, s44, s46
	s_addc_u32 s47, s45, s47
	s_and_b64 s[48:49], s[4:5], exec
	s_cselect_b32 s59, s47, s53
	s_cselect_b32 s58, s46, s52
	s_ashr_i32 s35, s34, 31
	s_lshl_b64 s[48:49], s[34:35], 17
	s_add_u32 s48, s60, s48
	s_addc_u32 s49, s61, s49
	s_and_b64 s[56:57], s[4:5], exec
	s_cselect_b32 s57, s49, s55
	s_cselect_b32 s56, s48, s54
	s_add_u32 s80, s52, 0x10080
	s_addc_u32 s81, s53, 0
	s_add_i32 s83, s51, 0xc000
	v_lshl_add_u64 v[64:65], s[80:81], 0, v[128:129]
	s_mov_b32 m0, s83
	s_add_i32 s35, s51, 0xe000
	ds_read_b128 v[32:35], v147
	ds_read_b128 v[36:39], v147 offset:1024
	ds_read_b128 v[40:43], v147 offset:2048
	ds_read_b128 v[44:47], v147 offset:3072
	ds_read_b128 v[48:51], v147 offset:4096
	ds_read_b128 v[52:55], v147 offset:5120
	ds_read_b128 v[56:59], v147 offset:6144
	ds_read_b128 v[60:63], v147 offset:7168
	global_load_lds_dwordx4 v[64:65], off
	v_lshl_add_u64 v[64:65], s[80:81], 0, v[132:133]
	s_mov_b32 m0, s35
	s_nop 0
	global_load_lds_dwordx4 v[64:65], off
	s_waitcnt vmcnt(8)
	s_waitcnt lgkmcnt(0)
	s_barrier
	s_setprio 1
	v_mfma_f32_16x16x32_bf16 v[64:67], v[0:3], v[32:35], 0
	v_mfma_f32_16x16x32_bf16 v[68:71], v[8:11], v[32:35], 0
	v_mfma_f32_16x16x32_bf16 v[72:75], v[0:3], v[40:43], 0
	v_mfma_f32_16x16x32_bf16 v[76:79], v[8:11], v[40:43], 0
	v_mfma_f32_16x16x32_bf16 v[80:83], v[0:3], v[48:51], 0
	v_mfma_f32_16x16x32_bf16 v[84:87], v[8:11], v[48:51], 0
	v_mfma_f32_16x16x32_bf16 v[88:91], v[0:3], v[56:59], 0
	v_mfma_f32_16x16x32_bf16 v[92:95], v[8:11], v[56:59], 0
	v_mfma_f32_16x16x32_bf16 v[64:67], v[4:7], v[36:39], v[64:67]
	v_mfma_f32_16x16x32_bf16 v[68:71], v[12:15], v[36:39], v[68:71]
	v_mfma_f32_16x16x32_bf16 v[72:75], v[4:7], v[44:47], v[72:75]
	v_mfma_f32_16x16x32_bf16 v[76:79], v[12:15], v[44:47], v[76:79]
	v_mfma_f32_16x16x32_bf16 v[80:83], v[4:7], v[52:55], v[80:83]
	v_mfma_f32_16x16x32_bf16 v[84:87], v[12:15], v[52:55], v[84:87]
	v_mfma_f32_16x16x32_bf16 v[88:91], v[4:7], v[60:63], v[88:91]
	v_mfma_f32_16x16x32_bf16 v[92:95], v[12:15], v[60:63], v[92:95]
	v_mfma_f32_16x16x32_bf16 v[96:99], v[16:19], v[32:35], 0
	v_mfma_f32_16x16x32_bf16 v[32:35], v[24:27], v[32:35], 0
	v_mfma_f32_16x16x32_bf16 v[96:99], v[20:23], v[36:39], v[96:99]
	v_mfma_f32_16x16x32_bf16 v[32:35], v[28:31], v[36:39], v[32:35]
	v_mfma_f32_16x16x32_bf16 v[36:39], v[16:19], v[40:43], 0
	v_mfma_f32_16x16x32_bf16 v[40:43], v[24:27], v[40:43], 0
	v_mfma_f32_16x16x32_bf16 v[36:39], v[20:23], v[44:47], v[36:39]
	v_mfma_f32_16x16x32_bf16 v[40:43], v[28:31], v[44:47], v[40:43]
	v_mfma_f32_16x16x32_bf16 v[44:47], v[16:19], v[48:51], 0
	v_mfma_f32_16x16x32_bf16 v[48:51], v[24:27], v[48:51], 0
	v_mfma_f32_16x16x32_bf16 v[44:47], v[20:23], v[52:55], v[44:47]
	v_mfma_f32_16x16x32_bf16 v[48:51], v[28:31], v[52:55], v[48:51]
	v_mfma_f32_16x16x32_bf16 v[52:55], v[16:19], v[56:59], 0
	v_mfma_f32_16x16x32_bf16 v[56:59], v[24:27], v[56:59], 0
	v_mfma_f32_16x16x32_bf16 v[52:55], v[20:23], v[60:63], v[52:55]
	v_mfma_f32_16x16x32_bf16 v[56:59], v[28:31], v[60:63], v[56:59]
	s_setprio 0
	s_barrier
	s_add_i32 s81, s72, s62
	v_lshl_add_u64 v[140:141], s[54:55], 0, v[130:131]
	s_add_i32 s37, s81, 0x2000
	v_lshl_add_u64 v[148:149], v[140:141], 0, s[18:19]
	s_mov_b32 m0, s81
	v_lshl_add_u64 v[212:213], s[54:55], 0, v[134:135]
	s_add_u32 s84, s54, 0x10100
	ds_read_b128 v[60:63], v147 offset:16384
	ds_read_b128 v[100:103], v147 offset:17408
	ds_read_b128 v[104:107], v147 offset:18432
	ds_read_b128 v[108:111], v147 offset:19456
	ds_read_b128 v[112:115], v147 offset:20480
	ds_read_b128 v[116:119], v147 offset:21504
	ds_read_b128 v[120:123], v147 offset:22528
	ds_read_b128 v[124:127], v147 offset:23552
	global_load_lds_dwordx4 v[148:149], off
	v_lshl_add_u64 v[148:149], v[212:213], 0, s[18:19]
	s_mov_b32 m0, s37
	s_addc_u32 s85, s55, 0
	s_add_i32 s79, s73, s62
	global_load_lds_dwordx4 v[148:149], off
	v_lshl_add_u64 v[148:149], s[84:85], 0, v[130:131]
	s_mov_b32 m0, s79
	s_add_i32 s80, s79, 0x2000
	global_load_lds_dwordx4 v[148:149], off
	v_lshl_add_u64 v[148:149], s[84:85], 0, v[134:135]
	s_mov_b32 m0, s80
	v_lshl_add_u64 v[214:215], s[52:53], 0, v[128:129]
	global_load_lds_dwordx4 v[148:149], off
	v_lshl_add_u64 v[148:149], v[214:215], 0, s[18:19]
	s_mov_b32 m0, s51
	v_lshl_add_u64 v[216:217], s[52:53], 0, v[132:133]
	global_load_lds_dwordx4 v[148:149], off
	v_lshl_add_u64 v[148:149], v[216:217], 0, s[18:19]
	s_mov_b32 m0, s63
	s_nop 0
	global_load_lds_dwordx4 v[148:149], off
	s_waitcnt vmcnt(8)
	s_waitcnt lgkmcnt(0)
	s_barrier
	s_setprio 1
	v_mfma_f32_16x16x32_bf16 v[148:151], v[0:3], v[60:63], 0
	v_mfma_f32_16x16x32_bf16 v[156:159], v[0:3], v[104:107], 0
	v_mfma_f32_16x16x32_bf16 v[164:167], v[0:3], v[112:115], 0
	v_mfma_f32_16x16x32_bf16 v[0:3], v[0:3], v[120:123], 0
	v_mfma_f32_16x16x32_bf16 v[148:151], v[4:7], v[100:103], v[148:151]
	v_mfma_f32_16x16x32_bf16 v[156:159], v[4:7], v[108:111], v[156:159]
	v_mfma_f32_16x16x32_bf16 v[164:167], v[4:7], v[116:119], v[164:167]
	v_mfma_f32_16x16x32_bf16 v[0:3], v[4:7], v[124:127], v[0:3]
	v_mfma_f32_16x16x32_bf16 v[4:7], v[8:11], v[120:123], 0
	v_mfma_f32_16x16x32_bf16 v[152:155], v[8:11], v[60:63], 0
	v_mfma_f32_16x16x32_bf16 v[160:163], v[8:11], v[104:107], 0
	v_mfma_f32_16x16x32_bf16 v[168:171], v[8:11], v[112:115], 0
	v_mfma_f32_16x16x32_bf16 v[4:7], v[12:15], v[124:127], v[4:7]
	v_mfma_f32_16x16x32_bf16 v[152:155], v[12:15], v[100:103], v[152:155]
	v_mfma_f32_16x16x32_bf16 v[160:163], v[12:15], v[108:111], v[160:163]
	v_mfma_f32_16x16x32_bf16 v[168:171], v[12:15], v[116:119], v[168:171]
	v_mfma_f32_16x16x32_bf16 v[8:11], v[16:19], v[60:63], 0
	v_mfma_f32_16x16x32_bf16 v[12:15], v[24:27], v[60:63], 0
	v_mfma_f32_16x16x32_bf16 v[8:11], v[20:23], v[100:103], v[8:11]
	v_mfma_f32_16x16x32_bf16 v[12:15], v[28:31], v[100:103], v[12:15]
	v_mfma_f32_16x16x32_bf16 v[60:63], v[16:19], v[104:107], 0
	v_mfma_f32_16x16x32_bf16 v[100:103], v[24:27], v[104:107], 0
	v_mfma_f32_16x16x32_bf16 v[104:107], v[16:19], v[112:115], 0
	v_mfma_f32_16x16x32_bf16 v[16:19], v[16:19], v[120:123], 0
	v_mfma_f32_16x16x32_bf16 v[60:63], v[20:23], v[108:111], v[60:63]
	v_mfma_f32_16x16x32_bf16 v[100:103], v[28:31], v[108:111], v[100:103]
	v_mfma_f32_16x16x32_bf16 v[104:107], v[20:23], v[116:119], v[104:107]
	v_mfma_f32_16x16x32_bf16 v[108:111], v[24:27], v[112:115], 0
	v_mfma_f32_16x16x32_bf16 v[16:19], v[20:23], v[124:127], v[16:19]
	v_mfma_f32_16x16x32_bf16 v[20:23], v[24:27], v[120:123], 0
	v_mfma_f32_16x16x32_bf16 v[108:111], v[28:31], v[116:119], v[108:111]
	v_mfma_f32_16x16x32_bf16 v[20:23], v[28:31], v[124:127], v[20:23]
	s_setprio 0
	s_barrier
	s_add_i32 s82, 0, 0x18000
	s_add_i32 s88, 0, 0x1c000
	v_add_u32_e32 v228, s82, v143
	v_add_u32_e32 v236, s88, v143
	ds_read_b128 v[24:27], v228
	ds_read_b128 v[28:31], v228 offset:1024
	ds_read_b128 v[112:115], v228 offset:2048
	ds_read_b128 v[116:119], v228 offset:3072
	ds_read_b128 v[120:123], v236
	ds_read_b128 v[124:127], v236 offset:1024
	ds_read_b128 v[172:175], v236 offset:2048
	ds_read_b128 v[176:179], v236 offset:3072
	s_add_u32 s84, s52, 0x10100
	s_addc_u32 s85, s53, 0
	s_mov_b32 m0, s64
	v_lshl_add_u64 v[218:219], s[84:85], 0, v[128:129]
	ds_read_b128 v[180:183], v147 offset:32768
	ds_read_b128 v[184:187], v147 offset:33792
	ds_read_b128 v[188:191], v147 offset:34816
	ds_read_b128 v[192:195], v147 offset:35840
	ds_read_b128 v[196:199], v147 offset:36864
	ds_read_b128 v[200:203], v147 offset:37888
	ds_read_b128 v[204:207], v147 offset:38912
	ds_read_b128 v[208:211], v147 offset:39936
	global_load_lds_dwordx4 v[218:219], off
	v_lshl_add_u64 v[218:219], s[84:85], 0, v[132:133]
	s_mov_b32 m0, s65
	s_nop 0
	global_load_lds_dwordx4 v[218:219], off
	s_waitcnt vmcnt(8)
	s_waitcnt lgkmcnt(0)
	s_barrier
	s_setprio 1
	v_mfma_f32_16x16x32_bf16 v[64:67], v[24:27], v[180:183], v[64:67]
	v_mfma_f32_16x16x32_bf16 v[68:71], v[112:115], v[180:183], v[68:71]
	v_mfma_f32_16x16x32_bf16 v[72:75], v[24:27], v[188:191], v[72:75]
	v_mfma_f32_16x16x32_bf16 v[76:79], v[112:115], v[188:191], v[76:79]
	v_mfma_f32_16x16x32_bf16 v[80:83], v[24:27], v[196:199], v[80:83]
	v_mfma_f32_16x16x32_bf16 v[84:87], v[112:115], v[196:199], v[84:87]
	v_mfma_f32_16x16x32_bf16 v[88:91], v[24:27], v[204:207], v[88:91]
	v_mfma_f32_16x16x32_bf16 v[92:95], v[112:115], v[204:207], v[92:95]
	v_mfma_f32_16x16x32_bf16 v[64:67], v[28:31], v[184:187], v[64:67]
	v_mfma_f32_16x16x32_bf16 v[68:71], v[116:119], v[184:187], v[68:71]
	v_mfma_f32_16x16x32_bf16 v[72:75], v[28:31], v[192:195], v[72:75]
	v_mfma_f32_16x16x32_bf16 v[76:79], v[116:119], v[192:195], v[76:79]
	v_mfma_f32_16x16x32_bf16 v[80:83], v[28:31], v[200:203], v[80:83]
	v_mfma_f32_16x16x32_bf16 v[84:87], v[116:119], v[200:203], v[84:87]
	v_mfma_f32_16x16x32_bf16 v[88:91], v[28:31], v[208:211], v[88:91]
	v_mfma_f32_16x16x32_bf16 v[92:95], v[116:119], v[208:211], v[92:95]
	v_mfma_f32_16x16x32_bf16 v[96:99], v[120:123], v[180:183], v[96:99]
	v_mfma_f32_16x16x32_bf16 v[32:35], v[172:175], v[180:183], v[32:35]
	v_mfma_f32_16x16x32_bf16 v[36:39], v[120:123], v[188:191], v[36:39]
	v_mfma_f32_16x16x32_bf16 v[40:43], v[172:175], v[188:191], v[40:43]
	v_mfma_f32_16x16x32_bf16 v[44:47], v[120:123], v[196:199], v[44:47]
	v_mfma_f32_16x16x32_bf16 v[48:51], v[172:175], v[196:199], v[48:51]
	v_mfma_f32_16x16x32_bf16 v[52:55], v[120:123], v[204:207], v[52:55]
	v_mfma_f32_16x16x32_bf16 v[56:59], v[172:175], v[204:207], v[56:59]
	v_mfma_f32_16x16x32_bf16 v[96:99], v[124:127], v[184:187], v[96:99]
	v_mfma_f32_16x16x32_bf16 v[32:35], v[176:179], v[184:187], v[32:35]
	v_mfma_f32_16x16x32_bf16 v[36:39], v[124:127], v[192:195], v[36:39]
	v_mfma_f32_16x16x32_bf16 v[40:43], v[176:179], v[192:195], v[40:43]
	v_mfma_f32_16x16x32_bf16 v[44:47], v[124:127], v[200:203], v[44:47]
	v_mfma_f32_16x16x32_bf16 v[48:51], v[176:179], v[200:203], v[48:51]
	v_mfma_f32_16x16x32_bf16 v[52:55], v[124:127], v[208:211], v[52:55]
	v_mfma_f32_16x16x32_bf16 v[56:59], v[176:179], v[208:211], v[56:59]
	s_setprio 0
	s_barrier
	s_add_i32 s84, s82, s62
	s_add_i32 s82, s84, 0x2000
	v_lshl_add_u64 v[140:141], v[140:141], 0, s[20:21]
	s_mov_b32 m0, s84
	s_add_u32 s86, s54, 0x10180
	ds_read_b128 v[180:183], v147 offset:49152
	ds_read_b128 v[184:187], v147 offset:50176
	ds_read_b128 v[188:191], v147 offset:51200
	ds_read_b128 v[192:195], v147 offset:52224
	ds_read_b128 v[196:199], v147 offset:53248
	ds_read_b128 v[200:203], v147 offset:54272
	ds_read_b128 v[204:207], v147 offset:55296
	ds_read_b128 v[208:211], v147 offset:56320
	global_load_lds_dwordx4 v[140:141], off
	v_lshl_add_u64 v[140:141], v[212:213], 0, s[20:21]
	s_mov_b32 m0, s82
	s_addc_u32 s87, s55, 0
	s_add_i32 s54, s88, s62
	global_load_lds_dwordx4 v[140:141], off
	v_lshl_add_u64 v[140:141], s[86:87], 0, v[130:131]
	s_mov_b32 m0, s54
	s_add_i32 s55, s54, 0x2000
	global_load_lds_dwordx4 v[140:141], off
	v_lshl_add_u64 v[140:141], s[86:87], 0, v[134:135]
	s_mov_b32 m0, s55
	s_nop 0
	global_load_lds_dwordx4 v[140:141], off
	v_lshl_add_u64 v[140:141], v[214:215], 0, s[20:21]
	s_mov_b32 m0, s66
	s_nop 0
	global_load_lds_dwordx4 v[140:141], off
	v_lshl_add_u64 v[140:141], v[216:217], 0, s[20:21]
	s_mov_b32 m0, s67
	s_nop 0
	global_load_lds_dwordx4 v[140:141], off
	s_waitcnt vmcnt(8)
	s_waitcnt lgkmcnt(0)
	s_barrier
	s_setprio 1
	v_mfma_f32_16x16x32_bf16 v[0:3], v[24:27], v[204:207], v[0:3]
	v_mfma_f32_16x16x32_bf16 v[4:7], v[112:115], v[204:207], v[4:7]
	v_mfma_f32_16x16x32_bf16 v[148:151], v[24:27], v[180:183], v[148:151]
	v_mfma_f32_16x16x32_bf16 v[152:155], v[112:115], v[180:183], v[152:155]
	v_mfma_f32_16x16x32_bf16 v[156:159], v[24:27], v[188:191], v[156:159]
	v_mfma_f32_16x16x32_bf16 v[160:163], v[112:115], v[188:191], v[160:163]
	v_mfma_f32_16x16x32_bf16 v[164:167], v[24:27], v[196:199], v[164:167]
	v_mfma_f32_16x16x32_bf16 v[168:171], v[112:115], v[196:199], v[168:171]
	v_mfma_f32_16x16x32_bf16 v[0:3], v[28:31], v[208:211], v[0:3]
	v_mfma_f32_16x16x32_bf16 v[4:7], v[116:119], v[208:211], v[4:7]
	v_mfma_f32_16x16x32_bf16 v[148:151], v[28:31], v[184:187], v[148:151]
	v_mfma_f32_16x16x32_bf16 v[152:155], v[116:119], v[184:187], v[152:155]
	v_mfma_f32_16x16x32_bf16 v[156:159], v[28:31], v[192:195], v[156:159]
	v_mfma_f32_16x16x32_bf16 v[160:163], v[116:119], v[192:195], v[160:163]
	v_mfma_f32_16x16x32_bf16 v[164:167], v[28:31], v[200:203], v[164:167]
	v_mfma_f32_16x16x32_bf16 v[168:171], v[116:119], v[200:203], v[168:171]
	v_mfma_f32_16x16x32_bf16 v[8:11], v[120:123], v[180:183], v[8:11]
	v_mfma_f32_16x16x32_bf16 v[12:15], v[172:175], v[180:183], v[12:15]
	v_mfma_f32_16x16x32_bf16 v[24:27], v[120:123], v[188:191], v[60:63]
	v_mfma_f32_16x16x32_bf16 v[28:31], v[172:175], v[188:191], v[100:103]
	v_mfma_f32_16x16x32_bf16 v[60:63], v[120:123], v[196:199], v[104:107]
	v_mfma_f32_16x16x32_bf16 v[100:103], v[172:175], v[196:199], v[108:111]
	v_mfma_f32_16x16x32_bf16 v[16:19], v[120:123], v[204:207], v[16:19]
	v_mfma_f32_16x16x32_bf16 v[20:23], v[172:175], v[204:207], v[20:23]
	v_mfma_f32_16x16x32_bf16 v[8:11], v[124:127], v[184:187], v[8:11]
	v_mfma_f32_16x16x32_bf16 v[12:15], v[176:179], v[184:187], v[12:15]
	v_mfma_f32_16x16x32_bf16 v[24:27], v[124:127], v[192:195], v[24:27]
	v_mfma_f32_16x16x32_bf16 v[28:31], v[176:179], v[192:195], v[28:31]
	v_mfma_f32_16x16x32_bf16 v[60:63], v[124:127], v[200:203], v[60:63]
	v_mfma_f32_16x16x32_bf16 v[100:103], v[176:179], v[200:203], v[100:103]
	v_mfma_f32_16x16x32_bf16 v[16:19], v[124:127], v[208:211], v[16:19]
	v_mfma_f32_16x16x32_bf16 v[20:23], v[176:179], v[208:211], v[20:23]
	s_setprio 0
	s_barrier
	ds_read_b128 v[104:107], v145
	ds_read_b128 v[108:111], v145 offset:1024
	ds_read_b128 v[112:115], v145 offset:2048
	ds_read_b128 v[116:119], v145 offset:3072
	ds_read_b128 v[120:123], v146
	ds_read_b128 v[124:127], v146 offset:1024
	ds_read_b128 v[172:175], v146 offset:2048
	ds_read_b128 v[176:179], v146 offset:3072
	s_add_u32 s52, s52, 0x10180
	s_addc_u32 s53, s53, 0
	s_mov_b32 m0, s83
	v_lshl_add_u64 v[140:141], s[52:53], 0, v[128:129]
	ds_read_b128 v[180:183], v147
	ds_read_b128 v[184:187], v147 offset:1024
	ds_read_b128 v[188:191], v147 offset:2048
	ds_read_b128 v[192:195], v147 offset:3072
	ds_read_b128 v[196:199], v147 offset:4096
	ds_read_b128 v[200:203], v147 offset:5120
	ds_read_b128 v[204:207], v147 offset:6144
	ds_read_b128 v[208:211], v147 offset:7168
	global_load_lds_dwordx4 v[140:141], off
	v_lshl_add_u64 v[140:141], s[52:53], 0, v[132:133]
	s_mov_b32 m0, s35
	s_nop 0
	global_load_lds_dwordx4 v[140:141], off
	s_waitcnt vmcnt(8)
	s_waitcnt lgkmcnt(0)
	s_barrier
	s_setprio 1
	v_mfma_f32_16x16x32_bf16 v[88:91], v[104:107], v[204:207], v[88:91]
	v_mfma_f32_16x16x32_bf16 v[64:67], v[104:107], v[180:183], v[64:67]
	v_mfma_f32_16x16x32_bf16 v[68:71], v[112:115], v[180:183], v[68:71]
	v_mfma_f32_16x16x32_bf16 v[72:75], v[104:107], v[188:191], v[72:75]
	v_mfma_f32_16x16x32_bf16 v[76:79], v[112:115], v[188:191], v[76:79]
	v_mfma_f32_16x16x32_bf16 v[80:83], v[104:107], v[196:199], v[80:83]
	v_mfma_f32_16x16x32_bf16 v[84:87], v[112:115], v[196:199], v[84:87]
	v_mfma_f32_16x16x32_bf16 v[212:215], v[108:111], v[208:211], v[88:91]
	v_mfma_f32_16x16x32_bf16 v[88:91], v[112:115], v[204:207], v[92:95]
	v_mfma_f32_16x16x32_bf16 v[64:67], v[108:111], v[184:187], v[64:67]
	v_mfma_f32_16x16x32_bf16 v[68:71], v[116:119], v[184:187], v[68:71]
	v_mfma_f32_16x16x32_bf16 v[72:75], v[108:111], v[192:195], v[72:75]
	v_mfma_f32_16x16x32_bf16 v[76:79], v[116:119], v[192:195], v[76:79]
	v_mfma_f32_16x16x32_bf16 v[80:83], v[108:111], v[200:203], v[80:83]
	v_mfma_f32_16x16x32_bf16 v[84:87], v[116:119], v[200:203], v[84:87]
	v_mfma_f32_16x16x32_bf16 v[92:95], v[116:119], v[208:211], v[88:91]
	v_mfma_f32_16x16x32_bf16 v[48:51], v[172:175], v[196:199], v[48:51]
	v_mfma_f32_16x16x32_bf16 v[88:91], v[120:123], v[180:183], v[96:99]
	v_mfma_f32_16x16x32_bf16 v[32:35], v[172:175], v[180:183], v[32:35]
	v_mfma_f32_16x16x32_bf16 v[36:39], v[120:123], v[188:191], v[36:39]
	v_mfma_f32_16x16x32_bf16 v[40:43], v[172:175], v[188:191], v[40:43]
	v_mfma_f32_16x16x32_bf16 v[44:47], v[120:123], v[196:199], v[44:47]
	v_mfma_f32_16x16x32_bf16 v[180:183], v[176:179], v[200:203], v[48:51]
	v_mfma_f32_16x16x32_bf16 v[48:51], v[120:123], v[204:207], v[52:55]
	v_mfma_f32_16x16x32_bf16 v[32:35], v[176:179], v[184:187], v[32:35]
	v_mfma_f32_16x16x32_bf16 v[36:39], v[124:127], v[192:195], v[36:39]
	v_mfma_f32_16x16x32_bf16 v[40:43], v[176:179], v[192:195], v[40:43]
	v_mfma_f32_16x16x32_bf16 v[44:47], v[124:127], v[200:203], v[44:47]
	v_mfma_f32_16x16x32_bf16 v[52:55], v[124:127], v[208:211], v[48:51]
	v_mfma_f32_16x16x32_bf16 v[48:51], v[172:175], v[204:207], v[56:59]
	v_mfma_f32_16x16x32_bf16 v[220:223], v[124:127], v[184:187], v[88:91]
	v_mfma_f32_16x16x32_bf16 v[184:187], v[176:179], v[208:211], v[48:51]
	s_setprio 0
	s_barrier
	s_mov_b32 m0, s81
	v_lshl_add_u64 v[140:141], s[56:57], 0, v[130:131]
	s_add_u32 s52, s56, 0x10000
	s_nop 0
	ds_read_b128 v[48:51], v147 offset:16384
	ds_read_b128 v[56:59], v147 offset:17408
	ds_read_b128 v[88:91], v147 offset:18432
	ds_read_b128 v[96:99], v147 offset:19456
	ds_read_b128 v[188:191], v147 offset:20480
	ds_read_b128 v[192:195], v147 offset:21504
	ds_read_b128 v[196:199], v147 offset:22528
	ds_read_b128 v[200:203], v147 offset:23552
	global_load_lds_dwordx4 v[140:141], off
	v_lshl_add_u64 v[252:253], s[56:57], 0, v[134:135]
	s_mov_b32 m0, s37
	s_addc_u32 s53, s57, 0
	global_load_lds_dwordx4 v[252:253], off
	v_lshl_add_u64 v[204:205], s[52:53], 0, v[130:131]
	s_mov_b32 m0, s79
	v_lshl_add_u64 v[136:137], s[58:59], 0, v[128:129]
	global_load_lds_dwordx4 v[204:205], off
	v_lshl_add_u64 v[204:205], s[52:53], 0, v[134:135]
	s_mov_b32 m0, s80
	v_lshl_add_u64 v[138:139], s[58:59], 0, v[132:133]
	global_load_lds_dwordx4 v[204:205], off
	s_mov_b32 m0, s51
	s_nop 0
	global_load_lds_dwordx4 v[136:137], off
	s_mov_b32 m0, s63
	s_nop 0
	global_load_lds_dwordx4 v[138:139], off
	s_waitcnt vmcnt(8)
	s_waitcnt lgkmcnt(0)
	s_barrier
	s_setprio 1
	v_mfma_f32_16x16x32_bf16 v[0:3], v[104:107], v[196:199], v[0:3]
	v_mfma_f32_16x16x32_bf16 v[4:7], v[112:115], v[196:199], v[4:7]
	v_mfma_f32_16x16x32_bf16 v[148:151], v[104:107], v[48:51], v[148:151]
	v_mfma_f32_16x16x32_bf16 v[152:155], v[112:115], v[48:51], v[152:155]
	v_mfma_f32_16x16x32_bf16 v[156:159], v[104:107], v[88:91], v[156:159]
	v_mfma_f32_16x16x32_bf16 v[160:163], v[112:115], v[88:91], v[160:163]
	v_mfma_f32_16x16x32_bf16 v[164:167], v[104:107], v[188:191], v[164:167]
	v_mfma_f32_16x16x32_bf16 v[168:171], v[112:115], v[188:191], v[168:171]
	v_mfma_f32_16x16x32_bf16 v[0:3], v[108:111], v[200:203], v[0:3]
	v_mfma_f32_16x16x32_bf16 v[4:7], v[116:119], v[200:203], v[4:7]
	v_mfma_f32_16x16x32_bf16 v[148:151], v[108:111], v[56:59], v[148:151]
	v_mfma_f32_16x16x32_bf16 v[152:155], v[116:119], v[56:59], v[152:155]
	v_mfma_f32_16x16x32_bf16 v[156:159], v[108:111], v[96:99], v[156:159]
	v_mfma_f32_16x16x32_bf16 v[160:163], v[116:119], v[96:99], v[160:163]
	v_mfma_f32_16x16x32_bf16 v[164:167], v[108:111], v[192:195], v[164:167]
	v_mfma_f32_16x16x32_bf16 v[168:171], v[116:119], v[192:195], v[168:171]
	v_mfma_f32_16x16x32_bf16 v[12:15], v[172:175], v[48:51], v[12:15]
	v_mfma_f32_16x16x32_bf16 v[204:207], v[176:179], v[56:59], v[12:15]
	v_mfma_f32_16x16x32_bf16 v[12:15], v[120:123], v[88:91], v[24:27]
	v_mfma_f32_16x16x32_bf16 v[24:27], v[124:127], v[96:99], v[12:15]
	v_mfma_f32_16x16x32_bf16 v[12:15], v[172:175], v[88:91], v[28:31]
	v_mfma_f32_16x16x32_bf16 v[208:211], v[176:179], v[96:99], v[12:15]
	v_mfma_f32_16x16x32_bf16 v[12:15], v[120:123], v[188:191], v[60:63]
	v_mfma_f32_16x16x32_bf16 v[224:227], v[124:127], v[192:195], v[12:15]
	v_mfma_f32_16x16x32_bf16 v[12:15], v[172:175], v[188:191], v[100:103]
	v_mfma_f32_16x16x32_bf16 v[8:11], v[120:123], v[48:51], v[8:11]
	v_mfma_f32_16x16x32_bf16 v[188:191], v[176:179], v[192:195], v[12:15]
	v_mfma_f32_16x16x32_bf16 v[12:15], v[120:123], v[196:199], v[16:19]
	v_mfma_f32_16x16x32_bf16 v[8:11], v[124:127], v[56:59], v[8:11]
	v_mfma_f32_16x16x32_bf16 v[192:195], v[124:127], v[200:203], v[12:15]
	v_mfma_f32_16x16x32_bf16 v[12:15], v[172:175], v[196:199], v[20:23]
	v_mfma_f32_16x16x32_bf16 v[172:175], v[176:179], v[200:203], v[12:15]
	s_setprio 0
	s_barrier
	s_nop 4
	ds_read_b128 v[12:15], v228
	ds_read_b128 v[16:19], v228 offset:1024
	ds_read_b128 v[176:179], v228 offset:2048
	ds_read_b128 v[196:199], v228 offset:3072
	ds_read_b128 v[200:203], v236
	ds_read_b128 v[228:231], v236 offset:1024
	ds_read_b128 v[232:235], v236 offset:2048
	ds_read_b128 v[236:239], v236 offset:3072
	s_add_u32 s52, s58, 0x10000
	s_addc_u32 s53, s59, 0
	s_mov_b32 m0, s64
	v_lshl_add_u64 v[48:49], s[52:53], 0, v[128:129]
	ds_read_b128 v[20:23], v147 offset:32768
	ds_read_b128 v[28:31], v147 offset:33792
	ds_read_b128 v[60:63], v147 offset:34816
	ds_read_b128 v[100:103], v147 offset:35840
	ds_read_b128 v[240:243], v147 offset:36864
	ds_read_b128 v[244:247], v147 offset:37888
	ds_read_b128 v[248:251], v147 offset:38912
	ds_read_b128 v[216:219], v147 offset:39936
	global_load_lds_dwordx4 v[48:49], off
	v_lshl_add_u64 v[48:49], s[52:53], 0, v[132:133]
	s_mov_b32 m0, s65
	s_nop 0
	global_load_lds_dwordx4 v[48:49], off
	s_waitcnt vmcnt(8)
	s_waitcnt lgkmcnt(0)
	s_barrier
	s_setprio 1
	v_mfma_f32_16x16x32_bf16 v[48:51], v[12:15], v[20:23], v[64:67]
	v_mfma_f32_16x16x32_bf16 v[120:123], v[16:19], v[28:31], v[48:51]
	v_mfma_f32_16x16x32_bf16 v[48:51], v[176:179], v[20:23], v[68:71]
	v_mfma_f32_16x16x32_bf16 v[112:115], v[196:199], v[28:31], v[48:51]
	v_mfma_f32_16x16x32_bf16 v[48:51], v[12:15], v[60:63], v[72:75]
	v_mfma_f32_16x16x32_bf16 v[104:107], v[16:19], v[100:103], v[48:51]
	v_mfma_f32_16x16x32_bf16 v[48:51], v[176:179], v[60:63], v[76:79]
	v_mfma_f32_16x16x32_bf16 v[96:99], v[196:199], v[100:103], v[48:51]
	v_mfma_f32_16x16x32_bf16 v[48:51], v[12:15], v[240:243], v[80:83]
	v_mfma_f32_16x16x32_bf16 v[88:91], v[16:19], v[244:247], v[48:51]
	v_mfma_f32_16x16x32_bf16 v[48:51], v[176:179], v[240:243], v[84:87]
	v_mfma_f32_16x16x32_bf16 v[80:83], v[196:199], v[244:247], v[48:51]
	v_mfma_f32_16x16x32_bf16 v[48:51], v[12:15], v[248:251], v[212:215]
	v_mfma_f32_16x16x32_bf16 v[56:59], v[16:19], v[216:219], v[48:51]
	v_mfma_f32_16x16x32_bf16 v[48:51], v[176:179], v[248:251], v[92:95]
	v_mfma_f32_16x16x32_bf16 v[48:51], v[196:199], v[216:219], v[48:51]
	v_mfma_f32_16x16x32_bf16 v[64:67], v[200:203], v[20:23], v[220:223]
	v_mfma_f32_16x16x32_bf16 v[20:23], v[232:235], v[20:23], v[32:35]
	v_mfma_f32_16x16x32_bf16 v[116:119], v[236:239], v[28:31], v[20:23]
	v_mfma_f32_16x16x32_bf16 v[20:23], v[200:203], v[60:63], v[36:39]
	v_mfma_f32_16x16x32_bf16 v[108:111], v[228:231], v[100:103], v[20:23]
	v_mfma_f32_16x16x32_bf16 v[20:23], v[232:235], v[60:63], v[40:43]
	v_mfma_f32_16x16x32_bf16 v[100:103], v[236:239], v[100:103], v[20:23]
	v_mfma_f32_16x16x32_bf16 v[20:23], v[200:203], v[240:243], v[44:47]
	v_mfma_f32_16x16x32_bf16 v[92:95], v[228:231], v[244:247], v[20:23]
	v_mfma_f32_16x16x32_bf16 v[20:23], v[232:235], v[240:243], v[180:183]
	v_mfma_f32_16x16x32_bf16 v[84:87], v[236:239], v[244:247], v[20:23]
	v_mfma_f32_16x16x32_bf16 v[20:23], v[200:203], v[248:251], v[52:55]
	v_mfma_f32_16x16x32_bf16 v[60:63], v[228:231], v[216:219], v[20:23]
	v_mfma_f32_16x16x32_bf16 v[20:23], v[232:235], v[248:251], v[184:187]
	v_mfma_f32_16x16x32_bf16 v[124:127], v[228:231], v[28:31], v[64:67]
	v_mfma_f32_16x16x32_bf16 v[52:55], v[236:239], v[216:219], v[20:23]
	s_setprio 0
	s_barrier
	s_mov_b32 m0, s84
	s_nop 2
	v_lshl_add_u64 v[20:21], v[140:141], 0, s[12:13]
	s_add_u32 s52, s56, 0x10080
	ds_read_b128 v[32:35], v147 offset:49152
	ds_read_b128 v[40:43], v147 offset:50176
	ds_read_b128 v[180:183], v147 offset:51200
	ds_read_b128 v[184:187], v147 offset:52224
	ds_read_b128 v[212:215], v147 offset:53248
	ds_read_b128 v[216:219], v147 offset:54272
	ds_read_b128 v[220:223], v147 offset:55296
	ds_read_b128 v[240:243], v147 offset:56320
	global_load_lds_dwordx4 v[20:21], off
	v_lshl_add_u64 v[20:21], v[252:253], 0, s[12:13]
	s_mov_b32 m0, s82
	s_addc_u32 s53, s57, 0
	global_load_lds_dwordx4 v[20:21], off
	v_lshl_add_u64 v[20:21], s[52:53], 0, v[130:131]
	s_mov_b32 m0, s54
	s_nop 0
	global_load_lds_dwordx4 v[20:21], off
	v_lshl_add_u64 v[20:21], s[52:53], 0, v[134:135]
	s_mov_b32 m0, s55
	s_nop 0
	global_load_lds_dwordx4 v[20:21], off
	v_lshl_add_u64 v[20:21], v[136:137], 0, s[12:13]
	s_mov_b32 m0, s66
	s_nop 0
	global_load_lds_dwordx4 v[20:21], off
	v_lshl_add_u64 v[20:21], v[138:139], 0, s[12:13]
	s_mov_b32 m0, s67
	s_nop 0
	global_load_lds_dwordx4 v[20:21], off
	s_waitcnt vmcnt(8)
	s_waitcnt lgkmcnt(0)
	s_barrier
	s_setprio 1
	v_mfma_f32_16x16x32_bf16 v[20:23], v[12:15], v[32:35], v[148:151]
	v_mfma_f32_16x16x32_bf16 v[76:79], v[16:19], v[40:43], v[20:23]
	v_mfma_f32_16x16x32_bf16 v[20:23], v[176:179], v[32:35], v[152:155]
	v_mfma_f32_16x16x32_bf16 v[68:71], v[196:199], v[40:43], v[20:23]
	v_mfma_f32_16x16x32_bf16 v[20:23], v[12:15], v[180:183], v[156:159]
	v_mfma_f32_16x16x32_bf16 v[44:47], v[16:19], v[184:187], v[20:23]
	v_mfma_f32_16x16x32_bf16 v[20:23], v[176:179], v[180:183], v[160:163]
	v_mfma_f32_16x16x32_bf16 v[36:39], v[196:199], v[184:187], v[20:23]
	v_mfma_f32_16x16x32_bf16 v[20:23], v[12:15], v[212:215], v[164:167]
	v_mfma_f32_16x16x32_bf16 v[0:3], v[12:15], v[220:223], v[0:3]
	v_mfma_f32_16x16x32_bf16 v[28:31], v[16:19], v[216:219], v[20:23]
	v_mfma_f32_16x16x32_bf16 v[20:23], v[176:179], v[212:215], v[168:171]
	v_mfma_f32_16x16x32_bf16 v[12:15], v[16:19], v[240:243], v[0:3]
	v_mfma_f32_16x16x32_bf16 v[0:3], v[176:179], v[220:223], v[4:7]
	v_mfma_f32_16x16x32_bf16 v[20:23], v[196:199], v[216:219], v[20:23]
	v_mfma_f32_16x16x32_bf16 v[4:7], v[196:199], v[240:243], v[0:3]
	v_mfma_f32_16x16x32_bf16 v[0:3], v[200:203], v[32:35], v[8:11]
	v_mfma_f32_16x16x32_bf16 v[72:75], v[228:231], v[40:43], v[0:3]
	v_mfma_f32_16x16x32_bf16 v[0:3], v[232:235], v[32:35], v[204:207]
	v_mfma_f32_16x16x32_bf16 v[64:67], v[236:239], v[40:43], v[0:3]
	v_mfma_f32_16x16x32_bf16 v[0:3], v[200:203], v[180:183], v[24:27]
	v_mfma_f32_16x16x32_bf16 v[40:43], v[228:231], v[184:187], v[0:3]
	v_mfma_f32_16x16x32_bf16 v[0:3], v[232:235], v[180:183], v[208:211]
	v_mfma_f32_16x16x32_bf16 v[32:35], v[236:239], v[184:187], v[0:3]
	v_mfma_f32_16x16x32_bf16 v[0:3], v[200:203], v[212:215], v[224:227]
	v_mfma_f32_16x16x32_bf16 v[24:27], v[228:231], v[216:219], v[0:3]
	v_mfma_f32_16x16x32_bf16 v[0:3], v[232:235], v[212:215], v[188:191]
	v_mfma_f32_16x16x32_bf16 v[16:19], v[236:239], v[216:219], v[0:3]
	v_mfma_f32_16x16x32_bf16 v[0:3], v[200:203], v[220:223], v[192:195]
	v_mfma_f32_16x16x32_bf16 v[8:11], v[228:231], v[240:243], v[0:3]
	v_mfma_f32_16x16x32_bf16 v[0:3], v[232:235], v[220:223], v[172:175]
	v_mfma_f32_16x16x32_bf16 v[0:3], v[236:239], v[240:243], v[0:3]
	s_setprio 0
	s_barrier
	s_andn2_b64 vcc, exec, s[14:15]
	s_cbranch_vccnz .LBB0_155
	s_barrier

.LBB0_178:
	ds_read_b128 v[148:151], v157
	ds_read_b128 v[162:165], v157 offset:1024
	ds_read_b128 v[166:169], v157 offset:2048
	ds_read_b128 v[170:173], v157 offset:3072
	ds_read_b128 v[174:177], v158
	ds_read_b128 v[178:181], v158 offset:1024
	ds_read_b128 v[182:185], v158 offset:2048
	ds_read_b128 v[186:189], v158 offset:3072
	s_add_u32 s48, s46, 0xfff80080
	s_addc_u32 s49, s47, -1
	s_cmp_eq_u32 s72, 28
	s_cselect_b32 s51, s31, s49
	s_cselect_b32 s50, s66, s48
	s_cselect_b32 s49, s27, s71
	s_cselect_b32 s48, s67, s70
	v_lshl_add_u64 v[152:153], s[46:47], 0, v[142:143]
	s_add_i32 m0, s13, 0xc000
	ds_read_b128 v[190:193], v159
	ds_read_b128 v[194:197], v159 offset:1024
	ds_read_b128 v[198:201], v159 offset:2048
	ds_read_b128 v[202:205], v159 offset:3072
	ds_read_b128 v[206:209], v159 offset:4096
	ds_read_b128 v[210:213], v159 offset:5120
	ds_read_b128 v[214:217], v159 offset:6144
	ds_read_b128 v[218:221], v159 offset:7168
	global_load_lds_dwordx4 v[152:153], off
	v_lshl_add_u64 v[152:153], s[46:47], 0, v[140:141]
	s_add_i32 m0, s13, 0xe000
	s_nop 0
	global_load_lds_dwordx4 v[152:153], off
	s_waitcnt vmcnt(8)
	s_waitcnt lgkmcnt(0)
	s_barrier
	s_setprio 1
	v_mfma_f32_16x16x32_bf16 v[124:127], v[148:151], v[190:193], v[124:127]
	v_mfma_f32_16x16x32_bf16 v[120:123], v[166:169], v[190:193], v[120:123]
	v_mfma_f32_16x16x32_bf16 v[108:111], v[148:151], v[198:201], v[108:111]
	v_mfma_f32_16x16x32_bf16 v[104:107], v[166:169], v[198:201], v[104:107]
	v_mfma_f32_16x16x32_bf16 v[92:95], v[148:151], v[206:209], v[92:95]
	v_mfma_f32_16x16x32_bf16 v[88:91], v[166:169], v[206:209], v[88:91]
	v_mfma_f32_16x16x32_bf16 v[76:79], v[148:151], v[214:217], v[76:79]
	v_mfma_f32_16x16x32_bf16 v[72:75], v[166:169], v[214:217], v[72:75]
	v_mfma_f32_16x16x32_bf16 v[124:127], v[162:165], v[194:197], v[124:127]
	v_mfma_f32_16x16x32_bf16 v[120:123], v[170:173], v[194:197], v[120:123]
	v_mfma_f32_16x16x32_bf16 v[108:111], v[162:165], v[202:205], v[108:111]
	v_mfma_f32_16x16x32_bf16 v[104:107], v[170:173], v[202:205], v[104:107]
	v_mfma_f32_16x16x32_bf16 v[92:95], v[162:165], v[210:213], v[92:95]
	v_mfma_f32_16x16x32_bf16 v[88:91], v[170:173], v[210:213], v[88:91]
	v_mfma_f32_16x16x32_bf16 v[76:79], v[162:165], v[218:221], v[76:79]
	v_mfma_f32_16x16x32_bf16 v[72:75], v[170:173], v[218:221], v[72:75]
	v_mfma_f32_16x16x32_bf16 v[116:119], v[174:177], v[190:193], v[116:119]
	v_mfma_f32_16x16x32_bf16 v[112:115], v[182:185], v[190:193], v[112:115]
	v_mfma_f32_16x16x32_bf16 v[100:103], v[174:177], v[198:201], v[100:103]
	v_mfma_f32_16x16x32_bf16 v[96:99], v[182:185], v[198:201], v[96:99]
	v_mfma_f32_16x16x32_bf16 v[84:87], v[174:177], v[206:209], v[84:87]
	v_mfma_f32_16x16x32_bf16 v[80:83], v[182:185], v[206:209], v[80:83]
	v_mfma_f32_16x16x32_bf16 v[68:71], v[174:177], v[214:217], v[68:71]
	v_mfma_f32_16x16x32_bf16 v[64:67], v[182:185], v[214:217], v[64:67]
	v_mfma_f32_16x16x32_bf16 v[116:119], v[178:181], v[194:197], v[116:119]
	v_mfma_f32_16x16x32_bf16 v[112:115], v[186:189], v[194:197], v[112:115]
	v_mfma_f32_16x16x32_bf16 v[100:103], v[178:181], v[202:205], v[100:103]
	v_mfma_f32_16x16x32_bf16 v[96:99], v[186:189], v[202:205], v[96:99]
	v_mfma_f32_16x16x32_bf16 v[84:87], v[178:181], v[210:213], v[84:87]
	v_mfma_f32_16x16x32_bf16 v[80:83], v[186:189], v[210:213], v[80:83]
	v_mfma_f32_16x16x32_bf16 v[68:71], v[178:181], v[218:221], v[68:71]
	v_mfma_f32_16x16x32_bf16 v[64:67], v[186:189], v[218:221], v[64:67]
	s_setprio 0
	s_barrier
	s_add_i32 s73, s62, s52
	v_lshl_add_u64 v[152:153], s[48:49], 0, v[130:131]
	s_mov_b32 m0, s73
	ds_read_b128 v[190:193], v159 offset:16384
	ds_read_b128 v[194:197], v159 offset:17408
	ds_read_b128 v[198:201], v159 offset:18432
	ds_read_b128 v[202:205], v159 offset:19456
	ds_read_b128 v[206:209], v159 offset:20480
	ds_read_b128 v[210:213], v159 offset:21504
	ds_read_b128 v[214:217], v159 offset:22528
	ds_read_b128 v[218:221], v159 offset:23552
	global_load_lds_dwordx4 v[152:153], off
	s_add_i32 m0, s73, 0x2000
	s_add_u32 s74, s48, 0x80000
	v_lshl_add_u64 v[222:223], s[48:49], 0, v[134:135]
	s_addc_u32 s75, s49, 0
	s_add_i32 s73, s63, s52
	global_load_lds_dwordx4 v[222:223], off
	v_lshl_add_u64 v[224:225], s[74:75], 0, v[130:131]
	s_mov_b32 m0, s73
	v_lshl_add_u64 v[226:227], s[50:51], 0, v[132:133]
	global_load_lds_dwordx4 v[224:225], off
	v_lshl_add_u64 v[224:225], s[74:75], 0, v[134:135]
	s_add_i32 m0, s73, 0x2000
	s_nop 0
	global_load_lds_dwordx4 v[224:225], off
	v_lshl_add_u64 v[224:225], s[50:51], 0, v[128:129]
	s_mov_b32 m0, s13
	s_nop 0
	global_load_lds_dwordx4 v[224:225], off
	s_mov_b32 m0, s53
	s_nop 0
	global_load_lds_dwordx4 v[226:227], off
	s_waitcnt vmcnt(8)
	s_waitcnt lgkmcnt(0)
	s_barrier
	s_setprio 1
	v_mfma_f32_16x16x32_bf16 v[60:63], v[148:151], v[190:193], v[60:63]
	v_mfma_f32_16x16x32_bf16 v[56:59], v[166:169], v[190:193], v[56:59]
	v_mfma_f32_16x16x32_bf16 v[44:47], v[148:151], v[198:201], v[44:47]
	v_mfma_f32_16x16x32_bf16 v[40:43], v[166:169], v[198:201], v[40:43]
	v_mfma_f32_16x16x32_bf16 v[28:31], v[148:151], v[206:209], v[28:31]
	v_mfma_f32_16x16x32_bf16 v[24:27], v[166:169], v[206:209], v[24:27]
	v_mfma_f32_16x16x32_bf16 v[12:15], v[148:151], v[214:217], v[12:15]
	v_mfma_f32_16x16x32_bf16 v[8:11], v[166:169], v[214:217], v[8:11]
	v_mfma_f32_16x16x32_bf16 v[60:63], v[162:165], v[194:197], v[60:63]
	v_mfma_f32_16x16x32_bf16 v[56:59], v[170:173], v[194:197], v[56:59]
	v_mfma_f32_16x16x32_bf16 v[44:47], v[162:165], v[202:205], v[44:47]
	v_mfma_f32_16x16x32_bf16 v[40:43], v[170:173], v[202:205], v[40:43]
	v_mfma_f32_16x16x32_bf16 v[28:31], v[162:165], v[210:213], v[28:31]
	v_mfma_f32_16x16x32_bf16 v[24:27], v[170:173], v[210:213], v[24:27]
	v_mfma_f32_16x16x32_bf16 v[12:15], v[162:165], v[218:221], v[12:15]
	v_mfma_f32_16x16x32_bf16 v[8:11], v[170:173], v[218:221], v[8:11]
	v_mfma_f32_16x16x32_bf16 v[52:55], v[174:177], v[190:193], v[52:55]
	v_mfma_f32_16x16x32_bf16 v[48:51], v[182:185], v[190:193], v[48:51]
	v_mfma_f32_16x16x32_bf16 v[36:39], v[174:177], v[198:201], v[36:39]
	v_mfma_f32_16x16x32_bf16 v[32:35], v[182:185], v[198:201], v[32:35]
	v_mfma_f32_16x16x32_bf16 v[20:23], v[174:177], v[206:209], v[20:23]
	v_mfma_f32_16x16x32_bf16 v[16:19], v[182:185], v[206:209], v[16:19]
	v_mfma_f32_16x16x32_bf16 v[4:7], v[174:177], v[214:217], v[4:7]
	v_mfma_f32_16x16x32_bf16 v[0:3], v[182:185], v[214:217], v[0:3]
	v_mfma_f32_16x16x32_bf16 v[52:55], v[178:181], v[194:197], v[52:55]
	v_mfma_f32_16x16x32_bf16 v[48:51], v[186:189], v[194:197], v[48:51]
	v_mfma_f32_16x16x32_bf16 v[36:39], v[178:181], v[202:205], v[36:39]
	v_mfma_f32_16x16x32_bf16 v[32:35], v[186:189], v[202:205], v[32:35]
	v_mfma_f32_16x16x32_bf16 v[20:23], v[178:181], v[210:213], v[20:23]
	v_mfma_f32_16x16x32_bf16 v[16:19], v[186:189], v[210:213], v[16:19]
	v_mfma_f32_16x16x32_bf16 v[4:7], v[178:181], v[218:221], v[4:7]
	v_mfma_f32_16x16x32_bf16 v[0:3], v[186:189], v[218:221], v[0:3]
	s_setprio 0
	s_barrier
	s_add_i32 s73, 0, 0x18000
	v_add_u32_e32 v137, s73, v155
	s_add_i32 s74, 0, 0x1c000
	ds_read_b128 v[148:151], v137
	ds_read_b128 v[162:165], v137 offset:1024
	ds_read_b128 v[166:169], v137 offset:2048
	ds_read_b128 v[170:173], v137 offset:3072
	v_add_u32_e32 v137, s74, v155
	ds_read_b128 v[174:177], v137
	ds_read_b128 v[178:181], v137 offset:1024
	ds_read_b128 v[182:185], v137 offset:2048
	ds_read_b128 v[186:189], v137 offset:3072
	s_add_u32 s50, s50, 0x80000
	s_addc_u32 s51, s51, 0
	s_mov_b32 m0, s54
	v_lshl_add_u64 v[228:229], s[50:51], 0, v[128:129]
	ds_read_b128 v[190:193], v159 offset:32768
	ds_read_b128 v[194:197], v159 offset:33792
	ds_read_b128 v[198:201], v159 offset:34816
	ds_read_b128 v[202:205], v159 offset:35840
	ds_read_b128 v[206:209], v159 offset:36864
	ds_read_b128 v[210:213], v159 offset:37888
	ds_read_b128 v[214:217], v159 offset:38912
	ds_read_b128 v[218:221], v159 offset:39936
	global_load_lds_dwordx4 v[228:229], off
	v_lshl_add_u64 v[228:229], s[50:51], 0, v[132:133]
	s_mov_b32 m0, s55
	s_nop 0
	global_load_lds_dwordx4 v[228:229], off
	s_waitcnt vmcnt(8)
	s_waitcnt lgkmcnt(0)
	s_barrier
	s_setprio 1
	v_mfma_f32_16x16x32_bf16 v[124:127], v[148:151], v[190:193], v[124:127]
	v_mfma_f32_16x16x32_bf16 v[120:123], v[166:169], v[190:193], v[120:123]
	v_mfma_f32_16x16x32_bf16 v[108:111], v[148:151], v[198:201], v[108:111]
	v_mfma_f32_16x16x32_bf16 v[104:107], v[166:169], v[198:201], v[104:107]
	v_mfma_f32_16x16x32_bf16 v[92:95], v[148:151], v[206:209], v[92:95]
	v_mfma_f32_16x16x32_bf16 v[88:91], v[166:169], v[206:209], v[88:91]
	v_mfma_f32_16x16x32_bf16 v[76:79], v[148:151], v[214:217], v[76:79]
	v_mfma_f32_16x16x32_bf16 v[72:75], v[166:169], v[214:217], v[72:75]
	v_mfma_f32_16x16x32_bf16 v[124:127], v[162:165], v[194:197], v[124:127]
	v_mfma_f32_16x16x32_bf16 v[120:123], v[170:173], v[194:197], v[120:123]
	v_mfma_f32_16x16x32_bf16 v[108:111], v[162:165], v[202:205], v[108:111]
	v_mfma_f32_16x16x32_bf16 v[104:107], v[170:173], v[202:205], v[104:107]
	v_mfma_f32_16x16x32_bf16 v[92:95], v[162:165], v[210:213], v[92:95]
	v_mfma_f32_16x16x32_bf16 v[88:91], v[170:173], v[210:213], v[88:91]
	v_mfma_f32_16x16x32_bf16 v[76:79], v[162:165], v[218:221], v[76:79]
	v_mfma_f32_16x16x32_bf16 v[72:75], v[170:173], v[218:221], v[72:75]
	v_mfma_f32_16x16x32_bf16 v[116:119], v[174:177], v[190:193], v[116:119]
	v_mfma_f32_16x16x32_bf16 v[112:115], v[182:185], v[190:193], v[112:115]
	v_mfma_f32_16x16x32_bf16 v[100:103], v[174:177], v[198:201], v[100:103]
	v_mfma_f32_16x16x32_bf16 v[96:99], v[182:185], v[198:201], v[96:99]
	v_mfma_f32_16x16x32_bf16 v[84:87], v[174:177], v[206:209], v[84:87]
	v_mfma_f32_16x16x32_bf16 v[80:83], v[182:185], v[206:209], v[80:83]
	v_mfma_f32_16x16x32_bf16 v[68:71], v[174:177], v[214:217], v[68:71]
	v_mfma_f32_16x16x32_bf16 v[64:67], v[182:185], v[214:217], v[64:67]
	v_mfma_f32_16x16x32_bf16 v[116:119], v[178:181], v[194:197], v[116:119]
	v_mfma_f32_16x16x32_bf16 v[112:115], v[186:189], v[194:197], v[112:115]
	v_mfma_f32_16x16x32_bf16 v[100:103], v[178:181], v[202:205], v[100:103]
	v_mfma_f32_16x16x32_bf16 v[96:99], v[186:189], v[202:205], v[96:99]
	v_mfma_f32_16x16x32_bf16 v[84:87], v[178:181], v[210:213], v[84:87]
	v_mfma_f32_16x16x32_bf16 v[80:83], v[186:189], v[210:213], v[80:83]
	v_mfma_f32_16x16x32_bf16 v[68:71], v[178:181], v[218:221], v[68:71]
	v_mfma_f32_16x16x32_bf16 v[64:67], v[186:189], v[218:221], v[64:67]
	s_setprio 0
	s_barrier
	s_add_i32 s50, s73, s52
	v_lshl_add_u64 v[152:153], v[152:153], 0, s[22:23]
	s_mov_b32 m0, s50
	ds_read_b128 v[190:193], v159 offset:49152
	ds_read_b128 v[194:197], v159 offset:50176
	ds_read_b128 v[198:201], v159 offset:51200
	ds_read_b128 v[202:205], v159 offset:52224
	ds_read_b128 v[206:209], v159 offset:53248
	ds_read_b128 v[210:213], v159 offset:54272
	ds_read_b128 v[214:217], v159 offset:55296
	ds_read_b128 v[218:221], v159 offset:56320
	global_load_lds_dwordx4 v[152:153], off
	s_add_i32 m0, s50, 0x2000
	s_add_u32 s48, s48, 0x80080
	v_lshl_add_u64 v[152:153], v[222:223], 0, s[22:23]
	s_addc_u32 s49, s49, 0
	s_add_i32 s50, s74, s52
	global_load_lds_dwordx4 v[152:153], off
	v_lshl_add_u64 v[152:153], s[48:49], 0, v[130:131]
	s_mov_b32 m0, s50
	s_nop 0
	global_load_lds_dwordx4 v[152:153], off
	v_lshl_add_u64 v[152:153], s[48:49], 0, v[134:135]
	s_add_i32 m0, s50, 0x2000
	s_nop 0
	global_load_lds_dwordx4 v[152:153], off
	v_lshl_add_u64 v[152:153], v[224:225], 0, s[22:23]
	s_mov_b32 m0, s57
	s_nop 0
	global_load_lds_dwordx4 v[152:153], off
	v_lshl_add_u64 v[152:153], v[226:227], 0, s[22:23]
	s_mov_b32 m0, s58
	s_nop 0
	global_load_lds_dwordx4 v[152:153], off
	s_waitcnt vmcnt(8)
	s_waitcnt lgkmcnt(0)
	s_barrier
	s_setprio 1
	v_mfma_f32_16x16x32_bf16 v[60:63], v[148:151], v[190:193], v[60:63]
	v_mfma_f32_16x16x32_bf16 v[56:59], v[166:169], v[190:193], v[56:59]
	v_mfma_f32_16x16x32_bf16 v[44:47], v[148:151], v[198:201], v[44:47]
	v_mfma_f32_16x16x32_bf16 v[40:43], v[166:169], v[198:201], v[40:43]
	v_mfma_f32_16x16x32_bf16 v[28:31], v[148:151], v[206:209], v[28:31]
	v_mfma_f32_16x16x32_bf16 v[24:27], v[166:169], v[206:209], v[24:27]
	v_mfma_f32_16x16x32_bf16 v[12:15], v[148:151], v[214:217], v[12:15]
	v_mfma_f32_16x16x32_bf16 v[8:11], v[166:169], v[214:217], v[8:11]
	v_mfma_f32_16x16x32_bf16 v[60:63], v[162:165], v[194:197], v[60:63]
	v_mfma_f32_16x16x32_bf16 v[56:59], v[170:173], v[194:197], v[56:59]
	v_mfma_f32_16x16x32_bf16 v[44:47], v[162:165], v[202:205], v[44:47]
	v_mfma_f32_16x16x32_bf16 v[40:43], v[170:173], v[202:205], v[40:43]
	v_mfma_f32_16x16x32_bf16 v[28:31], v[162:165], v[210:213], v[28:31]
	v_mfma_f32_16x16x32_bf16 v[24:27], v[170:173], v[210:213], v[24:27]
	v_mfma_f32_16x16x32_bf16 v[12:15], v[162:165], v[218:221], v[12:15]
	v_mfma_f32_16x16x32_bf16 v[8:11], v[170:173], v[218:221], v[8:11]
	v_mfma_f32_16x16x32_bf16 v[52:55], v[174:177], v[190:193], v[52:55]
	v_mfma_f32_16x16x32_bf16 v[48:51], v[182:185], v[190:193], v[48:51]
	v_mfma_f32_16x16x32_bf16 v[36:39], v[174:177], v[198:201], v[36:39]
	v_mfma_f32_16x16x32_bf16 v[32:35], v[182:185], v[198:201], v[32:35]
	v_mfma_f32_16x16x32_bf16 v[20:23], v[174:177], v[206:209], v[20:23]
	v_mfma_f32_16x16x32_bf16 v[16:19], v[182:185], v[206:209], v[16:19]
	v_mfma_f32_16x16x32_bf16 v[4:7], v[174:177], v[214:217], v[4:7]
	v_mfma_f32_16x16x32_bf16 v[0:3], v[182:185], v[214:217], v[0:3]
	v_mfma_f32_16x16x32_bf16 v[52:55], v[178:181], v[194:197], v[52:55]
	v_mfma_f32_16x16x32_bf16 v[48:51], v[186:189], v[194:197], v[48:51]
	v_mfma_f32_16x16x32_bf16 v[36:39], v[178:181], v[202:205], v[36:39]
	v_mfma_f32_16x16x32_bf16 v[32:35], v[186:189], v[202:205], v[32:35]
	v_mfma_f32_16x16x32_bf16 v[20:23], v[178:181], v[210:213], v[20:23]
	v_mfma_f32_16x16x32_bf16 v[16:19], v[186:189], v[210:213], v[16:19]
	v_mfma_f32_16x16x32_bf16 v[4:7], v[178:181], v[218:221], v[4:7]
	v_mfma_f32_16x16x32_bf16 v[0:3], v[186:189], v[218:221], v[0:3]
	s_setprio 0
	s_barrier
	s_add_i32 s72, s72, 2
	s_add_u32 s70, s70, 0x100
	s_addc_u32 s71, s71, 0
	s_add_u32 s46, s46, 0x100
	s_addc_u32 s47, s47, 0
	s_cmp_gt_u32 s72, 29
	s_cbranch_scc0 .LBB0_178
	s_and_b64 vcc, exec, s[24:25]
	s_cbranch_vccz .LBB0_181
	s_barrier

.LBB0_337:
	ds_read_b128 v[144:147], v151
	ds_read_b128 v[156:159], v151 offset:1024
	ds_read_b128 v[160:163], v151 offset:2048
	ds_read_b128 v[164:167], v151 offset:3072
	ds_read_b128 v[168:171], v152
	ds_read_b128 v[172:175], v152 offset:1024
	ds_read_b128 v[176:179], v152 offset:2048
	ds_read_b128 v[180:183], v152 offset:3072
	s_add_u32 s50, s48, 0xfff80080
	s_addc_u32 s51, s49, -1
	s_cmp_eq_u32 s75, 28
	s_cselect_b32 s53, s31, s51
	s_cselect_b32 s52, s47, s50
	s_cselect_b32 s51, s27, s74
	s_cselect_b32 s50, s71, s72
	v_lshl_add_u64 v[216:217], s[48:49], 0, v[138:139]
	s_add_i32 m0, s57, 0xc000
	ds_read_b128 v[184:187], v153
	ds_read_b128 v[188:191], v153 offset:1024
	ds_read_b128 v[192:195], v153 offset:2048
	ds_read_b128 v[196:199], v153 offset:3072
	ds_read_b128 v[200:203], v153 offset:4096
	ds_read_b128 v[204:207], v153 offset:5120
	ds_read_b128 v[208:211], v153 offset:6144
	ds_read_b128 v[212:215], v153 offset:7168
	global_load_lds_dwordx4 v[216:217], off
	v_lshl_add_u64 v[216:217], s[48:49], 0, v[136:137]
	s_add_i32 m0, s57, 0xe000
	s_nop 0
	global_load_lds_dwordx4 v[216:217], off
	s_waitcnt vmcnt(8)
	s_waitcnt lgkmcnt(0)
	s_barrier
	s_setprio 1
	v_mfma_f32_16x16x32_bf16 v[124:127], v[144:147], v[184:187], v[124:127]
	v_mfma_f32_16x16x32_bf16 v[120:123], v[160:163], v[184:187], v[120:123]
	v_mfma_f32_16x16x32_bf16 v[108:111], v[144:147], v[192:195], v[108:111]
	v_mfma_f32_16x16x32_bf16 v[104:107], v[160:163], v[192:195], v[104:107]
	v_mfma_f32_16x16x32_bf16 v[92:95], v[144:147], v[200:203], v[92:95]
	v_mfma_f32_16x16x32_bf16 v[88:91], v[160:163], v[200:203], v[88:91]
	v_mfma_f32_16x16x32_bf16 v[76:79], v[144:147], v[208:211], v[76:79]
	v_mfma_f32_16x16x32_bf16 v[72:75], v[160:163], v[208:211], v[72:75]
	v_mfma_f32_16x16x32_bf16 v[124:127], v[156:159], v[188:191], v[124:127]
	v_mfma_f32_16x16x32_bf16 v[120:123], v[164:167], v[188:191], v[120:123]
	v_mfma_f32_16x16x32_bf16 v[108:111], v[156:159], v[196:199], v[108:111]
	v_mfma_f32_16x16x32_bf16 v[104:107], v[164:167], v[196:199], v[104:107]
	v_mfma_f32_16x16x32_bf16 v[92:95], v[156:159], v[204:207], v[92:95]
	v_mfma_f32_16x16x32_bf16 v[88:91], v[164:167], v[204:207], v[88:91]
	v_mfma_f32_16x16x32_bf16 v[76:79], v[156:159], v[212:215], v[76:79]
	v_mfma_f32_16x16x32_bf16 v[72:75], v[164:167], v[212:215], v[72:75]
	v_mfma_f32_16x16x32_bf16 v[116:119], v[168:171], v[184:187], v[116:119]
	v_mfma_f32_16x16x32_bf16 v[112:115], v[176:179], v[184:187], v[112:115]
	v_mfma_f32_16x16x32_bf16 v[100:103], v[168:171], v[192:195], v[100:103]
	v_mfma_f32_16x16x32_bf16 v[96:99], v[176:179], v[192:195], v[96:99]
	v_mfma_f32_16x16x32_bf16 v[84:87], v[168:171], v[200:203], v[84:87]
	v_mfma_f32_16x16x32_bf16 v[80:83], v[176:179], v[200:203], v[80:83]
	v_mfma_f32_16x16x32_bf16 v[68:71], v[168:171], v[208:211], v[68:71]
	v_mfma_f32_16x16x32_bf16 v[64:67], v[176:179], v[208:211], v[64:67]
	v_mfma_f32_16x16x32_bf16 v[116:119], v[172:175], v[188:191], v[116:119]
	v_mfma_f32_16x16x32_bf16 v[112:115], v[180:183], v[188:191], v[112:115]
	v_mfma_f32_16x16x32_bf16 v[100:103], v[172:175], v[196:199], v[100:103]
	v_mfma_f32_16x16x32_bf16 v[96:99], v[180:183], v[196:199], v[96:99]
	v_mfma_f32_16x16x32_bf16 v[84:87], v[172:175], v[204:207], v[84:87]
	v_mfma_f32_16x16x32_bf16 v[80:83], v[180:183], v[204:207], v[80:83]
	v_mfma_f32_16x16x32_bf16 v[68:71], v[172:175], v[212:215], v[68:71]
	v_mfma_f32_16x16x32_bf16 v[64:67], v[180:183], v[212:215], v[64:67]
	s_setprio 0
	s_barrier
	s_add_i32 s76, s66, s56
	v_lshl_add_u64 v[216:217], s[50:51], 0, v[130:131]
	s_mov_b32 m0, s76
	ds_read_b128 v[184:187], v153 offset:16384
	ds_read_b128 v[188:191], v153 offset:17408
	ds_read_b128 v[192:195], v153 offset:18432
	ds_read_b128 v[196:199], v153 offset:19456
	ds_read_b128 v[200:203], v153 offset:20480
	ds_read_b128 v[204:207], v153 offset:21504
	ds_read_b128 v[208:211], v153 offset:22528
	ds_read_b128 v[212:215], v153 offset:23552
	global_load_lds_dwordx4 v[216:217], off
	s_add_i32 m0, s76, 0x2000
	s_add_u32 s76, s50, 0x80000
	v_lshl_add_u64 v[218:219], s[50:51], 0, v[134:135]
	s_addc_u32 s77, s51, 0
	s_add_i32 s78, s67, s56
	global_load_lds_dwordx4 v[218:219], off
	v_lshl_add_u64 v[220:221], s[76:77], 0, v[130:131]
	s_mov_b32 m0, s78
	v_lshl_add_u64 v[222:223], s[52:53], 0, v[132:133]
	global_load_lds_dwordx4 v[220:221], off
	v_lshl_add_u64 v[220:221], s[76:77], 0, v[134:135]
	s_add_i32 m0, s78, 0x2000
	s_nop 0
	global_load_lds_dwordx4 v[220:221], off
	v_lshl_add_u64 v[220:221], s[52:53], 0, v[128:129]
	s_mov_b32 m0, s57
	s_nop 0
	global_load_lds_dwordx4 v[220:221], off
	s_mov_b32 m0, s58
	s_nop 0
	global_load_lds_dwordx4 v[222:223], off
	s_waitcnt vmcnt(8)
	s_waitcnt lgkmcnt(0)
	s_barrier
	s_setprio 1
	v_mfma_f32_16x16x32_bf16 v[60:63], v[144:147], v[184:187], v[60:63]
	v_mfma_f32_16x16x32_bf16 v[56:59], v[160:163], v[184:187], v[56:59]
	v_mfma_f32_16x16x32_bf16 v[44:47], v[144:147], v[192:195], v[44:47]
	v_mfma_f32_16x16x32_bf16 v[40:43], v[160:163], v[192:195], v[40:43]
	v_mfma_f32_16x16x32_bf16 v[28:31], v[144:147], v[200:203], v[28:31]
	v_mfma_f32_16x16x32_bf16 v[24:27], v[160:163], v[200:203], v[24:27]
	v_mfma_f32_16x16x32_bf16 v[12:15], v[144:147], v[208:211], v[12:15]
	v_mfma_f32_16x16x32_bf16 v[8:11], v[160:163], v[208:211], v[8:11]
	v_mfma_f32_16x16x32_bf16 v[60:63], v[156:159], v[188:191], v[60:63]
	v_mfma_f32_16x16x32_bf16 v[56:59], v[164:167], v[188:191], v[56:59]
	v_mfma_f32_16x16x32_bf16 v[44:47], v[156:159], v[196:199], v[44:47]
	v_mfma_f32_16x16x32_bf16 v[40:43], v[164:167], v[196:199], v[40:43]
	v_mfma_f32_16x16x32_bf16 v[28:31], v[156:159], v[204:207], v[28:31]
	v_mfma_f32_16x16x32_bf16 v[24:27], v[164:167], v[204:207], v[24:27]
	v_mfma_f32_16x16x32_bf16 v[12:15], v[156:159], v[212:215], v[12:15]
	v_mfma_f32_16x16x32_bf16 v[8:11], v[164:167], v[212:215], v[8:11]
	v_mfma_f32_16x16x32_bf16 v[52:55], v[168:171], v[184:187], v[52:55]
	v_mfma_f32_16x16x32_bf16 v[48:51], v[176:179], v[184:187], v[48:51]
	v_mfma_f32_16x16x32_bf16 v[36:39], v[168:171], v[192:195], v[36:39]
	v_mfma_f32_16x16x32_bf16 v[32:35], v[176:179], v[192:195], v[32:35]
	v_mfma_f32_16x16x32_bf16 v[20:23], v[168:171], v[200:203], v[20:23]
	v_mfma_f32_16x16x32_bf16 v[16:19], v[176:179], v[200:203], v[16:19]
	v_mfma_f32_16x16x32_bf16 v[4:7], v[168:171], v[208:211], v[4:7]
	v_mfma_f32_16x16x32_bf16 v[0:3], v[176:179], v[208:211], v[0:3]
	v_mfma_f32_16x16x32_bf16 v[52:55], v[172:175], v[188:191], v[52:55]
	v_mfma_f32_16x16x32_bf16 v[48:51], v[180:183], v[188:191], v[48:51]
	v_mfma_f32_16x16x32_bf16 v[36:39], v[172:175], v[196:199], v[36:39]
	v_mfma_f32_16x16x32_bf16 v[32:35], v[180:183], v[196:199], v[32:35]
	v_mfma_f32_16x16x32_bf16 v[20:23], v[172:175], v[204:207], v[20:23]
	v_mfma_f32_16x16x32_bf16 v[16:19], v[180:183], v[204:207], v[16:19]
	v_mfma_f32_16x16x32_bf16 v[4:7], v[172:175], v[212:215], v[4:7]
	v_mfma_f32_16x16x32_bf16 v[0:3], v[180:183], v[212:215], v[0:3]
	s_setprio 0
	s_barrier
	s_add_i32 s76, 0, 0x18000
	v_add_u32_e32 v155, s76, v149
	s_add_i32 s77, 0, 0x1c000
	ds_read_b128 v[144:147], v155
	ds_read_b128 v[156:159], v155 offset:1024
	ds_read_b128 v[160:163], v155 offset:2048
	ds_read_b128 v[164:167], v155 offset:3072
	v_add_u32_e32 v155, s77, v149
	ds_read_b128 v[168:171], v155
	ds_read_b128 v[172:175], v155 offset:1024
	ds_read_b128 v[176:179], v155 offset:2048
	ds_read_b128 v[180:183], v155 offset:3072
	s_add_u32 s52, s52, 0x80000
	s_addc_u32 s53, s53, 0
	s_mov_b32 m0, s59
	v_lshl_add_u64 v[224:225], s[52:53], 0, v[128:129]
	ds_read_b128 v[184:187], v153 offset:32768
	ds_read_b128 v[188:191], v153 offset:33792
	ds_read_b128 v[192:195], v153 offset:34816
	ds_read_b128 v[196:199], v153 offset:35840
	ds_read_b128 v[200:203], v153 offset:36864
	ds_read_b128 v[204:207], v153 offset:37888
	ds_read_b128 v[208:211], v153 offset:38912
	ds_read_b128 v[212:215], v153 offset:39936
	global_load_lds_dwordx4 v[224:225], off
	v_lshl_add_u64 v[224:225], s[52:53], 0, v[132:133]
	s_mov_b32 m0, s60
	s_nop 0
	global_load_lds_dwordx4 v[224:225], off
	s_waitcnt vmcnt(8)
	s_waitcnt lgkmcnt(0)
	s_barrier
	s_setprio 1
	v_mfma_f32_16x16x32_bf16 v[124:127], v[144:147], v[184:187], v[124:127]
	v_mfma_f32_16x16x32_bf16 v[120:123], v[160:163], v[184:187], v[120:123]
	v_mfma_f32_16x16x32_bf16 v[108:111], v[144:147], v[192:195], v[108:111]
	v_mfma_f32_16x16x32_bf16 v[104:107], v[160:163], v[192:195], v[104:107]
	v_mfma_f32_16x16x32_bf16 v[92:95], v[144:147], v[200:203], v[92:95]
	v_mfma_f32_16x16x32_bf16 v[88:91], v[160:163], v[200:203], v[88:91]
	v_mfma_f32_16x16x32_bf16 v[76:79], v[144:147], v[208:211], v[76:79]
	v_mfma_f32_16x16x32_bf16 v[72:75], v[160:163], v[208:211], v[72:75]
	v_mfma_f32_16x16x32_bf16 v[124:127], v[156:159], v[188:191], v[124:127]
	v_mfma_f32_16x16x32_bf16 v[120:123], v[164:167], v[188:191], v[120:123]
	v_mfma_f32_16x16x32_bf16 v[108:111], v[156:159], v[196:199], v[108:111]
	v_mfma_f32_16x16x32_bf16 v[104:107], v[164:167], v[196:199], v[104:107]
	v_mfma_f32_16x16x32_bf16 v[92:95], v[156:159], v[204:207], v[92:95]
	v_mfma_f32_16x16x32_bf16 v[88:91], v[164:167], v[204:207], v[88:91]
	v_mfma_f32_16x16x32_bf16 v[76:79], v[156:159], v[212:215], v[76:79]
	v_mfma_f32_16x16x32_bf16 v[72:75], v[164:167], v[212:215], v[72:75]
	v_mfma_f32_16x16x32_bf16 v[116:119], v[168:171], v[184:187], v[116:119]
	v_mfma_f32_16x16x32_bf16 v[112:115], v[176:179], v[184:187], v[112:115]
	v_mfma_f32_16x16x32_bf16 v[100:103], v[168:171], v[192:195], v[100:103]
	v_mfma_f32_16x16x32_bf16 v[96:99], v[176:179], v[192:195], v[96:99]
	v_mfma_f32_16x16x32_bf16 v[84:87], v[168:171], v[200:203], v[84:87]
	v_mfma_f32_16x16x32_bf16 v[80:83], v[176:179], v[200:203], v[80:83]
	v_mfma_f32_16x16x32_bf16 v[68:71], v[168:171], v[208:211], v[68:71]
	v_mfma_f32_16x16x32_bf16 v[64:67], v[176:179], v[208:211], v[64:67]
	v_mfma_f32_16x16x32_bf16 v[116:119], v[172:175], v[188:191], v[116:119]
	v_mfma_f32_16x16x32_bf16 v[112:115], v[180:183], v[188:191], v[112:115]
	v_mfma_f32_16x16x32_bf16 v[100:103], v[172:175], v[196:199], v[100:103]
	v_mfma_f32_16x16x32_bf16 v[96:99], v[180:183], v[196:199], v[96:99]
	v_mfma_f32_16x16x32_bf16 v[84:87], v[172:175], v[204:207], v[84:87]
	v_mfma_f32_16x16x32_bf16 v[80:83], v[180:183], v[204:207], v[80:83]
	v_mfma_f32_16x16x32_bf16 v[68:71], v[172:175], v[212:215], v[68:71]
	v_mfma_f32_16x16x32_bf16 v[64:67], v[180:183], v[212:215], v[64:67]
	s_setprio 0
	s_barrier
	s_add_i32 s52, s76, s56
	v_lshl_add_u64 v[216:217], v[216:217], 0, s[22:23]
	s_mov_b32 m0, s52
	ds_read_b128 v[184:187], v153 offset:49152
	ds_read_b128 v[188:191], v153 offset:50176
	ds_read_b128 v[192:195], v153 offset:51200
	ds_read_b128 v[196:199], v153 offset:52224
	ds_read_b128 v[200:203], v153 offset:53248
	ds_read_b128 v[204:207], v153 offset:54272
	ds_read_b128 v[208:211], v153 offset:55296
	ds_read_b128 v[212:215], v153 offset:56320
	global_load_lds_dwordx4 v[216:217], off
	s_add_i32 m0, s52, 0x2000
	s_add_u32 s50, s50, 0x80080
	v_lshl_add_u64 v[216:217], v[218:219], 0, s[22:23]
	s_addc_u32 s51, s51, 0
	s_add_i32 s52, s77, s56
	global_load_lds_dwordx4 v[216:217], off
	v_lshl_add_u64 v[216:217], s[50:51], 0, v[130:131]
	s_mov_b32 m0, s52
	s_nop 0
	global_load_lds_dwordx4 v[216:217], off
	v_lshl_add_u64 v[216:217], s[50:51], 0, v[134:135]
	s_add_i32 m0, s52, 0x2000
	s_nop 0
	global_load_lds_dwordx4 v[216:217], off
	v_lshl_add_u64 v[216:217], v[220:221], 0, s[22:23]
	s_mov_b32 m0, s62
	s_nop 0
	global_load_lds_dwordx4 v[216:217], off
	v_lshl_add_u64 v[216:217], v[222:223], 0, s[22:23]
	s_mov_b32 m0, s63
	s_nop 0
	global_load_lds_dwordx4 v[216:217], off
	s_waitcnt vmcnt(8)
	s_waitcnt lgkmcnt(0)
	s_barrier
	s_setprio 1
	v_mfma_f32_16x16x32_bf16 v[60:63], v[144:147], v[184:187], v[60:63]
	v_mfma_f32_16x16x32_bf16 v[56:59], v[160:163], v[184:187], v[56:59]
	v_mfma_f32_16x16x32_bf16 v[44:47], v[144:147], v[192:195], v[44:47]
	v_mfma_f32_16x16x32_bf16 v[40:43], v[160:163], v[192:195], v[40:43]
	v_mfma_f32_16x16x32_bf16 v[28:31], v[144:147], v[200:203], v[28:31]
	v_mfma_f32_16x16x32_bf16 v[24:27], v[160:163], v[200:203], v[24:27]
	v_mfma_f32_16x16x32_bf16 v[12:15], v[144:147], v[208:211], v[12:15]
	v_mfma_f32_16x16x32_bf16 v[8:11], v[160:163], v[208:211], v[8:11]
	v_mfma_f32_16x16x32_bf16 v[60:63], v[156:159], v[188:191], v[60:63]
	v_mfma_f32_16x16x32_bf16 v[56:59], v[164:167], v[188:191], v[56:59]
	v_mfma_f32_16x16x32_bf16 v[44:47], v[156:159], v[196:199], v[44:47]
	v_mfma_f32_16x16x32_bf16 v[40:43], v[164:167], v[196:199], v[40:43]
	v_mfma_f32_16x16x32_bf16 v[28:31], v[156:159], v[204:207], v[28:31]
	v_mfma_f32_16x16x32_bf16 v[24:27], v[164:167], v[204:207], v[24:27]
	v_mfma_f32_16x16x32_bf16 v[12:15], v[156:159], v[212:215], v[12:15]
	v_mfma_f32_16x16x32_bf16 v[8:11], v[164:167], v[212:215], v[8:11]
	v_mfma_f32_16x16x32_bf16 v[52:55], v[168:171], v[184:187], v[52:55]
	v_mfma_f32_16x16x32_bf16 v[48:51], v[176:179], v[184:187], v[48:51]
	v_mfma_f32_16x16x32_bf16 v[36:39], v[168:171], v[192:195], v[36:39]
	v_mfma_f32_16x16x32_bf16 v[32:35], v[176:179], v[192:195], v[32:35]
	v_mfma_f32_16x16x32_bf16 v[20:23], v[168:171], v[200:203], v[20:23]
	v_mfma_f32_16x16x32_bf16 v[16:19], v[176:179], v[200:203], v[16:19]
	v_mfma_f32_16x16x32_bf16 v[4:7], v[168:171], v[208:211], v[4:7]
	v_mfma_f32_16x16x32_bf16 v[0:3], v[176:179], v[208:211], v[0:3]
	v_mfma_f32_16x16x32_bf16 v[52:55], v[172:175], v[188:191], v[52:55]
	v_mfma_f32_16x16x32_bf16 v[48:51], v[180:183], v[188:191], v[48:51]
	v_mfma_f32_16x16x32_bf16 v[36:39], v[172:175], v[196:199], v[36:39]
	v_mfma_f32_16x16x32_bf16 v[32:35], v[180:183], v[196:199], v[32:35]
	v_mfma_f32_16x16x32_bf16 v[20:23], v[172:175], v[204:207], v[20:23]
	v_mfma_f32_16x16x32_bf16 v[16:19], v[180:183], v[204:207], v[16:19]
	v_mfma_f32_16x16x32_bf16 v[4:7], v[172:175], v[212:215], v[4:7]
	v_mfma_f32_16x16x32_bf16 v[0:3], v[180:183], v[212:215], v[0:3]
	s_setprio 0
	s_barrier
	s_add_i32 s75, s75, 2
	s_add_u32 s72, s72, 0x100
	s_addc_u32 s74, s74, 0
	s_add_u32 s48, s48, 0x100
	s_addc_u32 s49, s49, 0
	s_cmp_gt_u32 s75, 29
	s_cbranch_scc0 .LBB0_337
	s_and_b64 vcc, exec, s[24:25]
	s_cbranch_vccz .LBB0_340
	s_barrier

.LBB0_435:
	ds_read_b128 v[148:151], v222
	ds_read_b128 v[152:155], v222 offset:1024
	ds_read_b128 v[156:159], v222 offset:2048
	ds_read_b128 v[160:163], v222 offset:3072
	ds_read_b128 v[132:135], v223
	ds_read_b128 v[136:139], v223 offset:1024
	ds_read_b128 v[140:143], v223 offset:2048
	ds_read_b128 v[144:147], v223 offset:3072
	s_add_u32 s10, s54, 0xfff80080
	s_addc_u32 s11, s55, -1
	s_cmp_eq_u32 s84, 28
	s_cselect_b32 s59, s25, s11
	s_cselect_b32 s58, s46, s10
	s_cselect_b32 s57, s23, s83
	s_cselect_b32 s56, s47, s82
	v_lshl_add_u64 v[2:3], s[54:55], 0, v[208:209]
	s_add_i32 m0, s37, 0xc000
	s_waitcnt lgkmcnt(0)
	ds_read_b128 v[164:167], v224
	ds_read_b128 v[168:171], v224 offset:1024
	ds_read_b128 v[172:175], v224 offset:2048
	ds_read_b128 v[176:179], v224 offset:3072
	ds_read_b128 v[180:183], v224 offset:4096
	ds_read_b128 v[184:187], v224 offset:5120
	ds_read_b128 v[188:191], v224 offset:6144
	ds_read_b128 v[192:195], v224 offset:7168
	global_load_lds_dwordx4 v[2:3], off
	v_lshl_add_u64 v[2:3], s[54:55], 0, v[206:207]
	s_add_i32 m0, s37, 0xe000
	s_nop 0
	global_load_lds_dwordx4 v[2:3], off
	s_waitcnt vmcnt(8)
	s_waitcnt lgkmcnt(0)
	s_barrier
	s_setprio 1
	v_mfma_f32_16x16x32_bf16 v[120:123], v[148:151], v[164:167], v[120:123]
	v_mfma_f32_16x16x32_bf16 v[116:119], v[156:159], v[164:167], v[116:119]
	v_mfma_f32_16x16x32_bf16 v[104:107], v[148:151], v[172:175], v[104:107]
	v_mfma_f32_16x16x32_bf16 v[100:103], v[156:159], v[172:175], v[100:103]
	v_mfma_f32_16x16x32_bf16 v[88:91], v[148:151], v[180:183], v[88:91]
	v_mfma_f32_16x16x32_bf16 v[84:87], v[156:159], v[180:183], v[84:87]
	v_mfma_f32_16x16x32_bf16 v[76:79], v[148:151], v[188:191], v[76:79]
	v_mfma_f32_16x16x32_bf16 v[72:75], v[156:159], v[188:191], v[72:75]
	v_mfma_f32_16x16x32_bf16 v[120:123], v[152:155], v[168:171], v[120:123]
	v_mfma_f32_16x16x32_bf16 v[116:119], v[160:163], v[168:171], v[116:119]
	v_mfma_f32_16x16x32_bf16 v[104:107], v[152:155], v[176:179], v[104:107]
	v_mfma_f32_16x16x32_bf16 v[100:103], v[160:163], v[176:179], v[100:103]
	v_mfma_f32_16x16x32_bf16 v[88:91], v[152:155], v[184:187], v[88:91]
	v_mfma_f32_16x16x32_bf16 v[84:87], v[160:163], v[184:187], v[84:87]
	v_mfma_f32_16x16x32_bf16 v[76:79], v[152:155], v[192:195], v[76:79]
	v_mfma_f32_16x16x32_bf16 v[72:75], v[160:163], v[192:195], v[72:75]
	v_mfma_f32_16x16x32_bf16 v[128:131], v[132:135], v[164:167], v[128:131]
	v_mfma_f32_16x16x32_bf16 v[124:127], v[140:143], v[164:167], v[124:127]
	v_mfma_f32_16x16x32_bf16 v[112:115], v[132:135], v[172:175], v[112:115]
	v_mfma_f32_16x16x32_bf16 v[108:111], v[140:143], v[172:175], v[108:111]
	v_mfma_f32_16x16x32_bf16 v[96:99], v[132:135], v[180:183], v[96:99]
	v_mfma_f32_16x16x32_bf16 v[92:95], v[140:143], v[180:183], v[92:95]
	v_mfma_f32_16x16x32_bf16 v[80:83], v[132:135], v[188:191], v[80:83]
	v_mfma_f32_16x16x32_bf16 v[68:71], v[140:143], v[188:191], v[68:71]
	v_mfma_f32_16x16x32_bf16 v[128:131], v[136:139], v[168:171], v[128:131]
	v_mfma_f32_16x16x32_bf16 v[124:127], v[144:147], v[168:171], v[124:127]
	v_mfma_f32_16x16x32_bf16 v[112:115], v[136:139], v[176:179], v[112:115]
	v_mfma_f32_16x16x32_bf16 v[108:111], v[144:147], v[176:179], v[108:111]
	v_mfma_f32_16x16x32_bf16 v[96:99], v[136:139], v[184:187], v[96:99]
	v_mfma_f32_16x16x32_bf16 v[92:95], v[144:147], v[184:187], v[92:95]
	v_mfma_f32_16x16x32_bf16 v[80:83], v[136:139], v[192:195], v[80:83]
	v_mfma_f32_16x16x32_bf16 v[68:71], v[144:147], v[192:195], v[68:71]
	s_setprio 0
	s_barrier
	s_add_i32 s10, s67, s48
	v_lshl_add_u64 v[2:3], s[56:57], 0, v[198:199]
	s_mov_b32 m0, s10
	ds_read_b128 v[188:191], v224 offset:16384
	ds_read_b128 v[192:195], v224 offset:17408
	ds_read_b128 v[180:183], v224 offset:18432
	ds_read_b128 v[184:187], v224 offset:19456
	ds_read_b128 v[172:175], v224 offset:20480
	ds_read_b128 v[176:179], v224 offset:21504
	ds_read_b128 v[164:167], v224 offset:22528
	ds_read_b128 v[168:171], v224 offset:23552
	global_load_lds_dwordx4 v[2:3], off
	s_add_i32 m0, s10, 0x2000
	s_add_u32 s10, s56, 0x80000
	v_lshl_add_u64 v[212:213], s[56:57], 0, v[202:203]
	s_addc_u32 s11, s57, 0
	s_add_i32 s78, s70, s48
	global_load_lds_dwordx4 v[212:213], off
	v_lshl_add_u64 v[214:215], s[10:11], 0, v[198:199]
	s_mov_b32 m0, s78
	v_lshl_add_u64 v[216:217], s[58:59], 0, v[200:201]
	global_load_lds_dwordx4 v[214:215], off
	v_lshl_add_u64 v[214:215], s[10:11], 0, v[202:203]
	s_add_i32 m0, s78, 0x2000
	v_cmp_ne_u32_e64 s[10:11], 1, v227
	global_load_lds_dwordx4 v[214:215], off
	v_lshl_add_u64 v[214:215], s[58:59], 0, v[196:197]
	s_mov_b32 m0, s37
	s_andn2_b64 vcc, exec, s[52:53]
	global_load_lds_dwordx4 v[214:215], off
	s_mov_b32 m0, s60
	s_nop 0
	global_load_lds_dwordx4 v[216:217], off
	s_waitcnt vmcnt(8)
	s_waitcnt lgkmcnt(0)
	s_barrier
	s_cbranch_vccnz .LBB0_437
	s_setprio 1
	v_mfma_f32_16x16x32_bf16 v[56:59], v[148:151], v[188:191], v[56:59]
	v_mfma_f32_16x16x32_bf16 v[52:55], v[156:159], v[188:191], v[52:55]
	v_mfma_f32_16x16x32_bf16 v[40:43], v[148:151], v[180:183], v[40:43]
	v_mfma_f32_16x16x32_bf16 v[36:39], v[156:159], v[180:183], v[36:39]
	v_mfma_f32_16x16x32_bf16 v[24:27], v[148:151], v[172:175], v[24:27]
	v_mfma_f32_16x16x32_bf16 v[20:23], v[156:159], v[172:175], v[20:23]
	v_mfma_f32_16x16x32_bf16 v[8:11], v[148:151], v[164:167], v[8:11]
	v_mfma_f32_16x16x32_bf16 v[4:7], v[156:159], v[164:167], v[4:7]
	v_mfma_f32_16x16x32_bf16 v[56:59], v[152:155], v[192:195], v[56:59]
	v_mfma_f32_16x16x32_bf16 v[52:55], v[160:163], v[192:195], v[52:55]
	v_mfma_f32_16x16x32_bf16 v[40:43], v[152:155], v[184:187], v[40:43]
	v_mfma_f32_16x16x32_bf16 v[36:39], v[160:163], v[184:187], v[36:39]
	v_mfma_f32_16x16x32_bf16 v[24:27], v[152:155], v[176:179], v[24:27]
	v_mfma_f32_16x16x32_bf16 v[20:23], v[160:163], v[176:179], v[20:23]
	v_mfma_f32_16x16x32_bf16 v[8:11], v[152:155], v[168:171], v[8:11]
	v_mfma_f32_16x16x32_bf16 v[4:7], v[160:163], v[168:171], v[4:7]
	v_mfma_f32_16x16x32_bf16 v[64:67], v[132:135], v[188:191], v[64:67]
	v_mfma_f32_16x16x32_bf16 v[60:63], v[140:143], v[188:191], v[60:63]
	v_mfma_f32_16x16x32_bf16 v[48:51], v[132:135], v[180:183], v[48:51]
	v_mfma_f32_16x16x32_bf16 v[44:47], v[140:143], v[180:183], v[44:47]
	v_mfma_f32_16x16x32_bf16 v[32:35], v[132:135], v[172:175], v[32:35]
	v_mfma_f32_16x16x32_bf16 v[28:31], v[140:143], v[172:175], v[28:31]
	v_mfma_f32_16x16x32_bf16 v[16:19], v[132:135], v[164:167], v[16:19]
	v_mfma_f32_16x16x32_bf16 v[12:15], v[140:143], v[164:167], v[12:15]
	v_mfma_f32_16x16x32_bf16 v[64:67], v[136:139], v[192:195], v[64:67]
	v_mfma_f32_16x16x32_bf16 v[60:63], v[144:147], v[192:195], v[60:63]
	v_mfma_f32_16x16x32_bf16 v[48:51], v[136:139], v[184:187], v[48:51]
	v_mfma_f32_16x16x32_bf16 v[44:47], v[144:147], v[184:187], v[44:47]
	v_mfma_f32_16x16x32_bf16 v[32:35], v[136:139], v[176:179], v[32:35]
	v_mfma_f32_16x16x32_bf16 v[28:31], v[144:147], v[176:179], v[28:31]
	v_mfma_f32_16x16x32_bf16 v[16:19], v[136:139], v[168:171], v[16:19]
	v_mfma_f32_16x16x32_bf16 v[12:15], v[144:147], v[168:171], v[12:15]
	s_setprio 0
.LBB0_437:
	s_barrier
	s_add_i32 s78, 0, 0x18000
	v_add_u32_e32 v1, s78, v220
	s_add_i32 s79, 0, 0x1c000
	ds_read_b128 v[148:151], v1
	ds_read_b128 v[152:155], v1 offset:1024
	ds_read_b128 v[156:159], v1 offset:2048
	ds_read_b128 v[160:163], v1 offset:3072
	v_add_u32_e32 v1, s79, v220
	ds_read_b128 v[132:135], v1
	ds_read_b128 v[136:139], v1 offset:1024
	ds_read_b128 v[140:143], v1 offset:2048
	ds_read_b128 v[144:147], v1 offset:3072
	s_add_u32 s58, s58, 0x80000
	s_addc_u32 s59, s59, 0
	s_mov_b32 m0, s61
	v_lshl_add_u64 v[228:229], s[58:59], 0, v[196:197]
	s_waitcnt lgkmcnt(0)
	ds_read_b128 v[164:167], v224 offset:32768
	ds_read_b128 v[168:171], v224 offset:33792
	ds_read_b128 v[172:175], v224 offset:34816
	ds_read_b128 v[176:179], v224 offset:35840
	ds_read_b128 v[180:183], v224 offset:36864
	ds_read_b128 v[184:187], v224 offset:37888
	ds_read_b128 v[188:191], v224 offset:38912
	ds_read_b128 v[192:195], v224 offset:39936
	global_load_lds_dwordx4 v[228:229], off
	v_lshl_add_u64 v[228:229], s[58:59], 0, v[200:201]
	s_mov_b32 m0, s62
	s_nop 0
	global_load_lds_dwordx4 v[228:229], off
	s_waitcnt vmcnt(8)
	s_waitcnt lgkmcnt(0)
	s_barrier
	s_setprio 1
	v_mfma_f32_16x16x32_bf16 v[120:123], v[148:151], v[164:167], v[120:123]
	v_mfma_f32_16x16x32_bf16 v[116:119], v[156:159], v[164:167], v[116:119]
	v_mfma_f32_16x16x32_bf16 v[104:107], v[148:151], v[172:175], v[104:107]
	v_mfma_f32_16x16x32_bf16 v[100:103], v[156:159], v[172:175], v[100:103]
	v_mfma_f32_16x16x32_bf16 v[88:91], v[148:151], v[180:183], v[88:91]
	v_mfma_f32_16x16x32_bf16 v[84:87], v[156:159], v[180:183], v[84:87]
	v_mfma_f32_16x16x32_bf16 v[76:79], v[148:151], v[188:191], v[76:79]
	v_mfma_f32_16x16x32_bf16 v[72:75], v[156:159], v[188:191], v[72:75]
	v_mfma_f32_16x16x32_bf16 v[120:123], v[152:155], v[168:171], v[120:123]
	v_mfma_f32_16x16x32_bf16 v[116:119], v[160:163], v[168:171], v[116:119]
	v_mfma_f32_16x16x32_bf16 v[104:107], v[152:155], v[176:179], v[104:107]
	v_mfma_f32_16x16x32_bf16 v[100:103], v[160:163], v[176:179], v[100:103]
	v_mfma_f32_16x16x32_bf16 v[88:91], v[152:155], v[184:187], v[88:91]
	v_mfma_f32_16x16x32_bf16 v[84:87], v[160:163], v[184:187], v[84:87]
	v_mfma_f32_16x16x32_bf16 v[76:79], v[152:155], v[192:195], v[76:79]
	v_mfma_f32_16x16x32_bf16 v[72:75], v[160:163], v[192:195], v[72:75]
	v_mfma_f32_16x16x32_bf16 v[128:131], v[132:135], v[164:167], v[128:131]
	v_mfma_f32_16x16x32_bf16 v[124:127], v[140:143], v[164:167], v[124:127]
	v_mfma_f32_16x16x32_bf16 v[112:115], v[132:135], v[172:175], v[112:115]
	v_mfma_f32_16x16x32_bf16 v[108:111], v[140:143], v[172:175], v[108:111]
	v_mfma_f32_16x16x32_bf16 v[96:99], v[132:135], v[180:183], v[96:99]
	v_mfma_f32_16x16x32_bf16 v[92:95], v[140:143], v[180:183], v[92:95]
	v_mfma_f32_16x16x32_bf16 v[80:83], v[132:135], v[188:191], v[80:83]
	v_mfma_f32_16x16x32_bf16 v[68:71], v[140:143], v[188:191], v[68:71]
	v_mfma_f32_16x16x32_bf16 v[128:131], v[136:139], v[168:171], v[128:131]
	v_mfma_f32_16x16x32_bf16 v[124:127], v[144:147], v[168:171], v[124:127]
	v_mfma_f32_16x16x32_bf16 v[112:115], v[136:139], v[176:179], v[112:115]
	v_mfma_f32_16x16x32_bf16 v[108:111], v[144:147], v[176:179], v[108:111]
	v_mfma_f32_16x16x32_bf16 v[96:99], v[136:139], v[184:187], v[96:99]
	v_mfma_f32_16x16x32_bf16 v[92:95], v[144:147], v[184:187], v[92:95]
	v_mfma_f32_16x16x32_bf16 v[80:83], v[136:139], v[192:195], v[80:83]
	v_mfma_f32_16x16x32_bf16 v[68:71], v[144:147], v[192:195], v[68:71]
	s_setprio 0
	s_barrier
	s_add_i32 s58, s78, s48
	v_lshl_add_u64 v[2:3], v[2:3], 0, s[16:17]
	s_mov_b32 m0, s58
	ds_read_b128 v[188:191], v224 offset:49152
	ds_read_b128 v[192:195], v224 offset:50176
	ds_read_b128 v[180:183], v224 offset:51200
	ds_read_b128 v[184:187], v224 offset:52224
	ds_read_b128 v[172:175], v224 offset:53248
	ds_read_b128 v[176:179], v224 offset:54272
	ds_read_b128 v[164:167], v224 offset:55296
	ds_read_b128 v[168:171], v224 offset:56320
	global_load_lds_dwordx4 v[2:3], off
	s_add_i32 m0, s58, 0x2000
	s_add_u32 s56, s56, 0x80080
	v_lshl_add_u64 v[2:3], v[212:213], 0, s[16:17]
	s_addc_u32 s57, s57, 0
	s_add_i32 s58, s79, s48
	global_load_lds_dwordx4 v[2:3], off
	v_lshl_add_u64 v[2:3], s[56:57], 0, v[198:199]
	s_mov_b32 m0, s58
	s_and_b64 vcc, exec, s[10:11]
	global_load_lds_dwordx4 v[2:3], off
	v_lshl_add_u64 v[2:3], s[56:57], 0, v[202:203]
	s_add_i32 m0, s58, 0x2000
	s_nop 0
	global_load_lds_dwordx4 v[2:3], off
	v_lshl_add_u64 v[2:3], v[214:215], 0, s[16:17]
	s_mov_b32 m0, s63
	s_nop 0
	global_load_lds_dwordx4 v[2:3], off
	v_lshl_add_u64 v[2:3], v[216:217], 0, s[16:17]
	s_mov_b32 m0, s64
	s_nop 0
	global_load_lds_dwordx4 v[2:3], off
	s_waitcnt vmcnt(8)
	s_waitcnt lgkmcnt(0)
	s_barrier
	s_cbranch_vccnz .LBB0_434
	s_setprio 1
	v_mfma_f32_16x16x32_bf16 v[56:59], v[148:151], v[188:191], v[56:59]
	v_mfma_f32_16x16x32_bf16 v[52:55], v[156:159], v[188:191], v[52:55]
	v_mfma_f32_16x16x32_bf16 v[40:43], v[148:151], v[180:183], v[40:43]
	v_mfma_f32_16x16x32_bf16 v[36:39], v[156:159], v[180:183], v[36:39]
	v_mfma_f32_16x16x32_bf16 v[24:27], v[148:151], v[172:175], v[24:27]
	v_mfma_f32_16x16x32_bf16 v[20:23], v[156:159], v[172:175], v[20:23]
	v_mfma_f32_16x16x32_bf16 v[8:11], v[148:151], v[164:167], v[8:11]
	v_mfma_f32_16x16x32_bf16 v[2:5], v[156:159], v[164:167], v[4:7]
	v_mfma_f32_16x16x32_bf16 v[56:59], v[152:155], v[192:195], v[56:59]
	v_mfma_f32_16x16x32_bf16 v[52:55], v[160:163], v[192:195], v[52:55]
	v_mfma_f32_16x16x32_bf16 v[40:43], v[152:155], v[184:187], v[40:43]
	v_mfma_f32_16x16x32_bf16 v[36:39], v[160:163], v[184:187], v[36:39]
	v_mfma_f32_16x16x32_bf16 v[24:27], v[152:155], v[176:179], v[24:27]
	v_mfma_f32_16x16x32_bf16 v[20:23], v[160:163], v[176:179], v[20:23]
	v_mfma_f32_16x16x32_bf16 v[8:11], v[152:155], v[168:171], v[8:11]
	v_mfma_f32_16x16x32_bf16 v[4:7], v[160:163], v[168:171], v[2:5]
	v_mfma_f32_16x16x32_bf16 v[64:67], v[132:135], v[188:191], v[64:67]
	v_mfma_f32_16x16x32_bf16 v[60:63], v[140:143], v[188:191], v[60:63]
	v_mfma_f32_16x16x32_bf16 v[48:51], v[132:135], v[180:183], v[48:51]
	v_mfma_f32_16x16x32_bf16 v[44:47], v[140:143], v[180:183], v[44:47]
	v_mfma_f32_16x16x32_bf16 v[32:35], v[132:135], v[172:175], v[32:35]
	v_mfma_f32_16x16x32_bf16 v[28:31], v[140:143], v[172:175], v[28:31]
	v_mfma_f32_16x16x32_bf16 v[16:19], v[132:135], v[164:167], v[16:19]
	v_mfma_f32_16x16x32_bf16 v[12:15], v[140:143], v[164:167], v[12:15]
	v_mfma_f32_16x16x32_bf16 v[64:67], v[136:139], v[192:195], v[64:67]
	v_mfma_f32_16x16x32_bf16 v[60:63], v[144:147], v[192:195], v[60:63]
	v_mfma_f32_16x16x32_bf16 v[48:51], v[136:139], v[184:187], v[48:51]
	v_mfma_f32_16x16x32_bf16 v[44:47], v[144:147], v[184:187], v[44:47]
	v_mfma_f32_16x16x32_bf16 v[32:35], v[136:139], v[176:179], v[32:35]
	v_mfma_f32_16x16x32_bf16 v[28:31], v[144:147], v[176:179], v[28:31]
	v_mfma_f32_16x16x32_bf16 v[16:19], v[136:139], v[168:171], v[16:19]
	v_mfma_f32_16x16x32_bf16 v[12:15], v[144:147], v[168:171], v[12:15]
	s_setprio 0
	s_branch .LBB0_434

.LBB0_523:
	ds_read_b128 v[144:147], v151
	ds_read_b128 v[156:159], v151 offset:1024
	ds_read_b128 v[160:163], v151 offset:2048
	ds_read_b128 v[164:167], v151 offset:3072
	ds_read_b128 v[168:171], v152
	ds_read_b128 v[172:175], v152 offset:1024
	ds_read_b128 v[176:179], v152 offset:2048
	ds_read_b128 v[180:183], v152 offset:3072
	s_add_u32 s36, s34, 0x100
	s_addc_u32 s37, s35, 0
	s_cmpk_eq_i32 s66, 0x54
	s_cselect_b32 s55, s13, s37
	s_cselect_b32 s54, s12, s36
	s_cselect_b32 s53, s31, s47
	s_cselect_b32 s52, s30, s46
	v_lshl_add_u64 v[216:217], s[34:35], 0, v[138:139]
	s_add_i32 m0, s49, 0xc000
	ds_read_b128 v[184:187], v153
	ds_read_b128 v[188:191], v153 offset:1024
	ds_read_b128 v[192:195], v153 offset:2048
	ds_read_b128 v[196:199], v153 offset:3072
	ds_read_b128 v[200:203], v153 offset:4096
	ds_read_b128 v[204:207], v153 offset:5120
	ds_read_b128 v[208:211], v153 offset:6144
	ds_read_b128 v[212:215], v153 offset:7168
	global_load_lds_dwordx4 v[216:217], off
	v_lshl_add_u64 v[216:217], s[34:35], 0, v[136:137]
	s_add_i32 m0, s49, 0xe000
	s_nop 0
	global_load_lds_dwordx4 v[216:217], off
	s_waitcnt vmcnt(8)
	s_waitcnt lgkmcnt(0)
	s_barrier
	s_setprio 1
	v_mfma_f32_16x16x32_bf16 v[124:127], v[144:147], v[184:187], v[124:127]
	v_mfma_f32_16x16x32_bf16 v[120:123], v[160:163], v[184:187], v[120:123]
	v_mfma_f32_16x16x32_bf16 v[108:111], v[144:147], v[192:195], v[108:111]
	v_mfma_f32_16x16x32_bf16 v[104:107], v[160:163], v[192:195], v[104:107]
	v_mfma_f32_16x16x32_bf16 v[92:95], v[144:147], v[200:203], v[92:95]
	v_mfma_f32_16x16x32_bf16 v[88:91], v[160:163], v[200:203], v[88:91]
	v_mfma_f32_16x16x32_bf16 v[76:79], v[144:147], v[208:211], v[76:79]
	v_mfma_f32_16x16x32_bf16 v[72:75], v[160:163], v[208:211], v[72:75]
	v_mfma_f32_16x16x32_bf16 v[124:127], v[156:159], v[188:191], v[124:127]
	v_mfma_f32_16x16x32_bf16 v[120:123], v[164:167], v[188:191], v[120:123]
	v_mfma_f32_16x16x32_bf16 v[108:111], v[156:159], v[196:199], v[108:111]
	v_mfma_f32_16x16x32_bf16 v[104:107], v[164:167], v[196:199], v[104:107]
	v_mfma_f32_16x16x32_bf16 v[92:95], v[156:159], v[204:207], v[92:95]
	v_mfma_f32_16x16x32_bf16 v[88:91], v[164:167], v[204:207], v[88:91]
	v_mfma_f32_16x16x32_bf16 v[76:79], v[156:159], v[212:215], v[76:79]
	v_mfma_f32_16x16x32_bf16 v[72:75], v[164:167], v[212:215], v[72:75]
	v_mfma_f32_16x16x32_bf16 v[116:119], v[168:171], v[184:187], v[116:119]
	v_mfma_f32_16x16x32_bf16 v[112:115], v[176:179], v[184:187], v[112:115]
	v_mfma_f32_16x16x32_bf16 v[100:103], v[168:171], v[192:195], v[100:103]
	v_mfma_f32_16x16x32_bf16 v[96:99], v[176:179], v[192:195], v[96:99]
	v_mfma_f32_16x16x32_bf16 v[84:87], v[168:171], v[200:203], v[84:87]
	v_mfma_f32_16x16x32_bf16 v[80:83], v[176:179], v[200:203], v[80:83]
	v_mfma_f32_16x16x32_bf16 v[68:71], v[168:171], v[208:211], v[68:71]
	v_mfma_f32_16x16x32_bf16 v[64:67], v[176:179], v[208:211], v[64:67]
	v_mfma_f32_16x16x32_bf16 v[116:119], v[172:175], v[188:191], v[116:119]
	v_mfma_f32_16x16x32_bf16 v[112:115], v[180:183], v[188:191], v[112:115]
	v_mfma_f32_16x16x32_bf16 v[100:103], v[172:175], v[196:199], v[100:103]
	v_mfma_f32_16x16x32_bf16 v[96:99], v[180:183], v[196:199], v[96:99]
	v_mfma_f32_16x16x32_bf16 v[84:87], v[172:175], v[204:207], v[84:87]
	v_mfma_f32_16x16x32_bf16 v[80:83], v[180:183], v[204:207], v[80:83]
	v_mfma_f32_16x16x32_bf16 v[68:71], v[172:175], v[212:215], v[68:71]
	v_mfma_f32_16x16x32_bf16 v[64:67], v[180:183], v[212:215], v[64:67]
	s_setprio 0
	s_barrier
	s_add_i32 s34, s62, s48
	v_lshl_add_u64 v[216:217], s[52:53], 0, v[130:131]
	s_mov_b32 m0, s34
	ds_read_b128 v[184:187], v153 offset:16384
	ds_read_b128 v[188:191], v153 offset:17408
	ds_read_b128 v[192:195], v153 offset:18432
	ds_read_b128 v[196:199], v153 offset:19456
	ds_read_b128 v[200:203], v153 offset:20480
	ds_read_b128 v[204:207], v153 offset:21504
	ds_read_b128 v[208:211], v153 offset:22528
	ds_read_b128 v[212:215], v153 offset:23552
	global_load_lds_dwordx4 v[216:217], off
	s_add_i32 m0, s34, 0x2000
	s_add_u32 s34, s52, 0x160000
	v_lshl_add_u64 v[218:219], s[52:53], 0, v[134:135]
	s_addc_u32 s35, s53, 0
	s_add_i32 s67, s63, s48
	global_load_lds_dwordx4 v[218:219], off
	v_lshl_add_u64 v[220:221], s[34:35], 0, v[130:131]
	s_mov_b32 m0, s67
	v_lshl_add_u64 v[222:223], s[54:55], 0, v[132:133]
	global_load_lds_dwordx4 v[220:221], off
	v_lshl_add_u64 v[220:221], s[34:35], 0, v[134:135]
	s_add_i32 m0, s67, 0x2000
	s_nop 0
	global_load_lds_dwordx4 v[220:221], off
	v_lshl_add_u64 v[220:221], s[54:55], 0, v[128:129]
	s_mov_b32 m0, s49
	s_nop 0
	global_load_lds_dwordx4 v[220:221], off
	s_mov_b32 m0, s56
	s_nop 0
	global_load_lds_dwordx4 v[222:223], off
	s_waitcnt vmcnt(8)
	s_waitcnt lgkmcnt(0)
	s_barrier
	s_setprio 1
	v_mfma_f32_16x16x32_bf16 v[60:63], v[144:147], v[184:187], v[60:63]
	v_mfma_f32_16x16x32_bf16 v[56:59], v[160:163], v[184:187], v[56:59]
	v_mfma_f32_16x16x32_bf16 v[44:47], v[144:147], v[192:195], v[44:47]
	v_mfma_f32_16x16x32_bf16 v[40:43], v[160:163], v[192:195], v[40:43]
	v_mfma_f32_16x16x32_bf16 v[28:31], v[144:147], v[200:203], v[28:31]
	v_mfma_f32_16x16x32_bf16 v[24:27], v[160:163], v[200:203], v[24:27]
	v_mfma_f32_16x16x32_bf16 v[12:15], v[144:147], v[208:211], v[12:15]
	v_mfma_f32_16x16x32_bf16 v[8:11], v[160:163], v[208:211], v[8:11]
	v_mfma_f32_16x16x32_bf16 v[60:63], v[156:159], v[188:191], v[60:63]
	v_mfma_f32_16x16x32_bf16 v[56:59], v[164:167], v[188:191], v[56:59]
	v_mfma_f32_16x16x32_bf16 v[44:47], v[156:159], v[196:199], v[44:47]
	v_mfma_f32_16x16x32_bf16 v[40:43], v[164:167], v[196:199], v[40:43]
	v_mfma_f32_16x16x32_bf16 v[28:31], v[156:159], v[204:207], v[28:31]
	v_mfma_f32_16x16x32_bf16 v[24:27], v[164:167], v[204:207], v[24:27]
	v_mfma_f32_16x16x32_bf16 v[12:15], v[156:159], v[212:215], v[12:15]
	v_mfma_f32_16x16x32_bf16 v[8:11], v[164:167], v[212:215], v[8:11]
	v_mfma_f32_16x16x32_bf16 v[52:55], v[168:171], v[184:187], v[52:55]
	v_mfma_f32_16x16x32_bf16 v[48:51], v[176:179], v[184:187], v[48:51]
	v_mfma_f32_16x16x32_bf16 v[36:39], v[168:171], v[192:195], v[36:39]
	v_mfma_f32_16x16x32_bf16 v[32:35], v[176:179], v[192:195], v[32:35]
	v_mfma_f32_16x16x32_bf16 v[20:23], v[168:171], v[200:203], v[20:23]
	v_mfma_f32_16x16x32_bf16 v[16:19], v[176:179], v[200:203], v[16:19]
	v_mfma_f32_16x16x32_bf16 v[4:7], v[168:171], v[208:211], v[4:7]
	v_mfma_f32_16x16x32_bf16 v[0:3], v[176:179], v[208:211], v[0:3]
	v_mfma_f32_16x16x32_bf16 v[52:55], v[172:175], v[188:191], v[52:55]
	v_mfma_f32_16x16x32_bf16 v[48:51], v[180:183], v[188:191], v[48:51]
	v_mfma_f32_16x16x32_bf16 v[36:39], v[172:175], v[196:199], v[36:39]
	v_mfma_f32_16x16x32_bf16 v[32:35], v[180:183], v[196:199], v[32:35]
	v_mfma_f32_16x16x32_bf16 v[20:23], v[172:175], v[204:207], v[20:23]
	v_mfma_f32_16x16x32_bf16 v[16:19], v[180:183], v[204:207], v[16:19]
	v_mfma_f32_16x16x32_bf16 v[4:7], v[172:175], v[212:215], v[4:7]
	v_mfma_f32_16x16x32_bf16 v[0:3], v[180:183], v[212:215], v[0:3]
	s_setprio 0
	s_barrier
	s_add_i32 s67, 0, 0x18000
	v_add_u32_e32 v155, s67, v149
	s_add_i32 s70, 0, 0x1c000
	ds_read_b128 v[144:147], v155
	ds_read_b128 v[156:159], v155 offset:1024
	ds_read_b128 v[160:163], v155 offset:2048
	ds_read_b128 v[164:167], v155 offset:3072
	v_add_u32_e32 v155, s70, v149
	ds_read_b128 v[168:171], v155
	ds_read_b128 v[172:175], v155 offset:1024
	ds_read_b128 v[176:179], v155 offset:2048
	ds_read_b128 v[180:183], v155 offset:3072
	s_add_u32 s34, s54, 0x160000
	s_addc_u32 s35, s55, 0
	s_mov_b32 m0, s57
	v_lshl_add_u64 v[224:225], s[34:35], 0, v[128:129]
	ds_read_b128 v[184:187], v153 offset:32768
	ds_read_b128 v[188:191], v153 offset:33792
	ds_read_b128 v[192:195], v153 offset:34816
	ds_read_b128 v[196:199], v153 offset:35840
	ds_read_b128 v[200:203], v153 offset:36864
	ds_read_b128 v[204:207], v153 offset:37888
	ds_read_b128 v[208:211], v153 offset:38912
	ds_read_b128 v[212:215], v153 offset:39936
	global_load_lds_dwordx4 v[224:225], off
	v_lshl_add_u64 v[224:225], s[34:35], 0, v[132:133]
	s_mov_b32 m0, s58
	s_nop 0
	global_load_lds_dwordx4 v[224:225], off
	s_waitcnt vmcnt(8)
	s_waitcnt lgkmcnt(0)
	s_barrier
	s_setprio 1
	v_mfma_f32_16x16x32_bf16 v[124:127], v[144:147], v[184:187], v[124:127]
	v_mfma_f32_16x16x32_bf16 v[120:123], v[160:163], v[184:187], v[120:123]
	v_mfma_f32_16x16x32_bf16 v[108:111], v[144:147], v[192:195], v[108:111]
	v_mfma_f32_16x16x32_bf16 v[104:107], v[160:163], v[192:195], v[104:107]
	v_mfma_f32_16x16x32_bf16 v[92:95], v[144:147], v[200:203], v[92:95]
	v_mfma_f32_16x16x32_bf16 v[88:91], v[160:163], v[200:203], v[88:91]
	v_mfma_f32_16x16x32_bf16 v[76:79], v[144:147], v[208:211], v[76:79]
	v_mfma_f32_16x16x32_bf16 v[72:75], v[160:163], v[208:211], v[72:75]
	v_mfma_f32_16x16x32_bf16 v[124:127], v[156:159], v[188:191], v[124:127]
	v_mfma_f32_16x16x32_bf16 v[120:123], v[164:167], v[188:191], v[120:123]
	v_mfma_f32_16x16x32_bf16 v[108:111], v[156:159], v[196:199], v[108:111]
	v_mfma_f32_16x16x32_bf16 v[104:107], v[164:167], v[196:199], v[104:107]
	v_mfma_f32_16x16x32_bf16 v[92:95], v[156:159], v[204:207], v[92:95]
	v_mfma_f32_16x16x32_bf16 v[88:91], v[164:167], v[204:207], v[88:91]
	v_mfma_f32_16x16x32_bf16 v[76:79], v[156:159], v[212:215], v[76:79]
	v_mfma_f32_16x16x32_bf16 v[72:75], v[164:167], v[212:215], v[72:75]
	v_mfma_f32_16x16x32_bf16 v[116:119], v[168:171], v[184:187], v[116:119]
	v_mfma_f32_16x16x32_bf16 v[112:115], v[176:179], v[184:187], v[112:115]
	v_mfma_f32_16x16x32_bf16 v[100:103], v[168:171], v[192:195], v[100:103]
	v_mfma_f32_16x16x32_bf16 v[96:99], v[176:179], v[192:195], v[96:99]
	v_mfma_f32_16x16x32_bf16 v[84:87], v[168:171], v[200:203], v[84:87]
	v_mfma_f32_16x16x32_bf16 v[80:83], v[176:179], v[200:203], v[80:83]
	v_mfma_f32_16x16x32_bf16 v[68:71], v[168:171], v[208:211], v[68:71]
	v_mfma_f32_16x16x32_bf16 v[64:67], v[176:179], v[208:211], v[64:67]
	v_mfma_f32_16x16x32_bf16 v[116:119], v[172:175], v[188:191], v[116:119]
	v_mfma_f32_16x16x32_bf16 v[112:115], v[180:183], v[188:191], v[112:115]
	v_mfma_f32_16x16x32_bf16 v[100:103], v[172:175], v[196:199], v[100:103]
	v_mfma_f32_16x16x32_bf16 v[96:99], v[180:183], v[196:199], v[96:99]
	v_mfma_f32_16x16x32_bf16 v[84:87], v[172:175], v[204:207], v[84:87]
	v_mfma_f32_16x16x32_bf16 v[80:83], v[180:183], v[204:207], v[80:83]
	v_mfma_f32_16x16x32_bf16 v[68:71], v[172:175], v[212:215], v[68:71]
	v_mfma_f32_16x16x32_bf16 v[64:67], v[180:183], v[212:215], v[64:67]
	s_setprio 0
	s_barrier
	s_add_i32 s34, s67, s48
	v_lshl_add_u64 v[216:217], v[216:217], 0, s[24:25]
	s_mov_b32 m0, s34
	ds_read_b128 v[184:187], v153 offset:49152
	ds_read_b128 v[188:191], v153 offset:50176
	ds_read_b128 v[192:195], v153 offset:51200
	ds_read_b128 v[196:199], v153 offset:52224
	ds_read_b128 v[200:203], v153 offset:53248
	ds_read_b128 v[204:207], v153 offset:54272
	ds_read_b128 v[208:211], v153 offset:55296
	ds_read_b128 v[212:215], v153 offset:56320
	global_load_lds_dwordx4 v[216:217], off
	s_add_i32 m0, s34, 0x2000
	s_add_u32 s34, s52, 0x160080
	v_lshl_add_u64 v[216:217], v[218:219], 0, s[24:25]
	s_addc_u32 s35, s53, 0
	s_add_i32 s52, s70, s48
	global_load_lds_dwordx4 v[216:217], off
	v_lshl_add_u64 v[216:217], s[34:35], 0, v[130:131]
	s_mov_b32 m0, s52
	s_nop 0
	global_load_lds_dwordx4 v[216:217], off
	v_lshl_add_u64 v[216:217], s[34:35], 0, v[134:135]
	s_add_i32 m0, s52, 0x2000
	s_nop 0
	global_load_lds_dwordx4 v[216:217], off
	v_lshl_add_u64 v[216:217], v[220:221], 0, s[24:25]
	s_mov_b32 m0, s60
	s_nop 0
	global_load_lds_dwordx4 v[216:217], off
	v_lshl_add_u64 v[216:217], v[222:223], 0, s[24:25]
	s_mov_b32 m0, s61
	s_nop 0
	global_load_lds_dwordx4 v[216:217], off
	s_waitcnt vmcnt(8)
	s_waitcnt lgkmcnt(0)
	s_barrier
	s_setprio 1
	v_mfma_f32_16x16x32_bf16 v[60:63], v[144:147], v[184:187], v[60:63]
	v_mfma_f32_16x16x32_bf16 v[56:59], v[160:163], v[184:187], v[56:59]
	v_mfma_f32_16x16x32_bf16 v[44:47], v[144:147], v[192:195], v[44:47]
	v_mfma_f32_16x16x32_bf16 v[40:43], v[160:163], v[192:195], v[40:43]
	v_mfma_f32_16x16x32_bf16 v[28:31], v[144:147], v[200:203], v[28:31]
	v_mfma_f32_16x16x32_bf16 v[24:27], v[160:163], v[200:203], v[24:27]
	v_mfma_f32_16x16x32_bf16 v[12:15], v[144:147], v[208:211], v[12:15]
	v_mfma_f32_16x16x32_bf16 v[8:11], v[160:163], v[208:211], v[8:11]
	v_mfma_f32_16x16x32_bf16 v[60:63], v[156:159], v[188:191], v[60:63]
	v_mfma_f32_16x16x32_bf16 v[56:59], v[164:167], v[188:191], v[56:59]
	v_mfma_f32_16x16x32_bf16 v[44:47], v[156:159], v[196:199], v[44:47]
	v_mfma_f32_16x16x32_bf16 v[40:43], v[164:167], v[196:199], v[40:43]
	v_mfma_f32_16x16x32_bf16 v[28:31], v[156:159], v[204:207], v[28:31]
	v_mfma_f32_16x16x32_bf16 v[24:27], v[164:167], v[204:207], v[24:27]
	v_mfma_f32_16x16x32_bf16 v[12:15], v[156:159], v[212:215], v[12:15]
	v_mfma_f32_16x16x32_bf16 v[8:11], v[164:167], v[212:215], v[8:11]
	v_mfma_f32_16x16x32_bf16 v[52:55], v[168:171], v[184:187], v[52:55]
	v_mfma_f32_16x16x32_bf16 v[48:51], v[176:179], v[184:187], v[48:51]
	v_mfma_f32_16x16x32_bf16 v[36:39], v[168:171], v[192:195], v[36:39]
	v_mfma_f32_16x16x32_bf16 v[32:35], v[176:179], v[192:195], v[32:35]
	v_mfma_f32_16x16x32_bf16 v[20:23], v[168:171], v[200:203], v[20:23]
	v_mfma_f32_16x16x32_bf16 v[16:19], v[176:179], v[200:203], v[16:19]
	v_mfma_f32_16x16x32_bf16 v[4:7], v[168:171], v[208:211], v[4:7]
	v_mfma_f32_16x16x32_bf16 v[0:3], v[176:179], v[208:211], v[0:3]
	v_mfma_f32_16x16x32_bf16 v[52:55], v[172:175], v[188:191], v[52:55]
	v_mfma_f32_16x16x32_bf16 v[48:51], v[180:183], v[188:191], v[48:51]
	v_mfma_f32_16x16x32_bf16 v[36:39], v[172:175], v[196:199], v[36:39]
	v_mfma_f32_16x16x32_bf16 v[32:35], v[180:183], v[196:199], v[32:35]
	v_mfma_f32_16x16x32_bf16 v[20:23], v[172:175], v[204:207], v[20:23]
	v_mfma_f32_16x16x32_bf16 v[16:19], v[180:183], v[204:207], v[16:19]
	v_mfma_f32_16x16x32_bf16 v[4:7], v[172:175], v[212:215], v[4:7]
	v_mfma_f32_16x16x32_bf16 v[0:3], v[180:183], v[212:215], v[0:3]
	s_setprio 0
	s_barrier
	s_add_i32 s66, s66, 2
	s_add_u32 s46, s46, 0x100
	s_addc_u32 s47, s47, 0
	s_cmpk_gt_u32 s66, 0x55
	s_mov_b64 s[34:35], s[36:37]
	s_cbranch_scc0 .LBB0_523
	s_and_b64 vcc, exec, s[26:27]
	s_cbranch_vccz .LBB0_526
	s_barrier

.LBB0_617:
	ds_read_b128 v[146:149], v159
	ds_read_b128 v[150:153], v159 offset:1024
	ds_read_b128 v[164:167], v159 offset:2048
	ds_read_b128 v[168:171], v159 offset:3072
	ds_read_b128 v[172:175], v160
	ds_read_b128 v[176:179], v160 offset:1024
	ds_read_b128 v[180:183], v160 offset:2048
	ds_read_b128 v[184:187], v160 offset:3072
	s_add_u32 s58, s56, 0xfff80080
	s_addc_u32 s59, s57, -1
	s_cmp_eq_u32 s55, 28
	s_cselect_b32 s61, s35, s59
	s_cselect_b32 s60, s46, s58
	s_cselect_b32 s59, s31, s51
	s_cselect_b32 s58, s47, s50
	v_lshl_add_u64 v[154:155], s[56:57], 0, v[140:141]
	s_add_i32 m0, s45, 0xc000
	ds_read_b128 v[188:191], v161
	ds_read_b128 v[192:195], v161 offset:1024
	ds_read_b128 v[196:199], v161 offset:2048
	ds_read_b128 v[200:203], v161 offset:3072
	ds_read_b128 v[204:207], v161 offset:4096
	ds_read_b128 v[208:211], v161 offset:5120
	ds_read_b128 v[212:215], v161 offset:6144
	ds_read_b128 v[216:219], v161 offset:7168
	global_load_lds_dwordx4 v[154:155], off
	v_lshl_add_u64 v[154:155], s[56:57], 0, v[138:139]
	s_add_i32 m0, s45, 0xe000
	s_nop 0
	global_load_lds_dwordx4 v[154:155], off
	s_waitcnt vmcnt(8)
	s_waitcnt lgkmcnt(0)
	s_barrier
	s_setprio 1
	v_mfma_f32_16x16x32_bf16 v[124:127], v[146:149], v[188:191], v[124:127]
	v_mfma_f32_16x16x32_bf16 v[120:123], v[164:167], v[188:191], v[120:123]
	v_mfma_f32_16x16x32_bf16 v[108:111], v[146:149], v[196:199], v[108:111]
	v_mfma_f32_16x16x32_bf16 v[104:107], v[164:167], v[196:199], v[104:107]
	v_mfma_f32_16x16x32_bf16 v[92:95], v[146:149], v[204:207], v[92:95]
	v_mfma_f32_16x16x32_bf16 v[88:91], v[164:167], v[204:207], v[88:91]
	v_mfma_f32_16x16x32_bf16 v[76:79], v[146:149], v[212:215], v[76:79]
	v_mfma_f32_16x16x32_bf16 v[72:75], v[164:167], v[212:215], v[72:75]
	v_mfma_f32_16x16x32_bf16 v[124:127], v[150:153], v[192:195], v[124:127]
	v_mfma_f32_16x16x32_bf16 v[120:123], v[168:171], v[192:195], v[120:123]
	v_mfma_f32_16x16x32_bf16 v[108:111], v[150:153], v[200:203], v[108:111]
	v_mfma_f32_16x16x32_bf16 v[104:107], v[168:171], v[200:203], v[104:107]
	v_mfma_f32_16x16x32_bf16 v[92:95], v[150:153], v[208:211], v[92:95]
	v_mfma_f32_16x16x32_bf16 v[88:91], v[168:171], v[208:211], v[88:91]
	v_mfma_f32_16x16x32_bf16 v[76:79], v[150:153], v[216:219], v[76:79]
	v_mfma_f32_16x16x32_bf16 v[72:75], v[168:171], v[216:219], v[72:75]
	v_mfma_f32_16x16x32_bf16 v[116:119], v[172:175], v[188:191], v[116:119]
	v_mfma_f32_16x16x32_bf16 v[112:115], v[180:183], v[188:191], v[112:115]
	v_mfma_f32_16x16x32_bf16 v[100:103], v[172:175], v[196:199], v[100:103]
	v_mfma_f32_16x16x32_bf16 v[96:99], v[180:183], v[196:199], v[96:99]
	v_mfma_f32_16x16x32_bf16 v[84:87], v[172:175], v[204:207], v[84:87]
	v_mfma_f32_16x16x32_bf16 v[80:83], v[180:183], v[204:207], v[80:83]
	v_mfma_f32_16x16x32_bf16 v[68:71], v[172:175], v[212:215], v[68:71]
	v_mfma_f32_16x16x32_bf16 v[64:67], v[180:183], v[212:215], v[64:67]
	v_mfma_f32_16x16x32_bf16 v[116:119], v[176:179], v[192:195], v[116:119]
	v_mfma_f32_16x16x32_bf16 v[112:115], v[184:187], v[192:195], v[112:115]
	v_mfma_f32_16x16x32_bf16 v[100:103], v[176:179], v[200:203], v[100:103]
	v_mfma_f32_16x16x32_bf16 v[96:99], v[184:187], v[200:203], v[96:99]
	v_mfma_f32_16x16x32_bf16 v[84:87], v[176:179], v[208:211], v[84:87]
	v_mfma_f32_16x16x32_bf16 v[80:83], v[184:187], v[208:211], v[80:83]
	v_mfma_f32_16x16x32_bf16 v[68:71], v[176:179], v[216:219], v[68:71]
	v_mfma_f32_16x16x32_bf16 v[64:67], v[184:187], v[216:219], v[64:67]
	s_setprio 0
	s_barrier
	s_add_i32 s72, s66, s44
	v_lshl_add_u64 v[154:155], s[58:59], 0, v[130:131]
	s_mov_b32 m0, s72
	ds_read_b128 v[188:191], v161 offset:16384
	ds_read_b128 v[192:195], v161 offset:17408
	ds_read_b128 v[196:199], v161 offset:18432
	ds_read_b128 v[200:203], v161 offset:19456
	ds_read_b128 v[204:207], v161 offset:20480
	ds_read_b128 v[208:211], v161 offset:21504
	ds_read_b128 v[212:215], v161 offset:22528
	ds_read_b128 v[216:219], v161 offset:23552
	global_load_lds_dwordx4 v[154:155], off
	s_add_i32 m0, s72, 0x2000
	s_add_u32 s80, s58, 0x80000
	v_lshl_add_u64 v[220:221], s[58:59], 0, v[134:135]
	s_addc_u32 s81, s59, 0
	s_add_i32 s72, s67, s44
	global_load_lds_dwordx4 v[220:221], off
	v_lshl_add_u64 v[222:223], s[80:81], 0, v[130:131]
	s_mov_b32 m0, s72
	v_lshl_add_u64 v[224:225], s[60:61], 0, v[132:133]
	global_load_lds_dwordx4 v[222:223], off
	v_lshl_add_u64 v[222:223], s[80:81], 0, v[134:135]
	s_add_i32 m0, s72, 0x2000
	s_nop 0
	global_load_lds_dwordx4 v[222:223], off
	v_lshl_add_u64 v[222:223], s[60:61], 0, v[128:129]
	s_mov_b32 m0, s45
	s_nop 0
	global_load_lds_dwordx4 v[222:223], off
	s_mov_b32 m0, s48
	s_nop 0
	global_load_lds_dwordx4 v[224:225], off
	s_waitcnt vmcnt(8)
	s_waitcnt lgkmcnt(0)
	s_barrier
	s_setprio 1
	v_mfma_f32_16x16x32_bf16 v[60:63], v[146:149], v[188:191], v[60:63]
	v_mfma_f32_16x16x32_bf16 v[56:59], v[164:167], v[188:191], v[56:59]
	v_mfma_f32_16x16x32_bf16 v[44:47], v[146:149], v[196:199], v[44:47]
	v_mfma_f32_16x16x32_bf16 v[40:43], v[164:167], v[196:199], v[40:43]
	v_mfma_f32_16x16x32_bf16 v[28:31], v[146:149], v[204:207], v[28:31]
	v_mfma_f32_16x16x32_bf16 v[24:27], v[164:167], v[204:207], v[24:27]
	v_mfma_f32_16x16x32_bf16 v[12:15], v[146:149], v[212:215], v[12:15]
	v_mfma_f32_16x16x32_bf16 v[8:11], v[164:167], v[212:215], v[8:11]
	v_mfma_f32_16x16x32_bf16 v[60:63], v[150:153], v[192:195], v[60:63]
	v_mfma_f32_16x16x32_bf16 v[56:59], v[168:171], v[192:195], v[56:59]
	v_mfma_f32_16x16x32_bf16 v[44:47], v[150:153], v[200:203], v[44:47]
	v_mfma_f32_16x16x32_bf16 v[40:43], v[168:171], v[200:203], v[40:43]
	v_mfma_f32_16x16x32_bf16 v[28:31], v[150:153], v[208:211], v[28:31]
	v_mfma_f32_16x16x32_bf16 v[24:27], v[168:171], v[208:211], v[24:27]
	v_mfma_f32_16x16x32_bf16 v[12:15], v[150:153], v[216:219], v[12:15]
	v_mfma_f32_16x16x32_bf16 v[8:11], v[168:171], v[216:219], v[8:11]
	v_mfma_f32_16x16x32_bf16 v[52:55], v[172:175], v[188:191], v[52:55]
	v_mfma_f32_16x16x32_bf16 v[48:51], v[180:183], v[188:191], v[48:51]
	v_mfma_f32_16x16x32_bf16 v[36:39], v[172:175], v[196:199], v[36:39]
	v_mfma_f32_16x16x32_bf16 v[32:35], v[180:183], v[196:199], v[32:35]
	v_mfma_f32_16x16x32_bf16 v[20:23], v[172:175], v[204:207], v[20:23]
	v_mfma_f32_16x16x32_bf16 v[16:19], v[180:183], v[204:207], v[16:19]
	v_mfma_f32_16x16x32_bf16 v[4:7], v[172:175], v[212:215], v[4:7]
	v_mfma_f32_16x16x32_bf16 v[0:3], v[180:183], v[212:215], v[0:3]
	v_mfma_f32_16x16x32_bf16 v[52:55], v[176:179], v[192:195], v[52:55]
	v_mfma_f32_16x16x32_bf16 v[48:51], v[184:187], v[192:195], v[48:51]
	v_mfma_f32_16x16x32_bf16 v[36:39], v[176:179], v[200:203], v[36:39]
	v_mfma_f32_16x16x32_bf16 v[32:35], v[184:187], v[200:203], v[32:35]
	v_mfma_f32_16x16x32_bf16 v[20:23], v[176:179], v[208:211], v[20:23]
	v_mfma_f32_16x16x32_bf16 v[16:19], v[184:187], v[208:211], v[16:19]
	v_mfma_f32_16x16x32_bf16 v[4:7], v[176:179], v[216:219], v[4:7]
	v_mfma_f32_16x16x32_bf16 v[0:3], v[184:187], v[216:219], v[0:3]
	s_setprio 0
	s_barrier
	s_add_i32 s72, 0, 0x18000
	s_add_i32 s78, 0, 0x1c000
	v_add_u32_e32 v168, s72, v157
	v_add_u32_e32 v184, s78, v157
	ds_read_b128 v[146:149], v168
	ds_read_b128 v[150:153], v168 offset:1024
	ds_read_b128 v[164:167], v168 offset:2048
	ds_read_b128 v[168:171], v168 offset:3072
	ds_read_b128 v[172:175], v184
	ds_read_b128 v[176:179], v184 offset:1024
	ds_read_b128 v[180:183], v184 offset:2048
	ds_read_b128 v[184:187], v184 offset:3072
	s_add_u32 s60, s60, 0x80000
	s_addc_u32 s61, s61, 0
	s_mov_b32 m0, s49
	v_lshl_add_u64 v[226:227], s[60:61], 0, v[128:129]
	ds_read_b128 v[188:191], v161 offset:32768
	ds_read_b128 v[192:195], v161 offset:33792
	ds_read_b128 v[196:199], v161 offset:34816
	ds_read_b128 v[200:203], v161 offset:35840
	ds_read_b128 v[204:207], v161 offset:36864
	ds_read_b128 v[208:211], v161 offset:37888
	ds_read_b128 v[212:215], v161 offset:38912
	ds_read_b128 v[216:219], v161 offset:39936
	global_load_lds_dwordx4 v[226:227], off
	v_lshl_add_u64 v[226:227], s[60:61], 0, v[132:133]
	s_mov_b32 m0, s62
	s_nop 0
	global_load_lds_dwordx4 v[226:227], off
	s_waitcnt vmcnt(8)
	s_waitcnt lgkmcnt(0)
	s_barrier
	s_setprio 1
	v_mfma_f32_16x16x32_bf16 v[124:127], v[146:149], v[188:191], v[124:127]
	v_mfma_f32_16x16x32_bf16 v[120:123], v[164:167], v[188:191], v[120:123]
	v_mfma_f32_16x16x32_bf16 v[108:111], v[146:149], v[196:199], v[108:111]
	v_mfma_f32_16x16x32_bf16 v[104:107], v[164:167], v[196:199], v[104:107]
	v_mfma_f32_16x16x32_bf16 v[92:95], v[146:149], v[204:207], v[92:95]
	v_mfma_f32_16x16x32_bf16 v[88:91], v[164:167], v[204:207], v[88:91]
	v_mfma_f32_16x16x32_bf16 v[76:79], v[146:149], v[212:215], v[76:79]
	v_mfma_f32_16x16x32_bf16 v[72:75], v[164:167], v[212:215], v[72:75]
	v_mfma_f32_16x16x32_bf16 v[124:127], v[150:153], v[192:195], v[124:127]
	v_mfma_f32_16x16x32_bf16 v[120:123], v[168:171], v[192:195], v[120:123]
	v_mfma_f32_16x16x32_bf16 v[108:111], v[150:153], v[200:203], v[108:111]
	v_mfma_f32_16x16x32_bf16 v[104:107], v[168:171], v[200:203], v[104:107]
	v_mfma_f32_16x16x32_bf16 v[92:95], v[150:153], v[208:211], v[92:95]
	v_mfma_f32_16x16x32_bf16 v[88:91], v[168:171], v[208:211], v[88:91]
	v_mfma_f32_16x16x32_bf16 v[76:79], v[150:153], v[216:219], v[76:79]
	v_mfma_f32_16x16x32_bf16 v[72:75], v[168:171], v[216:219], v[72:75]
	v_mfma_f32_16x16x32_bf16 v[116:119], v[172:175], v[188:191], v[116:119]
	v_mfma_f32_16x16x32_bf16 v[112:115], v[180:183], v[188:191], v[112:115]
	v_mfma_f32_16x16x32_bf16 v[100:103], v[172:175], v[196:199], v[100:103]
	v_mfma_f32_16x16x32_bf16 v[96:99], v[180:183], v[196:199], v[96:99]
	v_mfma_f32_16x16x32_bf16 v[84:87], v[172:175], v[204:207], v[84:87]
	v_mfma_f32_16x16x32_bf16 v[80:83], v[180:183], v[204:207], v[80:83]
	v_mfma_f32_16x16x32_bf16 v[68:71], v[172:175], v[212:215], v[68:71]
	v_mfma_f32_16x16x32_bf16 v[64:67], v[180:183], v[212:215], v[64:67]
	v_mfma_f32_16x16x32_bf16 v[116:119], v[176:179], v[192:195], v[116:119]
	v_mfma_f32_16x16x32_bf16 v[112:115], v[184:187], v[192:195], v[112:115]
	v_mfma_f32_16x16x32_bf16 v[100:103], v[176:179], v[200:203], v[100:103]
	v_mfma_f32_16x16x32_bf16 v[96:99], v[184:187], v[200:203], v[96:99]
	v_mfma_f32_16x16x32_bf16 v[84:87], v[176:179], v[208:211], v[84:87]
	v_mfma_f32_16x16x32_bf16 v[80:83], v[184:187], v[208:211], v[80:83]
	v_mfma_f32_16x16x32_bf16 v[68:71], v[176:179], v[216:219], v[68:71]
	v_mfma_f32_16x16x32_bf16 v[64:67], v[184:187], v[216:219], v[64:67]
	s_setprio 0
	s_barrier
	s_add_i32 s60, s72, s44
	v_lshl_add_u64 v[154:155], v[154:155], 0, s[24:25]
	s_mov_b32 m0, s60
	ds_read_b128 v[188:191], v161 offset:49152
	ds_read_b128 v[192:195], v161 offset:50176
	ds_read_b128 v[196:199], v161 offset:51200
	ds_read_b128 v[200:203], v161 offset:52224
	ds_read_b128 v[204:207], v161 offset:53248
	ds_read_b128 v[208:211], v161 offset:54272
	ds_read_b128 v[212:215], v161 offset:55296
	ds_read_b128 v[216:219], v161 offset:56320
	global_load_lds_dwordx4 v[154:155], off
	s_add_i32 m0, s60, 0x2000
	s_add_u32 s58, s58, 0x80080
	v_lshl_add_u64 v[154:155], v[220:221], 0, s[24:25]
	s_addc_u32 s59, s59, 0
	s_add_i32 s60, s78, s44
	global_load_lds_dwordx4 v[154:155], off
	v_lshl_add_u64 v[154:155], s[58:59], 0, v[130:131]
	s_mov_b32 m0, s60
	s_nop 0
	global_load_lds_dwordx4 v[154:155], off
	v_lshl_add_u64 v[154:155], s[58:59], 0, v[134:135]
	s_add_i32 m0, s60, 0x2000
	s_nop 0
	global_load_lds_dwordx4 v[154:155], off
	v_lshl_add_u64 v[154:155], v[222:223], 0, s[24:25]
	s_mov_b32 m0, s64
	s_nop 0
	global_load_lds_dwordx4 v[154:155], off
	v_lshl_add_u64 v[154:155], v[224:225], 0, s[24:25]
	s_mov_b32 m0, s65
	s_nop 0
	global_load_lds_dwordx4 v[154:155], off
	s_waitcnt vmcnt(8)
	s_waitcnt lgkmcnt(0)
	s_barrier
	s_setprio 1
	v_mfma_f32_16x16x32_bf16 v[60:63], v[146:149], v[188:191], v[60:63]
	v_mfma_f32_16x16x32_bf16 v[56:59], v[164:167], v[188:191], v[56:59]
	v_mfma_f32_16x16x32_bf16 v[44:47], v[146:149], v[196:199], v[44:47]
	v_mfma_f32_16x16x32_bf16 v[40:43], v[164:167], v[196:199], v[40:43]
	v_mfma_f32_16x16x32_bf16 v[28:31], v[146:149], v[204:207], v[28:31]
	v_mfma_f32_16x16x32_bf16 v[24:27], v[164:167], v[204:207], v[24:27]
	v_mfma_f32_16x16x32_bf16 v[12:15], v[146:149], v[212:215], v[12:15]
	v_mfma_f32_16x16x32_bf16 v[8:11], v[164:167], v[212:215], v[8:11]
	v_mfma_f32_16x16x32_bf16 v[60:63], v[150:153], v[192:195], v[60:63]
	v_mfma_f32_16x16x32_bf16 v[56:59], v[168:171], v[192:195], v[56:59]
	v_mfma_f32_16x16x32_bf16 v[44:47], v[150:153], v[200:203], v[44:47]
	v_mfma_f32_16x16x32_bf16 v[40:43], v[168:171], v[200:203], v[40:43]
	v_mfma_f32_16x16x32_bf16 v[28:31], v[150:153], v[208:211], v[28:31]
	v_mfma_f32_16x16x32_bf16 v[24:27], v[168:171], v[208:211], v[24:27]
	v_mfma_f32_16x16x32_bf16 v[12:15], v[150:153], v[216:219], v[12:15]
	v_mfma_f32_16x16x32_bf16 v[8:11], v[168:171], v[216:219], v[8:11]
	v_mfma_f32_16x16x32_bf16 v[52:55], v[172:175], v[188:191], v[52:55]
	v_mfma_f32_16x16x32_bf16 v[48:51], v[180:183], v[188:191], v[48:51]
	v_mfma_f32_16x16x32_bf16 v[36:39], v[172:175], v[196:199], v[36:39]
	v_mfma_f32_16x16x32_bf16 v[32:35], v[180:183], v[196:199], v[32:35]
	v_mfma_f32_16x16x32_bf16 v[20:23], v[172:175], v[204:207], v[20:23]
	v_mfma_f32_16x16x32_bf16 v[16:19], v[180:183], v[204:207], v[16:19]
	v_mfma_f32_16x16x32_bf16 v[4:7], v[172:175], v[212:215], v[4:7]
	v_mfma_f32_16x16x32_bf16 v[0:3], v[180:183], v[212:215], v[0:3]
	v_mfma_f32_16x16x32_bf16 v[52:55], v[176:179], v[192:195], v[52:55]
	v_mfma_f32_16x16x32_bf16 v[48:51], v[184:187], v[192:195], v[48:51]
	v_mfma_f32_16x16x32_bf16 v[36:39], v[176:179], v[200:203], v[36:39]
	v_mfma_f32_16x16x32_bf16 v[32:35], v[184:187], v[200:203], v[32:35]
	v_mfma_f32_16x16x32_bf16 v[20:23], v[176:179], v[208:211], v[20:23]
	v_mfma_f32_16x16x32_bf16 v[16:19], v[184:187], v[208:211], v[16:19]
	v_mfma_f32_16x16x32_bf16 v[4:7], v[176:179], v[216:219], v[4:7]
	v_mfma_f32_16x16x32_bf16 v[0:3], v[184:187], v[216:219], v[0:3]
	s_setprio 0
	s_barrier
	s_add_i32 s55, s55, 2
	s_add_u32 s50, s50, 0x100
	s_addc_u32 s51, s51, 0
	s_add_u32 s56, s56, 0x100
	s_addc_u32 s57, s57, 0
	s_cmp_gt_u32 s55, 29
	s_cbranch_scc0 .LBB0_617
	s_and_b64 vcc, exec, s[26:27]
	s_cbranch_vccz .LBB0_620
	s_barrier

.LBB0_708:
	ds_read_b128 v[0:3], v145
	ds_read_b128 v[4:7], v145 offset:1024
	ds_read_b128 v[8:11], v145 offset:2048
	ds_read_b128 v[12:15], v145 offset:3072
	ds_read_b128 v[16:19], v146
	ds_read_b128 v[20:23], v146 offset:1024
	ds_read_b128 v[24:27], v146 offset:2048
	ds_read_b128 v[28:31], v146 offset:3072
	s_ashr_i32 s37, s36, 31
	s_lshl_b64 s[52:53], s[36:37], 17
	s_add_u32 s52, s6, s52
	s_addc_u32 s53, s7, s53
	s_and_b64 s[54:55], s[8:9], exec
	s_cselect_b32 s65, s53, s59
	s_cselect_b32 s64, s52, s58
	s_ashr_i32 s35, s34, 31
	s_lshl_b64 s[54:55], s[34:35], 17
	s_add_u32 s54, s44, s54
	s_addc_u32 s55, s45, s55
	s_and_b64 s[62:63], s[8:9], exec
	s_cselect_b32 s63, s55, s61
	s_cselect_b32 s62, s54, s60
	s_add_u32 s86, s58, 0x10080
	s_addc_u32 s87, s59, 0
	s_mov_b32 m0, s72
	v_lshl_add_u64 v[64:65], s[86:87], 0, v[128:129]
	ds_read_b128 v[32:35], v147
	ds_read_b128 v[36:39], v147 offset:1024
	ds_read_b128 v[40:43], v147 offset:2048
	ds_read_b128 v[44:47], v147 offset:3072
	ds_read_b128 v[48:51], v147 offset:4096
	ds_read_b128 v[52:55], v147 offset:5120
	ds_read_b128 v[56:59], v147 offset:6144
	ds_read_b128 v[60:63], v147 offset:7168
	global_load_lds_dwordx4 v[64:65], off
	v_lshl_add_u64 v[64:65], s[86:87], 0, v[132:133]
	s_mov_b32 m0, s80
	s_nop 0
	global_load_lds_dwordx4 v[64:65], off
	s_waitcnt vmcnt(8)
	s_waitcnt lgkmcnt(0)
	s_barrier
	s_setprio 1
	v_mfma_f32_16x16x32_bf16 v[64:67], v[0:3], v[32:35], 0
	v_mfma_f32_16x16x32_bf16 v[68:71], v[8:11], v[32:35], 0
	v_mfma_f32_16x16x32_bf16 v[72:75], v[0:3], v[40:43], 0
	v_mfma_f32_16x16x32_bf16 v[76:79], v[8:11], v[40:43], 0
	v_mfma_f32_16x16x32_bf16 v[80:83], v[0:3], v[48:51], 0
	v_mfma_f32_16x16x32_bf16 v[84:87], v[8:11], v[48:51], 0
	v_mfma_f32_16x16x32_bf16 v[88:91], v[0:3], v[56:59], 0
	v_mfma_f32_16x16x32_bf16 v[92:95], v[8:11], v[56:59], 0
	v_mfma_f32_16x16x32_bf16 v[64:67], v[4:7], v[36:39], v[64:67]
	v_mfma_f32_16x16x32_bf16 v[68:71], v[12:15], v[36:39], v[68:71]
	v_mfma_f32_16x16x32_bf16 v[72:75], v[4:7], v[44:47], v[72:75]
	v_mfma_f32_16x16x32_bf16 v[76:79], v[12:15], v[44:47], v[76:79]
	v_mfma_f32_16x16x32_bf16 v[80:83], v[4:7], v[52:55], v[80:83]
	v_mfma_f32_16x16x32_bf16 v[84:87], v[12:15], v[52:55], v[84:87]
	v_mfma_f32_16x16x32_bf16 v[88:91], v[4:7], v[60:63], v[88:91]
	v_mfma_f32_16x16x32_bf16 v[92:95], v[12:15], v[60:63], v[92:95]
	v_mfma_f32_16x16x32_bf16 v[96:99], v[16:19], v[32:35], 0
	v_mfma_f32_16x16x32_bf16 v[32:35], v[24:27], v[32:35], 0
	v_mfma_f32_16x16x32_bf16 v[96:99], v[20:23], v[36:39], v[96:99]
	v_mfma_f32_16x16x32_bf16 v[32:35], v[28:31], v[36:39], v[32:35]
	v_mfma_f32_16x16x32_bf16 v[36:39], v[16:19], v[40:43], 0
	v_mfma_f32_16x16x32_bf16 v[40:43], v[24:27], v[40:43], 0
	v_mfma_f32_16x16x32_bf16 v[36:39], v[20:23], v[44:47], v[36:39]
	v_mfma_f32_16x16x32_bf16 v[40:43], v[28:31], v[44:47], v[40:43]
	v_mfma_f32_16x16x32_bf16 v[44:47], v[16:19], v[48:51], 0
	v_mfma_f32_16x16x32_bf16 v[48:51], v[24:27], v[48:51], 0
	v_mfma_f32_16x16x32_bf16 v[44:47], v[20:23], v[52:55], v[44:47]
	v_mfma_f32_16x16x32_bf16 v[48:51], v[28:31], v[52:55], v[48:51]
	v_mfma_f32_16x16x32_bf16 v[52:55], v[16:19], v[56:59], 0
	v_mfma_f32_16x16x32_bf16 v[56:59], v[24:27], v[56:59], 0
	v_mfma_f32_16x16x32_bf16 v[52:55], v[20:23], v[60:63], v[52:55]
	v_mfma_f32_16x16x32_bf16 v[56:59], v[28:31], v[60:63], v[56:59]
	s_setprio 0
	s_barrier
	s_add_i32 s85, s70, s48
	v_lshl_add_u64 v[140:141], s[60:61], 0, v[130:131]
	s_add_i32 s35, s85, 0x2000
	v_lshl_add_u64 v[148:149], v[140:141], 0, s[20:21]
	s_mov_b32 m0, s85
	v_lshl_add_u64 v[212:213], s[60:61], 0, v[134:135]
	s_add_u32 s86, s60, 0x10100
	ds_read_b128 v[60:63], v147 offset:16384
	ds_read_b128 v[100:103], v147 offset:17408
	ds_read_b128 v[104:107], v147 offset:18432
	ds_read_b128 v[108:111], v147 offset:19456
	ds_read_b128 v[112:115], v147 offset:20480
	ds_read_b128 v[116:119], v147 offset:21504
	ds_read_b128 v[120:123], v147 offset:22528
	ds_read_b128 v[124:127], v147 offset:23552
	global_load_lds_dwordx4 v[148:149], off
	v_lshl_add_u64 v[148:149], v[212:213], 0, s[20:21]
	s_mov_b32 m0, s35
	s_addc_u32 s87, s61, 0
	s_add_i32 s37, s71, s48
	global_load_lds_dwordx4 v[148:149], off
	v_lshl_add_u64 v[148:149], s[86:87], 0, v[130:131]
	s_mov_b32 m0, s37
	s_add_i32 s47, s37, 0x2000
	global_load_lds_dwordx4 v[148:149], off
	v_lshl_add_u64 v[148:149], s[86:87], 0, v[134:135]
	s_mov_b32 m0, s47
	v_lshl_add_u64 v[214:215], s[58:59], 0, v[128:129]
	global_load_lds_dwordx4 v[148:149], off
	v_lshl_add_u64 v[148:149], v[214:215], 0, s[20:21]
	s_mov_b32 m0, s49
	v_lshl_add_u64 v[216:217], s[58:59], 0, v[132:133]
	global_load_lds_dwordx4 v[148:149], off
	v_lshl_add_u64 v[148:149], v[216:217], 0, s[20:21]
	s_mov_b32 m0, s50
	s_nop 0
	global_load_lds_dwordx4 v[148:149], off
	s_waitcnt vmcnt(8)
	s_waitcnt lgkmcnt(0)
	s_barrier
	s_setprio 1
	v_mfma_f32_16x16x32_bf16 v[148:151], v[0:3], v[60:63], 0
	v_mfma_f32_16x16x32_bf16 v[156:159], v[0:3], v[104:107], 0
	v_mfma_f32_16x16x32_bf16 v[164:167], v[0:3], v[112:115], 0
	v_mfma_f32_16x16x32_bf16 v[0:3], v[0:3], v[120:123], 0
	v_mfma_f32_16x16x32_bf16 v[148:151], v[4:7], v[100:103], v[148:151]
	v_mfma_f32_16x16x32_bf16 v[156:159], v[4:7], v[108:111], v[156:159]
	v_mfma_f32_16x16x32_bf16 v[164:167], v[4:7], v[116:119], v[164:167]
	v_mfma_f32_16x16x32_bf16 v[0:3], v[4:7], v[124:127], v[0:3]
	v_mfma_f32_16x16x32_bf16 v[4:7], v[8:11], v[120:123], 0
	v_mfma_f32_16x16x32_bf16 v[152:155], v[8:11], v[60:63], 0
	v_mfma_f32_16x16x32_bf16 v[160:163], v[8:11], v[104:107], 0
	v_mfma_f32_16x16x32_bf16 v[168:171], v[8:11], v[112:115], 0
	v_mfma_f32_16x16x32_bf16 v[4:7], v[12:15], v[124:127], v[4:7]
	v_mfma_f32_16x16x32_bf16 v[152:155], v[12:15], v[100:103], v[152:155]
	v_mfma_f32_16x16x32_bf16 v[160:163], v[12:15], v[108:111], v[160:163]
	v_mfma_f32_16x16x32_bf16 v[168:171], v[12:15], v[116:119], v[168:171]
	v_mfma_f32_16x16x32_bf16 v[8:11], v[16:19], v[60:63], 0
	v_mfma_f32_16x16x32_bf16 v[12:15], v[24:27], v[60:63], 0
	v_mfma_f32_16x16x32_bf16 v[8:11], v[20:23], v[100:103], v[8:11]
	v_mfma_f32_16x16x32_bf16 v[12:15], v[28:31], v[100:103], v[12:15]
	v_mfma_f32_16x16x32_bf16 v[60:63], v[16:19], v[104:107], 0
	v_mfma_f32_16x16x32_bf16 v[100:103], v[24:27], v[104:107], 0
	v_mfma_f32_16x16x32_bf16 v[104:107], v[16:19], v[112:115], 0
	v_mfma_f32_16x16x32_bf16 v[16:19], v[16:19], v[120:123], 0
	v_mfma_f32_16x16x32_bf16 v[60:63], v[20:23], v[108:111], v[60:63]
	v_mfma_f32_16x16x32_bf16 v[100:103], v[28:31], v[108:111], v[100:103]
	v_mfma_f32_16x16x32_bf16 v[104:107], v[20:23], v[116:119], v[104:107]
	v_mfma_f32_16x16x32_bf16 v[108:111], v[24:27], v[112:115], 0
	v_mfma_f32_16x16x32_bf16 v[16:19], v[20:23], v[124:127], v[16:19]
	v_mfma_f32_16x16x32_bf16 v[20:23], v[24:27], v[120:123], 0
	v_mfma_f32_16x16x32_bf16 v[108:111], v[28:31], v[116:119], v[108:111]
	v_mfma_f32_16x16x32_bf16 v[20:23], v[28:31], v[124:127], v[20:23]
	s_setprio 0
	s_barrier
	s_add_i32 s78, 0, 0x18000
	s_add_i32 s79, 0, 0x1c000
	v_add_u32_e32 v224, s78, v143
	v_add_u32_e32 v232, s79, v143
	ds_read_b128 v[24:27], v224
	ds_read_b128 v[28:31], v224 offset:1024
	ds_read_b128 v[112:115], v224 offset:2048
	ds_read_b128 v[116:119], v224 offset:3072
	ds_read_b128 v[120:123], v232
	ds_read_b128 v[124:127], v232 offset:1024
	ds_read_b128 v[172:175], v232 offset:2048
	ds_read_b128 v[176:179], v232 offset:3072
	s_add_u32 s86, s58, 0x10100
	s_addc_u32 s87, s59, 0
	s_mov_b32 m0, s51
	v_lshl_add_u64 v[218:219], s[86:87], 0, v[128:129]
	ds_read_b128 v[180:183], v147 offset:32768
	ds_read_b128 v[184:187], v147 offset:33792
	ds_read_b128 v[188:191], v147 offset:34816
	ds_read_b128 v[192:195], v147 offset:35840
	ds_read_b128 v[196:199], v147 offset:36864
	ds_read_b128 v[200:203], v147 offset:37888
	ds_read_b128 v[204:207], v147 offset:38912
	ds_read_b128 v[208:211], v147 offset:39936
	global_load_lds_dwordx4 v[218:219], off
	v_lshl_add_u64 v[218:219], s[86:87], 0, v[132:133]
	s_mov_b32 m0, s57
	s_nop 0
	global_load_lds_dwordx4 v[218:219], off
	s_waitcnt vmcnt(8)
	s_waitcnt lgkmcnt(0)
	s_barrier
	s_setprio 1
	v_mfma_f32_16x16x32_bf16 v[64:67], v[24:27], v[180:183], v[64:67]
	v_mfma_f32_16x16x32_bf16 v[68:71], v[112:115], v[180:183], v[68:71]
	v_mfma_f32_16x16x32_bf16 v[72:75], v[24:27], v[188:191], v[72:75]
	v_mfma_f32_16x16x32_bf16 v[76:79], v[112:115], v[188:191], v[76:79]
	v_mfma_f32_16x16x32_bf16 v[80:83], v[24:27], v[196:199], v[80:83]
	v_mfma_f32_16x16x32_bf16 v[84:87], v[112:115], v[196:199], v[84:87]
	v_mfma_f32_16x16x32_bf16 v[88:91], v[24:27], v[204:207], v[88:91]
	v_mfma_f32_16x16x32_bf16 v[92:95], v[112:115], v[204:207], v[92:95]
	v_mfma_f32_16x16x32_bf16 v[64:67], v[28:31], v[184:187], v[64:67]
	v_mfma_f32_16x16x32_bf16 v[68:71], v[116:119], v[184:187], v[68:71]
	v_mfma_f32_16x16x32_bf16 v[72:75], v[28:31], v[192:195], v[72:75]
	v_mfma_f32_16x16x32_bf16 v[76:79], v[116:119], v[192:195], v[76:79]
	v_mfma_f32_16x16x32_bf16 v[80:83], v[28:31], v[200:203], v[80:83]
	v_mfma_f32_16x16x32_bf16 v[84:87], v[116:119], v[200:203], v[84:87]
	v_mfma_f32_16x16x32_bf16 v[88:91], v[28:31], v[208:211], v[88:91]
	v_mfma_f32_16x16x32_bf16 v[92:95], v[116:119], v[208:211], v[92:95]
	v_mfma_f32_16x16x32_bf16 v[96:99], v[120:123], v[180:183], v[96:99]
	v_mfma_f32_16x16x32_bf16 v[32:35], v[172:175], v[180:183], v[32:35]
	v_mfma_f32_16x16x32_bf16 v[36:39], v[120:123], v[188:191], v[36:39]
	v_mfma_f32_16x16x32_bf16 v[40:43], v[172:175], v[188:191], v[40:43]
	v_mfma_f32_16x16x32_bf16 v[44:47], v[120:123], v[196:199], v[44:47]
	v_mfma_f32_16x16x32_bf16 v[48:51], v[172:175], v[196:199], v[48:51]
	v_mfma_f32_16x16x32_bf16 v[52:55], v[120:123], v[204:207], v[52:55]
	v_mfma_f32_16x16x32_bf16 v[56:59], v[172:175], v[204:207], v[56:59]
	v_mfma_f32_16x16x32_bf16 v[96:99], v[124:127], v[184:187], v[96:99]
	v_mfma_f32_16x16x32_bf16 v[32:35], v[176:179], v[184:187], v[32:35]
	v_mfma_f32_16x16x32_bf16 v[36:39], v[124:127], v[192:195], v[36:39]
	v_mfma_f32_16x16x32_bf16 v[40:43], v[176:179], v[192:195], v[40:43]
	v_mfma_f32_16x16x32_bf16 v[44:47], v[124:127], v[200:203], v[44:47]
	v_mfma_f32_16x16x32_bf16 v[48:51], v[176:179], v[200:203], v[48:51]
	v_mfma_f32_16x16x32_bf16 v[52:55], v[124:127], v[208:211], v[52:55]
	v_mfma_f32_16x16x32_bf16 v[56:59], v[176:179], v[208:211], v[56:59]
	s_setprio 0
	s_barrier
	s_add_i32 s87, s78, s48
	s_add_i32 s86, s87, 0x2000
	v_lshl_add_u64 v[140:141], v[140:141], 0, s[22:23]
	s_mov_b32 m0, s87
	s_add_u32 s88, s60, 0x10180
	ds_read_b128 v[180:183], v147 offset:49152
	ds_read_b128 v[184:187], v147 offset:50176
	ds_read_b128 v[188:191], v147 offset:51200
	ds_read_b128 v[192:195], v147 offset:52224
	ds_read_b128 v[196:199], v147 offset:53248
	ds_read_b128 v[200:203], v147 offset:54272
	ds_read_b128 v[204:207], v147 offset:55296
	ds_read_b128 v[208:211], v147 offset:56320
	global_load_lds_dwordx4 v[140:141], off
	v_lshl_add_u64 v[140:141], v[212:213], 0, s[22:23]
	s_mov_b32 m0, s86
	s_addc_u32 s89, s61, 0
	s_add_i32 s60, s79, s48
	global_load_lds_dwordx4 v[140:141], off
	v_lshl_add_u64 v[140:141], s[88:89], 0, v[130:131]
	s_mov_b32 m0, s60
	s_add_i32 s61, s60, 0x2000
	global_load_lds_dwordx4 v[140:141], off
	v_lshl_add_u64 v[140:141], s[88:89], 0, v[134:135]
	s_mov_b32 m0, s61
	s_nop 0
	global_load_lds_dwordx4 v[140:141], off
	v_lshl_add_u64 v[140:141], v[214:215], 0, s[22:23]
	s_mov_b32 m0, s66
	s_nop 0
	global_load_lds_dwordx4 v[140:141], off
	v_lshl_add_u64 v[140:141], v[216:217], 0, s[22:23]
	s_mov_b32 m0, s67
	s_nop 0
	global_load_lds_dwordx4 v[140:141], off
	s_waitcnt vmcnt(8)
	s_waitcnt lgkmcnt(0)
	s_barrier
	s_setprio 1
	v_mfma_f32_16x16x32_bf16 v[0:3], v[24:27], v[204:207], v[0:3]
	v_mfma_f32_16x16x32_bf16 v[4:7], v[112:115], v[204:207], v[4:7]
	v_mfma_f32_16x16x32_bf16 v[148:151], v[24:27], v[180:183], v[148:151]
	v_mfma_f32_16x16x32_bf16 v[152:155], v[112:115], v[180:183], v[152:155]
	v_mfma_f32_16x16x32_bf16 v[156:159], v[24:27], v[188:191], v[156:159]
	v_mfma_f32_16x16x32_bf16 v[160:163], v[112:115], v[188:191], v[160:163]
	v_mfma_f32_16x16x32_bf16 v[164:167], v[24:27], v[196:199], v[164:167]
	v_mfma_f32_16x16x32_bf16 v[168:171], v[112:115], v[196:199], v[168:171]
	v_mfma_f32_16x16x32_bf16 v[0:3], v[28:31], v[208:211], v[0:3]
	v_mfma_f32_16x16x32_bf16 v[4:7], v[116:119], v[208:211], v[4:7]
	v_mfma_f32_16x16x32_bf16 v[148:151], v[28:31], v[184:187], v[148:151]
	v_mfma_f32_16x16x32_bf16 v[152:155], v[116:119], v[184:187], v[152:155]
	v_mfma_f32_16x16x32_bf16 v[156:159], v[28:31], v[192:195], v[156:159]
	v_mfma_f32_16x16x32_bf16 v[160:163], v[116:119], v[192:195], v[160:163]
	v_mfma_f32_16x16x32_bf16 v[164:167], v[28:31], v[200:203], v[164:167]
	v_mfma_f32_16x16x32_bf16 v[168:171], v[116:119], v[200:203], v[168:171]
	v_mfma_f32_16x16x32_bf16 v[8:11], v[120:123], v[180:183], v[8:11]
	v_mfma_f32_16x16x32_bf16 v[12:15], v[172:175], v[180:183], v[12:15]
	v_mfma_f32_16x16x32_bf16 v[24:27], v[120:123], v[188:191], v[60:63]
	v_mfma_f32_16x16x32_bf16 v[28:31], v[172:175], v[188:191], v[100:103]
	v_mfma_f32_16x16x32_bf16 v[60:63], v[120:123], v[196:199], v[104:107]
	v_mfma_f32_16x16x32_bf16 v[100:103], v[172:175], v[196:199], v[108:111]
	v_mfma_f32_16x16x32_bf16 v[16:19], v[120:123], v[204:207], v[16:19]
	v_mfma_f32_16x16x32_bf16 v[20:23], v[172:175], v[204:207], v[20:23]
	v_mfma_f32_16x16x32_bf16 v[8:11], v[124:127], v[184:187], v[8:11]
	v_mfma_f32_16x16x32_bf16 v[12:15], v[176:179], v[184:187], v[12:15]
	v_mfma_f32_16x16x32_bf16 v[24:27], v[124:127], v[192:195], v[24:27]
	v_mfma_f32_16x16x32_bf16 v[28:31], v[176:179], v[192:195], v[28:31]
	v_mfma_f32_16x16x32_bf16 v[60:63], v[124:127], v[200:203], v[60:63]
	v_mfma_f32_16x16x32_bf16 v[100:103], v[176:179], v[200:203], v[100:103]
	v_mfma_f32_16x16x32_bf16 v[16:19], v[124:127], v[208:211], v[16:19]
	v_mfma_f32_16x16x32_bf16 v[20:23], v[176:179], v[208:211], v[20:23]
	s_setprio 0
	s_barrier
	ds_read_b128 v[104:107], v145
	ds_read_b128 v[108:111], v145 offset:1024
	ds_read_b128 v[112:115], v145 offset:2048
	ds_read_b128 v[116:119], v145 offset:3072
	ds_read_b128 v[120:123], v146
	ds_read_b128 v[124:127], v146 offset:1024
	ds_read_b128 v[172:175], v146 offset:2048
	ds_read_b128 v[176:179], v146 offset:3072
	s_add_u32 s58, s58, 0x10180
	s_addc_u32 s59, s59, 0
	s_mov_b32 m0, s72
	v_lshl_add_u64 v[140:141], s[58:59], 0, v[128:129]
	ds_read_b128 v[180:183], v147
	ds_read_b128 v[184:187], v147 offset:1024
	ds_read_b128 v[188:191], v147 offset:2048
	ds_read_b128 v[192:195], v147 offset:3072
	ds_read_b128 v[196:199], v147 offset:4096
	ds_read_b128 v[200:203], v147 offset:5120
	ds_read_b128 v[204:207], v147 offset:6144
	ds_read_b128 v[208:211], v147 offset:7168
	global_load_lds_dwordx4 v[140:141], off
	v_lshl_add_u64 v[140:141], s[58:59], 0, v[132:133]
	s_mov_b32 m0, s80
	s_nop 0
	global_load_lds_dwordx4 v[140:141], off
	s_waitcnt vmcnt(8)
	s_waitcnt lgkmcnt(0)
	s_barrier
	s_setprio 1
	v_mfma_f32_16x16x32_bf16 v[88:91], v[104:107], v[204:207], v[88:91]
	v_mfma_f32_16x16x32_bf16 v[64:67], v[104:107], v[180:183], v[64:67]
	v_mfma_f32_16x16x32_bf16 v[68:71], v[112:115], v[180:183], v[68:71]
	v_mfma_f32_16x16x32_bf16 v[72:75], v[104:107], v[188:191], v[72:75]
	v_mfma_f32_16x16x32_bf16 v[76:79], v[112:115], v[188:191], v[76:79]
	v_mfma_f32_16x16x32_bf16 v[80:83], v[104:107], v[196:199], v[80:83]
	v_mfma_f32_16x16x32_bf16 v[84:87], v[112:115], v[196:199], v[84:87]
	v_mfma_f32_16x16x32_bf16 v[212:215], v[108:111], v[208:211], v[88:91]
	v_mfma_f32_16x16x32_bf16 v[88:91], v[112:115], v[204:207], v[92:95]
	v_mfma_f32_16x16x32_bf16 v[64:67], v[108:111], v[184:187], v[64:67]
	v_mfma_f32_16x16x32_bf16 v[68:71], v[116:119], v[184:187], v[68:71]
	v_mfma_f32_16x16x32_bf16 v[72:75], v[108:111], v[192:195], v[72:75]
	v_mfma_f32_16x16x32_bf16 v[76:79], v[116:119], v[192:195], v[76:79]
	v_mfma_f32_16x16x32_bf16 v[80:83], v[108:111], v[200:203], v[80:83]
	v_mfma_f32_16x16x32_bf16 v[84:87], v[116:119], v[200:203], v[84:87]
	v_mfma_f32_16x16x32_bf16 v[92:95], v[116:119], v[208:211], v[88:91]
	v_mfma_f32_16x16x32_bf16 v[48:51], v[172:175], v[196:199], v[48:51]
	v_mfma_f32_16x16x32_bf16 v[88:91], v[120:123], v[180:183], v[96:99]
	v_mfma_f32_16x16x32_bf16 v[32:35], v[172:175], v[180:183], v[32:35]
	v_mfma_f32_16x16x32_bf16 v[36:39], v[120:123], v[188:191], v[36:39]
	v_mfma_f32_16x16x32_bf16 v[40:43], v[172:175], v[188:191], v[40:43]
	v_mfma_f32_16x16x32_bf16 v[44:47], v[120:123], v[196:199], v[44:47]
	v_mfma_f32_16x16x32_bf16 v[180:183], v[176:179], v[200:203], v[48:51]
	v_mfma_f32_16x16x32_bf16 v[48:51], v[120:123], v[204:207], v[52:55]
	v_mfma_f32_16x16x32_bf16 v[32:35], v[176:179], v[184:187], v[32:35]
	v_mfma_f32_16x16x32_bf16 v[36:39], v[124:127], v[192:195], v[36:39]
	v_mfma_f32_16x16x32_bf16 v[40:43], v[176:179], v[192:195], v[40:43]
	v_mfma_f32_16x16x32_bf16 v[44:47], v[124:127], v[200:203], v[44:47]
	v_mfma_f32_16x16x32_bf16 v[52:55], v[124:127], v[208:211], v[48:51]
	v_mfma_f32_16x16x32_bf16 v[48:51], v[172:175], v[204:207], v[56:59]
	v_mfma_f32_16x16x32_bf16 v[216:219], v[124:127], v[184:187], v[88:91]
	v_mfma_f32_16x16x32_bf16 v[184:187], v[176:179], v[208:211], v[48:51]
	s_setprio 0
	s_barrier
	s_mov_b32 m0, s85
	v_lshl_add_u64 v[140:141], s[62:63], 0, v[130:131]
	s_add_u32 s58, s62, 0x10000
	s_nop 0
	ds_read_b128 v[48:51], v147 offset:16384
	ds_read_b128 v[56:59], v147 offset:17408
	ds_read_b128 v[88:91], v147 offset:18432
	ds_read_b128 v[96:99], v147 offset:19456
	ds_read_b128 v[188:191], v147 offset:20480
	ds_read_b128 v[192:195], v147 offset:21504
	ds_read_b128 v[196:199], v147 offset:22528
	ds_read_b128 v[200:203], v147 offset:23552
	global_load_lds_dwordx4 v[140:141], off
	v_lshl_add_u64 v[252:253], s[62:63], 0, v[134:135]
	s_mov_b32 m0, s35
	s_addc_u32 s59, s63, 0
	global_load_lds_dwordx4 v[252:253], off
	v_lshl_add_u64 v[204:205], s[58:59], 0, v[130:131]
	s_mov_b32 m0, s37
	v_lshl_add_u64 v[136:137], s[64:65], 0, v[128:129]
	global_load_lds_dwordx4 v[204:205], off
	v_lshl_add_u64 v[204:205], s[58:59], 0, v[134:135]
	s_mov_b32 m0, s47
	v_lshl_add_u64 v[138:139], s[64:65], 0, v[132:133]
	global_load_lds_dwordx4 v[204:205], off
	s_mov_b32 m0, s49
	s_nop 0
	global_load_lds_dwordx4 v[136:137], off
	s_mov_b32 m0, s50
	s_nop 0
	global_load_lds_dwordx4 v[138:139], off
	s_waitcnt vmcnt(8)
	s_waitcnt lgkmcnt(0)
	s_barrier
	s_setprio 1
	v_mfma_f32_16x16x32_bf16 v[0:3], v[104:107], v[196:199], v[0:3]
	v_mfma_f32_16x16x32_bf16 v[4:7], v[112:115], v[196:199], v[4:7]
	v_mfma_f32_16x16x32_bf16 v[148:151], v[104:107], v[48:51], v[148:151]
	v_mfma_f32_16x16x32_bf16 v[152:155], v[112:115], v[48:51], v[152:155]
	v_mfma_f32_16x16x32_bf16 v[156:159], v[104:107], v[88:91], v[156:159]
	v_mfma_f32_16x16x32_bf16 v[160:163], v[112:115], v[88:91], v[160:163]
	v_mfma_f32_16x16x32_bf16 v[164:167], v[104:107], v[188:191], v[164:167]
	v_mfma_f32_16x16x32_bf16 v[168:171], v[112:115], v[188:191], v[168:171]
	v_mfma_f32_16x16x32_bf16 v[0:3], v[108:111], v[200:203], v[0:3]
	v_mfma_f32_16x16x32_bf16 v[4:7], v[116:119], v[200:203], v[4:7]
	v_mfma_f32_16x16x32_bf16 v[148:151], v[108:111], v[56:59], v[148:151]
	v_mfma_f32_16x16x32_bf16 v[152:155], v[116:119], v[56:59], v[152:155]
	v_mfma_f32_16x16x32_bf16 v[156:159], v[108:111], v[96:99], v[156:159]
	v_mfma_f32_16x16x32_bf16 v[160:163], v[116:119], v[96:99], v[160:163]
	v_mfma_f32_16x16x32_bf16 v[164:167], v[108:111], v[192:195], v[164:167]
	v_mfma_f32_16x16x32_bf16 v[168:171], v[116:119], v[192:195], v[168:171]
	v_mfma_f32_16x16x32_bf16 v[12:15], v[172:175], v[48:51], v[12:15]
	v_mfma_f32_16x16x32_bf16 v[204:207], v[176:179], v[56:59], v[12:15]
	v_mfma_f32_16x16x32_bf16 v[12:15], v[120:123], v[88:91], v[24:27]
	v_mfma_f32_16x16x32_bf16 v[24:27], v[124:127], v[96:99], v[12:15]
	v_mfma_f32_16x16x32_bf16 v[12:15], v[172:175], v[88:91], v[28:31]
	v_mfma_f32_16x16x32_bf16 v[208:211], v[176:179], v[96:99], v[12:15]
	v_mfma_f32_16x16x32_bf16 v[12:15], v[120:123], v[188:191], v[60:63]
	v_mfma_f32_16x16x32_bf16 v[220:223], v[124:127], v[192:195], v[12:15]
	v_mfma_f32_16x16x32_bf16 v[12:15], v[172:175], v[188:191], v[100:103]
	v_mfma_f32_16x16x32_bf16 v[8:11], v[120:123], v[48:51], v[8:11]
	v_mfma_f32_16x16x32_bf16 v[188:191], v[176:179], v[192:195], v[12:15]
	v_mfma_f32_16x16x32_bf16 v[12:15], v[120:123], v[196:199], v[16:19]
	v_mfma_f32_16x16x32_bf16 v[8:11], v[124:127], v[56:59], v[8:11]
	v_mfma_f32_16x16x32_bf16 v[192:195], v[124:127], v[200:203], v[12:15]
	v_mfma_f32_16x16x32_bf16 v[12:15], v[172:175], v[196:199], v[20:23]
	v_mfma_f32_16x16x32_bf16 v[172:175], v[176:179], v[200:203], v[12:15]
	s_setprio 0
	s_barrier
	s_nop 4
	ds_read_b128 v[12:15], v224
	ds_read_b128 v[16:19], v224 offset:1024
	ds_read_b128 v[176:179], v224 offset:2048
	ds_read_b128 v[196:199], v224 offset:3072
	ds_read_b128 v[200:203], v232
	ds_read_b128 v[224:227], v232 offset:1024
	ds_read_b128 v[228:231], v232 offset:2048
	ds_read_b128 v[232:235], v232 offset:3072
	s_add_u32 s58, s64, 0x10000
	s_addc_u32 s59, s65, 0
	s_mov_b32 m0, s51
	v_lshl_add_u64 v[48:49], s[58:59], 0, v[128:129]
	ds_read_b128 v[20:23], v147 offset:32768
	ds_read_b128 v[28:31], v147 offset:33792
	ds_read_b128 v[60:63], v147 offset:34816
	ds_read_b128 v[100:103], v147 offset:35840
	ds_read_b128 v[236:239], v147 offset:36864
	ds_read_b128 v[240:243], v147 offset:37888
	ds_read_b128 v[244:247], v147 offset:38912
	ds_read_b128 v[248:251], v147 offset:39936
	global_load_lds_dwordx4 v[48:49], off
	v_lshl_add_u64 v[48:49], s[58:59], 0, v[132:133]
	s_mov_b32 m0, s57
	s_nop 0
	global_load_lds_dwordx4 v[48:49], off
	s_waitcnt vmcnt(8)
	s_waitcnt lgkmcnt(0)
	s_barrier
	s_setprio 1
	v_mfma_f32_16x16x32_bf16 v[48:51], v[12:15], v[20:23], v[64:67]
	v_mfma_f32_16x16x32_bf16 v[120:123], v[16:19], v[28:31], v[48:51]
	v_mfma_f32_16x16x32_bf16 v[48:51], v[176:179], v[20:23], v[68:71]
	v_mfma_f32_16x16x32_bf16 v[112:115], v[196:199], v[28:31], v[48:51]
	v_mfma_f32_16x16x32_bf16 v[48:51], v[12:15], v[60:63], v[72:75]
	v_mfma_f32_16x16x32_bf16 v[104:107], v[16:19], v[100:103], v[48:51]
	v_mfma_f32_16x16x32_bf16 v[48:51], v[176:179], v[60:63], v[76:79]
	v_mfma_f32_16x16x32_bf16 v[96:99], v[196:199], v[100:103], v[48:51]
	v_mfma_f32_16x16x32_bf16 v[48:51], v[12:15], v[236:239], v[80:83]
	v_mfma_f32_16x16x32_bf16 v[88:91], v[16:19], v[240:243], v[48:51]
	v_mfma_f32_16x16x32_bf16 v[48:51], v[176:179], v[236:239], v[84:87]
	v_mfma_f32_16x16x32_bf16 v[80:83], v[196:199], v[240:243], v[48:51]
	v_mfma_f32_16x16x32_bf16 v[48:51], v[12:15], v[244:247], v[212:215]
	v_mfma_f32_16x16x32_bf16 v[56:59], v[16:19], v[248:251], v[48:51]
	v_mfma_f32_16x16x32_bf16 v[48:51], v[176:179], v[244:247], v[92:95]
	v_mfma_f32_16x16x32_bf16 v[48:51], v[196:199], v[248:251], v[48:51]
	v_mfma_f32_16x16x32_bf16 v[64:67], v[200:203], v[20:23], v[216:219]
	v_mfma_f32_16x16x32_bf16 v[20:23], v[228:231], v[20:23], v[32:35]
	v_mfma_f32_16x16x32_bf16 v[116:119], v[232:235], v[28:31], v[20:23]
	v_mfma_f32_16x16x32_bf16 v[20:23], v[200:203], v[60:63], v[36:39]
	v_mfma_f32_16x16x32_bf16 v[108:111], v[224:227], v[100:103], v[20:23]
	v_mfma_f32_16x16x32_bf16 v[20:23], v[228:231], v[60:63], v[40:43]
	v_mfma_f32_16x16x32_bf16 v[100:103], v[232:235], v[100:103], v[20:23]
	v_mfma_f32_16x16x32_bf16 v[20:23], v[200:203], v[236:239], v[44:47]
	v_mfma_f32_16x16x32_bf16 v[92:95], v[224:227], v[240:243], v[20:23]
	v_mfma_f32_16x16x32_bf16 v[20:23], v[228:231], v[236:239], v[180:183]
	v_mfma_f32_16x16x32_bf16 v[84:87], v[232:235], v[240:243], v[20:23]
	v_mfma_f32_16x16x32_bf16 v[20:23], v[200:203], v[244:247], v[52:55]
	v_mfma_f32_16x16x32_bf16 v[60:63], v[224:227], v[248:251], v[20:23]
	v_mfma_f32_16x16x32_bf16 v[20:23], v[228:231], v[244:247], v[184:187]
	v_mfma_f32_16x16x32_bf16 v[124:127], v[224:227], v[28:31], v[64:67]
	v_mfma_f32_16x16x32_bf16 v[52:55], v[232:235], v[248:251], v[20:23]
	s_setprio 0
	s_barrier
	s_mov_b32 m0, s87
	s_nop 2
	v_lshl_add_u64 v[20:21], v[140:141], 0, s[14:15]
	s_add_u32 s58, s62, 0x10080
	ds_read_b128 v[32:35], v147 offset:49152
	ds_read_b128 v[40:43], v147 offset:50176
	ds_read_b128 v[180:183], v147 offset:51200
	ds_read_b128 v[184:187], v147 offset:52224
	ds_read_b128 v[212:215], v147 offset:53248
	ds_read_b128 v[216:219], v147 offset:54272
	ds_read_b128 v[236:239], v147 offset:55296
	ds_read_b128 v[240:243], v147 offset:56320
	global_load_lds_dwordx4 v[20:21], off
	v_lshl_add_u64 v[20:21], v[252:253], 0, s[14:15]
	s_mov_b32 m0, s86
	s_addc_u32 s59, s63, 0
	global_load_lds_dwordx4 v[20:21], off
	v_lshl_add_u64 v[20:21], s[58:59], 0, v[130:131]
	s_mov_b32 m0, s60
	s_nop 0
	global_load_lds_dwordx4 v[20:21], off
	v_lshl_add_u64 v[20:21], s[58:59], 0, v[134:135]
	s_mov_b32 m0, s61
	s_nop 0
	global_load_lds_dwordx4 v[20:21], off
	v_lshl_add_u64 v[20:21], v[136:137], 0, s[14:15]
	s_mov_b32 m0, s66
	s_nop 0
	global_load_lds_dwordx4 v[20:21], off
	v_lshl_add_u64 v[20:21], v[138:139], 0, s[14:15]
	s_mov_b32 m0, s67
	s_nop 0
	global_load_lds_dwordx4 v[20:21], off
	s_waitcnt vmcnt(8)
	s_waitcnt lgkmcnt(0)
	s_barrier
	s_setprio 1
	v_mfma_f32_16x16x32_bf16 v[20:23], v[12:15], v[32:35], v[148:151]
	v_mfma_f32_16x16x32_bf16 v[76:79], v[16:19], v[40:43], v[20:23]
	v_mfma_f32_16x16x32_bf16 v[20:23], v[176:179], v[32:35], v[152:155]
	v_mfma_f32_16x16x32_bf16 v[68:71], v[196:199], v[40:43], v[20:23]
	v_mfma_f32_16x16x32_bf16 v[20:23], v[12:15], v[180:183], v[156:159]
	v_mfma_f32_16x16x32_bf16 v[44:47], v[16:19], v[184:187], v[20:23]
	v_mfma_f32_16x16x32_bf16 v[20:23], v[176:179], v[180:183], v[160:163]
	v_mfma_f32_16x16x32_bf16 v[36:39], v[196:199], v[184:187], v[20:23]
	v_mfma_f32_16x16x32_bf16 v[20:23], v[12:15], v[212:215], v[164:167]
	v_mfma_f32_16x16x32_bf16 v[0:3], v[12:15], v[236:239], v[0:3]
	v_mfma_f32_16x16x32_bf16 v[28:31], v[16:19], v[216:219], v[20:23]
	v_mfma_f32_16x16x32_bf16 v[20:23], v[176:179], v[212:215], v[168:171]
	v_mfma_f32_16x16x32_bf16 v[12:15], v[16:19], v[240:243], v[0:3]
	v_mfma_f32_16x16x32_bf16 v[0:3], v[176:179], v[236:239], v[4:7]
	v_mfma_f32_16x16x32_bf16 v[20:23], v[196:199], v[216:219], v[20:23]
	v_mfma_f32_16x16x32_bf16 v[4:7], v[196:199], v[240:243], v[0:3]
	v_mfma_f32_16x16x32_bf16 v[0:3], v[200:203], v[32:35], v[8:11]
	v_mfma_f32_16x16x32_bf16 v[72:75], v[224:227], v[40:43], v[0:3]
	v_mfma_f32_16x16x32_bf16 v[0:3], v[228:231], v[32:35], v[204:207]
	v_mfma_f32_16x16x32_bf16 v[64:67], v[232:235], v[40:43], v[0:3]
	v_mfma_f32_16x16x32_bf16 v[0:3], v[200:203], v[180:183], v[24:27]
	v_mfma_f32_16x16x32_bf16 v[40:43], v[224:227], v[184:187], v[0:3]
	v_mfma_f32_16x16x32_bf16 v[0:3], v[228:231], v[180:183], v[208:211]
	v_mfma_f32_16x16x32_bf16 v[32:35], v[232:235], v[184:187], v[0:3]
	v_mfma_f32_16x16x32_bf16 v[0:3], v[200:203], v[212:215], v[220:223]
	v_mfma_f32_16x16x32_bf16 v[24:27], v[224:227], v[216:219], v[0:3]
	v_mfma_f32_16x16x32_bf16 v[0:3], v[228:231], v[212:215], v[188:191]
	v_mfma_f32_16x16x32_bf16 v[16:19], v[232:235], v[216:219], v[0:3]
	v_mfma_f32_16x16x32_bf16 v[0:3], v[200:203], v[236:239], v[192:195]
	v_mfma_f32_16x16x32_bf16 v[8:11], v[224:227], v[240:243], v[0:3]
	v_mfma_f32_16x16x32_bf16 v[0:3], v[228:231], v[236:239], v[172:175]
	v_mfma_f32_16x16x32_bf16 v[0:3], v[232:235], v[240:243], v[0:3]
	s_setprio 0
	s_barrier
	s_andn2_b64 vcc, exec, s[16:17]
	s_cbranch_vccnz .LBB0_710
	s_barrier

.LBB0_731:
	ds_read_b128 v[146:149], v153
	ds_read_b128 v[158:161], v153 offset:1024
	ds_read_b128 v[162:165], v153 offset:2048
	ds_read_b128 v[166:169], v153 offset:3072
	ds_read_b128 v[170:173], v154
	ds_read_b128 v[174:177], v154 offset:1024
	ds_read_b128 v[178:181], v154 offset:2048
	ds_read_b128 v[182:185], v154 offset:3072
	s_add_u32 s34, s30, 0xfff80080
	s_addc_u32 s35, s31, -1
	s_cmp_eq_u32 s61, 28
	s_cselect_b32 s37, s21, s35
	s_cselect_b32 s36, s46, s34
	s_cselect_b32 s35, s19, s60
	s_cselect_b32 s34, s47, s59
	v_lshl_add_u64 v[218:219], s[30:31], 0, v[140:141]
	s_add_i32 m0, s27, 0xc000
	ds_read_b128 v[186:189], v155
	ds_read_b128 v[190:193], v155 offset:1024
	ds_read_b128 v[194:197], v155 offset:2048
	ds_read_b128 v[198:201], v155 offset:3072
	ds_read_b128 v[202:205], v155 offset:4096
	ds_read_b128 v[206:209], v155 offset:5120
	ds_read_b128 v[210:213], v155 offset:6144
	ds_read_b128 v[214:217], v155 offset:7168
	global_load_lds_dwordx4 v[218:219], off
	v_lshl_add_u64 v[218:219], s[30:31], 0, v[138:139]
	s_add_i32 m0, s27, 0xe000
	s_nop 0
	global_load_lds_dwordx4 v[218:219], off
	s_waitcnt vmcnt(8)
	s_waitcnt lgkmcnt(0)
	s_barrier
	s_setprio 1
	v_mfma_f32_16x16x32_bf16 v[124:127], v[146:149], v[186:189], v[124:127]
	v_mfma_f32_16x16x32_bf16 v[120:123], v[162:165], v[186:189], v[120:123]
	v_mfma_f32_16x16x32_bf16 v[108:111], v[146:149], v[194:197], v[108:111]
	v_mfma_f32_16x16x32_bf16 v[104:107], v[162:165], v[194:197], v[104:107]
	v_mfma_f32_16x16x32_bf16 v[92:95], v[146:149], v[202:205], v[92:95]
	v_mfma_f32_16x16x32_bf16 v[88:91], v[162:165], v[202:205], v[88:91]
	v_mfma_f32_16x16x32_bf16 v[76:79], v[146:149], v[210:213], v[76:79]
	v_mfma_f32_16x16x32_bf16 v[72:75], v[162:165], v[210:213], v[72:75]
	v_mfma_f32_16x16x32_bf16 v[124:127], v[158:161], v[190:193], v[124:127]
	v_mfma_f32_16x16x32_bf16 v[120:123], v[166:169], v[190:193], v[120:123]
	v_mfma_f32_16x16x32_bf16 v[108:111], v[158:161], v[198:201], v[108:111]
	v_mfma_f32_16x16x32_bf16 v[104:107], v[166:169], v[198:201], v[104:107]
	v_mfma_f32_16x16x32_bf16 v[92:95], v[158:161], v[206:209], v[92:95]
	v_mfma_f32_16x16x32_bf16 v[88:91], v[166:169], v[206:209], v[88:91]
	v_mfma_f32_16x16x32_bf16 v[76:79], v[158:161], v[214:217], v[76:79]
	v_mfma_f32_16x16x32_bf16 v[72:75], v[166:169], v[214:217], v[72:75]
	v_mfma_f32_16x16x32_bf16 v[116:119], v[170:173], v[186:189], v[116:119]
	v_mfma_f32_16x16x32_bf16 v[112:115], v[178:181], v[186:189], v[112:115]
	v_mfma_f32_16x16x32_bf16 v[100:103], v[170:173], v[194:197], v[100:103]
	v_mfma_f32_16x16x32_bf16 v[96:99], v[178:181], v[194:197], v[96:99]
	v_mfma_f32_16x16x32_bf16 v[84:87], v[170:173], v[202:205], v[84:87]
	v_mfma_f32_16x16x32_bf16 v[80:83], v[178:181], v[202:205], v[80:83]
	v_mfma_f32_16x16x32_bf16 v[68:71], v[170:173], v[210:213], v[68:71]
	v_mfma_f32_16x16x32_bf16 v[64:67], v[178:181], v[210:213], v[64:67]
	v_mfma_f32_16x16x32_bf16 v[116:119], v[174:177], v[190:193], v[116:119]
	v_mfma_f32_16x16x32_bf16 v[112:115], v[182:185], v[190:193], v[112:115]
	v_mfma_f32_16x16x32_bf16 v[100:103], v[174:177], v[198:201], v[100:103]
	v_mfma_f32_16x16x32_bf16 v[96:99], v[182:185], v[198:201], v[96:99]
	v_mfma_f32_16x16x32_bf16 v[84:87], v[174:177], v[206:209], v[84:87]
	v_mfma_f32_16x16x32_bf16 v[80:83], v[182:185], v[206:209], v[80:83]
	v_mfma_f32_16x16x32_bf16 v[68:71], v[174:177], v[214:217], v[68:71]
	v_mfma_f32_16x16x32_bf16 v[64:67], v[182:185], v[214:217], v[64:67]
	s_setprio 0
	s_barrier
	s_add_i32 s62, s55, s48
	v_lshl_add_u64 v[218:219], s[34:35], 0, v[130:131]
	s_mov_b32 m0, s62
	ds_read_b128 v[186:189], v155 offset:16384
	ds_read_b128 v[190:193], v155 offset:17408
	ds_read_b128 v[194:197], v155 offset:18432
	ds_read_b128 v[198:201], v155 offset:19456
	ds_read_b128 v[202:205], v155 offset:20480
	ds_read_b128 v[206:209], v155 offset:21504
	ds_read_b128 v[210:213], v155 offset:22528
	ds_read_b128 v[214:217], v155 offset:23552
	global_load_lds_dwordx4 v[218:219], off
	s_add_i32 m0, s62, 0x2000
	s_add_u32 s62, s34, 0x80000
	v_lshl_add_u64 v[220:221], s[34:35], 0, v[134:135]
	s_addc_u32 s63, s35, 0
	s_add_i32 s64, s56, s48
	global_load_lds_dwordx4 v[220:221], off
	v_lshl_add_u64 v[222:223], s[62:63], 0, v[130:131]
	s_mov_b32 m0, s64
	v_lshl_add_u64 v[224:225], s[36:37], 0, v[132:133]
	global_load_lds_dwordx4 v[222:223], off
	v_lshl_add_u64 v[222:223], s[62:63], 0, v[134:135]
	s_add_i32 m0, s64, 0x2000
	s_nop 0
	global_load_lds_dwordx4 v[222:223], off
	v_lshl_add_u64 v[222:223], s[36:37], 0, v[128:129]
	s_mov_b32 m0, s27
	s_nop 0
	global_load_lds_dwordx4 v[222:223], off
	s_mov_b32 m0, s49
	s_nop 0
	global_load_lds_dwordx4 v[224:225], off
	s_waitcnt vmcnt(8)
	s_waitcnt lgkmcnt(0)
	s_barrier
	s_setprio 1
	v_mfma_f32_16x16x32_bf16 v[60:63], v[146:149], v[186:189], v[60:63]
	v_mfma_f32_16x16x32_bf16 v[56:59], v[162:165], v[186:189], v[56:59]
	v_mfma_f32_16x16x32_bf16 v[44:47], v[146:149], v[194:197], v[44:47]
	v_mfma_f32_16x16x32_bf16 v[40:43], v[162:165], v[194:197], v[40:43]
	v_mfma_f32_16x16x32_bf16 v[28:31], v[146:149], v[202:205], v[28:31]
	v_mfma_f32_16x16x32_bf16 v[24:27], v[162:165], v[202:205], v[24:27]
	v_mfma_f32_16x16x32_bf16 v[12:15], v[146:149], v[210:213], v[12:15]
	v_mfma_f32_16x16x32_bf16 v[8:11], v[162:165], v[210:213], v[8:11]
	v_mfma_f32_16x16x32_bf16 v[60:63], v[158:161], v[190:193], v[60:63]
	v_mfma_f32_16x16x32_bf16 v[56:59], v[166:169], v[190:193], v[56:59]
	v_mfma_f32_16x16x32_bf16 v[44:47], v[158:161], v[198:201], v[44:47]
	v_mfma_f32_16x16x32_bf16 v[40:43], v[166:169], v[198:201], v[40:43]
	v_mfma_f32_16x16x32_bf16 v[28:31], v[158:161], v[206:209], v[28:31]
	v_mfma_f32_16x16x32_bf16 v[24:27], v[166:169], v[206:209], v[24:27]
	v_mfma_f32_16x16x32_bf16 v[12:15], v[158:161], v[214:217], v[12:15]
	v_mfma_f32_16x16x32_bf16 v[8:11], v[166:169], v[214:217], v[8:11]
	v_mfma_f32_16x16x32_bf16 v[52:55], v[170:173], v[186:189], v[52:55]
	v_mfma_f32_16x16x32_bf16 v[48:51], v[178:181], v[186:189], v[48:51]
	v_mfma_f32_16x16x32_bf16 v[36:39], v[170:173], v[194:197], v[36:39]
	v_mfma_f32_16x16x32_bf16 v[32:35], v[178:181], v[194:197], v[32:35]
	v_mfma_f32_16x16x32_bf16 v[20:23], v[170:173], v[202:205], v[20:23]
	v_mfma_f32_16x16x32_bf16 v[16:19], v[178:181], v[202:205], v[16:19]
	v_mfma_f32_16x16x32_bf16 v[4:7], v[170:173], v[210:213], v[4:7]
	v_mfma_f32_16x16x32_bf16 v[0:3], v[178:181], v[210:213], v[0:3]
	v_mfma_f32_16x16x32_bf16 v[52:55], v[174:177], v[190:193], v[52:55]
	v_mfma_f32_16x16x32_bf16 v[48:51], v[182:185], v[190:193], v[48:51]
	v_mfma_f32_16x16x32_bf16 v[36:39], v[174:177], v[198:201], v[36:39]
	v_mfma_f32_16x16x32_bf16 v[32:35], v[182:185], v[198:201], v[32:35]
	v_mfma_f32_16x16x32_bf16 v[20:23], v[174:177], v[206:209], v[20:23]
	v_mfma_f32_16x16x32_bf16 v[16:19], v[182:185], v[206:209], v[16:19]
	v_mfma_f32_16x16x32_bf16 v[4:7], v[174:177], v[214:217], v[4:7]
	v_mfma_f32_16x16x32_bf16 v[0:3], v[182:185], v[214:217], v[0:3]
	s_setprio 0
	s_barrier
	s_add_i32 s62, 0, 0x18000
	s_add_i32 s63, 0, 0x1c000
	v_add_u32_e32 v166, s62, v151
	v_add_u32_e32 v182, s63, v151
	ds_read_b128 v[146:149], v166
	ds_read_b128 v[158:161], v166 offset:1024
	ds_read_b128 v[162:165], v166 offset:2048
	ds_read_b128 v[166:169], v166 offset:3072
	ds_read_b128 v[170:173], v182
	ds_read_b128 v[174:177], v182 offset:1024
	ds_read_b128 v[178:181], v182 offset:2048
	ds_read_b128 v[182:185], v182 offset:3072
	s_add_u32 s36, s36, 0x80000
	s_addc_u32 s37, s37, 0
	s_mov_b32 m0, s50
	v_lshl_add_u64 v[226:227], s[36:37], 0, v[128:129]
	ds_read_b128 v[186:189], v155 offset:32768
	ds_read_b128 v[190:193], v155 offset:33792
	ds_read_b128 v[194:197], v155 offset:34816
	ds_read_b128 v[198:201], v155 offset:35840
	ds_read_b128 v[202:205], v155 offset:36864
	ds_read_b128 v[206:209], v155 offset:37888
	ds_read_b128 v[210:213], v155 offset:38912
	ds_read_b128 v[214:217], v155 offset:39936
	global_load_lds_dwordx4 v[226:227], off
	v_lshl_add_u64 v[226:227], s[36:37], 0, v[132:133]
	s_mov_b32 m0, s51
	s_nop 0
	global_load_lds_dwordx4 v[226:227], off
	s_waitcnt vmcnt(8)
	s_waitcnt lgkmcnt(0)
	s_barrier
	s_setprio 1
	v_mfma_f32_16x16x32_bf16 v[124:127], v[146:149], v[186:189], v[124:127]
	v_mfma_f32_16x16x32_bf16 v[120:123], v[162:165], v[186:189], v[120:123]
	v_mfma_f32_16x16x32_bf16 v[108:111], v[146:149], v[194:197], v[108:111]
	v_mfma_f32_16x16x32_bf16 v[104:107], v[162:165], v[194:197], v[104:107]
	v_mfma_f32_16x16x32_bf16 v[92:95], v[146:149], v[202:205], v[92:95]
	v_mfma_f32_16x16x32_bf16 v[88:91], v[162:165], v[202:205], v[88:91]
	v_mfma_f32_16x16x32_bf16 v[76:79], v[146:149], v[210:213], v[76:79]
	v_mfma_f32_16x16x32_bf16 v[72:75], v[162:165], v[210:213], v[72:75]
	v_mfma_f32_16x16x32_bf16 v[124:127], v[158:161], v[190:193], v[124:127]
	v_mfma_f32_16x16x32_bf16 v[120:123], v[166:169], v[190:193], v[120:123]
	v_mfma_f32_16x16x32_bf16 v[108:111], v[158:161], v[198:201], v[108:111]
	v_mfma_f32_16x16x32_bf16 v[104:107], v[166:169], v[198:201], v[104:107]
	v_mfma_f32_16x16x32_bf16 v[92:95], v[158:161], v[206:209], v[92:95]
	v_mfma_f32_16x16x32_bf16 v[88:91], v[166:169], v[206:209], v[88:91]
	v_mfma_f32_16x16x32_bf16 v[76:79], v[158:161], v[214:217], v[76:79]
	v_mfma_f32_16x16x32_bf16 v[72:75], v[166:169], v[214:217], v[72:75]
	v_mfma_f32_16x16x32_bf16 v[116:119], v[170:173], v[186:189], v[116:119]
	v_mfma_f32_16x16x32_bf16 v[112:115], v[178:181], v[186:189], v[112:115]
	v_mfma_f32_16x16x32_bf16 v[100:103], v[170:173], v[194:197], v[100:103]
	v_mfma_f32_16x16x32_bf16 v[96:99], v[178:181], v[194:197], v[96:99]
	v_mfma_f32_16x16x32_bf16 v[84:87], v[170:173], v[202:205], v[84:87]
	v_mfma_f32_16x16x32_bf16 v[80:83], v[178:181], v[202:205], v[80:83]
	v_mfma_f32_16x16x32_bf16 v[68:71], v[170:173], v[210:213], v[68:71]
	v_mfma_f32_16x16x32_bf16 v[64:67], v[178:181], v[210:213], v[64:67]
	v_mfma_f32_16x16x32_bf16 v[116:119], v[174:177], v[190:193], v[116:119]
	v_mfma_f32_16x16x32_bf16 v[112:115], v[182:185], v[190:193], v[112:115]
	v_mfma_f32_16x16x32_bf16 v[100:103], v[174:177], v[198:201], v[100:103]
	v_mfma_f32_16x16x32_bf16 v[96:99], v[182:185], v[198:201], v[96:99]
	v_mfma_f32_16x16x32_bf16 v[84:87], v[174:177], v[206:209], v[84:87]
	v_mfma_f32_16x16x32_bf16 v[80:83], v[182:185], v[206:209], v[80:83]
	v_mfma_f32_16x16x32_bf16 v[68:71], v[174:177], v[214:217], v[68:71]
	v_mfma_f32_16x16x32_bf16 v[64:67], v[182:185], v[214:217], v[64:67]
	s_setprio 0
	s_barrier
	s_add_i32 s36, s62, s48
	v_lshl_add_u64 v[218:219], v[218:219], 0, s[14:15]
	s_mov_b32 m0, s36
	ds_read_b128 v[186:189], v155 offset:49152
	ds_read_b128 v[190:193], v155 offset:50176
	ds_read_b128 v[194:197], v155 offset:51200
	ds_read_b128 v[198:201], v155 offset:52224
	ds_read_b128 v[202:205], v155 offset:53248
	ds_read_b128 v[206:209], v155 offset:54272
	ds_read_b128 v[210:213], v155 offset:55296
	ds_read_b128 v[214:217], v155 offset:56320
	global_load_lds_dwordx4 v[218:219], off
	s_add_i32 m0, s36, 0x2000
	s_add_u32 s34, s34, 0x80080
	v_lshl_add_u64 v[218:219], v[220:221], 0, s[14:15]
	s_addc_u32 s35, s35, 0
	s_add_i32 s36, s63, s48
	global_load_lds_dwordx4 v[218:219], off
	v_lshl_add_u64 v[218:219], s[34:35], 0, v[130:131]
	s_mov_b32 m0, s36
	s_nop 0
	global_load_lds_dwordx4 v[218:219], off
	v_lshl_add_u64 v[218:219], s[34:35], 0, v[134:135]
	s_add_i32 m0, s36, 0x2000
	s_nop 0
	global_load_lds_dwordx4 v[218:219], off
	v_lshl_add_u64 v[218:219], v[222:223], 0, s[14:15]
	s_mov_b32 m0, s53
	s_nop 0
	global_load_lds_dwordx4 v[218:219], off
	v_lshl_add_u64 v[218:219], v[224:225], 0, s[14:15]
	s_mov_b32 m0, s54
	s_nop 0
	global_load_lds_dwordx4 v[218:219], off
	s_waitcnt vmcnt(8)
	s_waitcnt lgkmcnt(0)
	s_barrier
	s_setprio 1
	v_mfma_f32_16x16x32_bf16 v[60:63], v[146:149], v[186:189], v[60:63]
	v_mfma_f32_16x16x32_bf16 v[56:59], v[162:165], v[186:189], v[56:59]
	v_mfma_f32_16x16x32_bf16 v[44:47], v[146:149], v[194:197], v[44:47]
	v_mfma_f32_16x16x32_bf16 v[40:43], v[162:165], v[194:197], v[40:43]
	v_mfma_f32_16x16x32_bf16 v[28:31], v[146:149], v[202:205], v[28:31]
	v_mfma_f32_16x16x32_bf16 v[24:27], v[162:165], v[202:205], v[24:27]
	v_mfma_f32_16x16x32_bf16 v[12:15], v[146:149], v[210:213], v[12:15]
	v_mfma_f32_16x16x32_bf16 v[8:11], v[162:165], v[210:213], v[8:11]
	v_mfma_f32_16x16x32_bf16 v[60:63], v[158:161], v[190:193], v[60:63]
	v_mfma_f32_16x16x32_bf16 v[56:59], v[166:169], v[190:193], v[56:59]
	v_mfma_f32_16x16x32_bf16 v[44:47], v[158:161], v[198:201], v[44:47]
	v_mfma_f32_16x16x32_bf16 v[40:43], v[166:169], v[198:201], v[40:43]
	v_mfma_f32_16x16x32_bf16 v[28:31], v[158:161], v[206:209], v[28:31]
	v_mfma_f32_16x16x32_bf16 v[24:27], v[166:169], v[206:209], v[24:27]
	v_mfma_f32_16x16x32_bf16 v[12:15], v[158:161], v[214:217], v[12:15]
	v_mfma_f32_16x16x32_bf16 v[8:11], v[166:169], v[214:217], v[8:11]
	v_mfma_f32_16x16x32_bf16 v[52:55], v[170:173], v[186:189], v[52:55]
	v_mfma_f32_16x16x32_bf16 v[48:51], v[178:181], v[186:189], v[48:51]
	v_mfma_f32_16x16x32_bf16 v[36:39], v[170:173], v[194:197], v[36:39]
	v_mfma_f32_16x16x32_bf16 v[32:35], v[178:181], v[194:197], v[32:35]
	v_mfma_f32_16x16x32_bf16 v[20:23], v[170:173], v[202:205], v[20:23]
	v_mfma_f32_16x16x32_bf16 v[16:19], v[178:181], v[202:205], v[16:19]
	v_mfma_f32_16x16x32_bf16 v[4:7], v[170:173], v[210:213], v[4:7]
	v_mfma_f32_16x16x32_bf16 v[0:3], v[178:181], v[210:213], v[0:3]
	v_mfma_f32_16x16x32_bf16 v[52:55], v[174:177], v[190:193], v[52:55]
	v_mfma_f32_16x16x32_bf16 v[48:51], v[182:185], v[190:193], v[48:51]
	v_mfma_f32_16x16x32_bf16 v[36:39], v[174:177], v[198:201], v[36:39]
	v_mfma_f32_16x16x32_bf16 v[32:35], v[182:185], v[198:201], v[32:35]
	v_mfma_f32_16x16x32_bf16 v[20:23], v[174:177], v[206:209], v[20:23]
	v_mfma_f32_16x16x32_bf16 v[16:19], v[182:185], v[206:209], v[16:19]
	v_mfma_f32_16x16x32_bf16 v[4:7], v[174:177], v[214:217], v[4:7]
	v_mfma_f32_16x16x32_bf16 v[0:3], v[182:185], v[214:217], v[0:3]
	s_setprio 0
	s_barrier
	s_add_i32 s61, s61, 2
	s_add_u32 s59, s59, 0x100
	s_addc_u32 s60, s60, 0
	s_add_u32 s30, s30, 0x100
	s_addc_u32 s31, s31, 0
	s_cmp_gt_u32 s61, 29
	s_cbranch_scc0 .LBB0_731
	s_and_b64 vcc, exec, s[16:17]
	s_cbranch_vccz .LBB0_734
	s_barrier

.LBB0_952:
	ds_read_b128 v[144:147], v151
	ds_read_b128 v[156:159], v151 offset:1024
	ds_read_b128 v[160:163], v151 offset:2048
	ds_read_b128 v[164:167], v151 offset:3072
	ds_read_b128 v[168:171], v152
	ds_read_b128 v[172:175], v152 offset:1024
	ds_read_b128 v[176:179], v152 offset:2048
	ds_read_b128 v[180:183], v152 offset:3072
	s_add_u32 s54, s52, 0xfff80080
	s_addc_u32 s55, s53, -1
	s_cmp_eq_u32 s68, 28
	s_cselect_b32 s57, s27, s55
	s_cselect_b32 s56, s37, s54
	s_cselect_b32 s55, s25, s67
	s_cselect_b32 s54, s46, s47
	v_lshl_add_u64 v[216:217], s[52:53], 0, v[138:139]
	s_add_i32 m0, s59, 0xc000
	ds_read_b128 v[184:187], v153
	ds_read_b128 v[188:191], v153 offset:1024
	ds_read_b128 v[192:195], v153 offset:2048
	ds_read_b128 v[196:199], v153 offset:3072
	ds_read_b128 v[200:203], v153 offset:4096
	ds_read_b128 v[204:207], v153 offset:5120
	ds_read_b128 v[208:211], v153 offset:6144
	ds_read_b128 v[212:215], v153 offset:7168
	global_load_lds_dwordx4 v[216:217], off
	v_lshl_add_u64 v[216:217], s[52:53], 0, v[136:137]
	s_add_i32 m0, s59, 0xe000
	s_nop 0
	global_load_lds_dwordx4 v[216:217], off
	s_waitcnt vmcnt(8)
	s_waitcnt lgkmcnt(0)
	s_barrier
	s_setprio 1
	v_mfma_f32_16x16x32_bf16 v[116:119], v[144:147], v[184:187], v[116:119]
	v_mfma_f32_16x16x32_bf16 v[112:115], v[160:163], v[184:187], v[112:115]
	v_mfma_f32_16x16x32_bf16 v[104:107], v[144:147], v[192:195], v[104:107]
	v_mfma_f32_16x16x32_bf16 v[96:99], v[160:163], v[192:195], v[96:99]
	v_mfma_f32_16x16x32_bf16 v[88:91], v[144:147], v[200:203], v[88:91]
	v_mfma_f32_16x16x32_bf16 v[80:83], v[160:163], v[200:203], v[80:83]
	v_mfma_f32_16x16x32_bf16 v[72:75], v[144:147], v[208:211], v[72:75]
	v_mfma_f32_16x16x32_bf16 v[64:67], v[160:163], v[208:211], v[64:67]
	v_mfma_f32_16x16x32_bf16 v[116:119], v[156:159], v[188:191], v[116:119]
	v_mfma_f32_16x16x32_bf16 v[112:115], v[164:167], v[188:191], v[112:115]
	v_mfma_f32_16x16x32_bf16 v[104:107], v[156:159], v[196:199], v[104:107]
	v_mfma_f32_16x16x32_bf16 v[96:99], v[164:167], v[196:199], v[96:99]
	v_mfma_f32_16x16x32_bf16 v[88:91], v[156:159], v[204:207], v[88:91]
	v_mfma_f32_16x16x32_bf16 v[80:83], v[164:167], v[204:207], v[80:83]
	v_mfma_f32_16x16x32_bf16 v[72:75], v[156:159], v[212:215], v[72:75]
	v_mfma_f32_16x16x32_bf16 v[64:67], v[164:167], v[212:215], v[64:67]
	v_mfma_f32_16x16x32_bf16 v[124:127], v[168:171], v[184:187], v[124:127]
	v_mfma_f32_16x16x32_bf16 v[120:123], v[176:179], v[184:187], v[120:123]
	v_mfma_f32_16x16x32_bf16 v[108:111], v[168:171], v[192:195], v[108:111]
	v_mfma_f32_16x16x32_bf16 v[100:103], v[176:179], v[192:195], v[100:103]
	v_mfma_f32_16x16x32_bf16 v[92:95], v[168:171], v[200:203], v[92:95]
	v_mfma_f32_16x16x32_bf16 v[84:87], v[176:179], v[200:203], v[84:87]
	v_mfma_f32_16x16x32_bf16 v[76:79], v[168:171], v[208:211], v[76:79]
	v_mfma_f32_16x16x32_bf16 v[68:71], v[176:179], v[208:211], v[68:71]
	v_mfma_f32_16x16x32_bf16 v[124:127], v[172:175], v[188:191], v[124:127]
	v_mfma_f32_16x16x32_bf16 v[120:123], v[180:183], v[188:191], v[120:123]
	v_mfma_f32_16x16x32_bf16 v[108:111], v[172:175], v[196:199], v[108:111]
	v_mfma_f32_16x16x32_bf16 v[100:103], v[180:183], v[196:199], v[100:103]
	v_mfma_f32_16x16x32_bf16 v[92:95], v[172:175], v[204:207], v[92:95]
	v_mfma_f32_16x16x32_bf16 v[84:87], v[180:183], v[204:207], v[84:87]
	v_mfma_f32_16x16x32_bf16 v[76:79], v[172:175], v[212:215], v[76:79]
	v_mfma_f32_16x16x32_bf16 v[68:71], v[180:183], v[212:215], v[68:71]
	s_setprio 0
	s_barrier
	s_add_i32 s69, s64, s58
	v_lshl_add_u64 v[216:217], s[54:55], 0, v[130:131]
	s_mov_b32 m0, s69
	ds_read_b128 v[184:187], v153 offset:16384
	ds_read_b128 v[188:191], v153 offset:17408
	ds_read_b128 v[192:195], v153 offset:18432
	ds_read_b128 v[196:199], v153 offset:19456
	ds_read_b128 v[200:203], v153 offset:20480
	ds_read_b128 v[204:207], v153 offset:21504
	ds_read_b128 v[208:211], v153 offset:22528
	ds_read_b128 v[212:215], v153 offset:23552
	global_load_lds_dwordx4 v[216:217], off
	s_add_i32 m0, s69, 0x2000
	s_add_u32 s70, s54, 0x80000
	v_lshl_add_u64 v[218:219], s[54:55], 0, v[134:135]
	s_addc_u32 s71, s55, 0
	s_add_i32 s69, s65, s58
	global_load_lds_dwordx4 v[218:219], off
	v_lshl_add_u64 v[220:221], s[70:71], 0, v[130:131]
	s_mov_b32 m0, s69
	v_lshl_add_u64 v[222:223], s[56:57], 0, v[132:133]
	global_load_lds_dwordx4 v[220:221], off
	v_lshl_add_u64 v[220:221], s[70:71], 0, v[134:135]
	s_add_i32 m0, s69, 0x2000
	s_nop 0
	global_load_lds_dwordx4 v[220:221], off
	v_lshl_add_u64 v[220:221], s[56:57], 0, v[128:129]
	s_mov_b32 m0, s59
	s_nop 0
	global_load_lds_dwordx4 v[220:221], off
	s_mov_b32 m0, s50
	s_nop 0
	global_load_lds_dwordx4 v[222:223], off
	s_waitcnt vmcnt(8)
	s_waitcnt lgkmcnt(0)
	s_barrier
	s_setprio 1
	v_mfma_f32_16x16x32_bf16 v[56:59], v[144:147], v[184:187], v[56:59]
	v_mfma_f32_16x16x32_bf16 v[48:51], v[160:163], v[184:187], v[48:51]
	v_mfma_f32_16x16x32_bf16 v[40:43], v[144:147], v[192:195], v[40:43]
	v_mfma_f32_16x16x32_bf16 v[32:35], v[160:163], v[192:195], v[32:35]
	v_mfma_f32_16x16x32_bf16 v[24:27], v[144:147], v[200:203], v[24:27]
	v_mfma_f32_16x16x32_bf16 v[16:19], v[160:163], v[200:203], v[16:19]
	v_mfma_f32_16x16x32_bf16 v[8:11], v[144:147], v[208:211], v[8:11]
	v_mfma_f32_16x16x32_bf16 v[0:3], v[160:163], v[208:211], v[0:3]
	v_mfma_f32_16x16x32_bf16 v[56:59], v[156:159], v[188:191], v[56:59]
	v_mfma_f32_16x16x32_bf16 v[48:51], v[164:167], v[188:191], v[48:51]
	v_mfma_f32_16x16x32_bf16 v[40:43], v[156:159], v[196:199], v[40:43]
	v_mfma_f32_16x16x32_bf16 v[32:35], v[164:167], v[196:199], v[32:35]
	v_mfma_f32_16x16x32_bf16 v[24:27], v[156:159], v[204:207], v[24:27]
	v_mfma_f32_16x16x32_bf16 v[16:19], v[164:167], v[204:207], v[16:19]
	v_mfma_f32_16x16x32_bf16 v[8:11], v[156:159], v[212:215], v[8:11]
	v_mfma_f32_16x16x32_bf16 v[0:3], v[164:167], v[212:215], v[0:3]
	v_mfma_f32_16x16x32_bf16 v[60:63], v[168:171], v[184:187], v[60:63]
	v_mfma_f32_16x16x32_bf16 v[52:55], v[176:179], v[184:187], v[52:55]
	v_mfma_f32_16x16x32_bf16 v[44:47], v[168:171], v[192:195], v[44:47]
	v_mfma_f32_16x16x32_bf16 v[36:39], v[176:179], v[192:195], v[36:39]
	v_mfma_f32_16x16x32_bf16 v[28:31], v[168:171], v[200:203], v[28:31]
	v_mfma_f32_16x16x32_bf16 v[20:23], v[176:179], v[200:203], v[20:23]
	v_mfma_f32_16x16x32_bf16 v[12:15], v[168:171], v[208:211], v[12:15]
	v_mfma_f32_16x16x32_bf16 v[4:7], v[176:179], v[208:211], v[4:7]
	v_mfma_f32_16x16x32_bf16 v[60:63], v[172:175], v[188:191], v[60:63]
	v_mfma_f32_16x16x32_bf16 v[52:55], v[180:183], v[188:191], v[52:55]
	v_mfma_f32_16x16x32_bf16 v[44:47], v[172:175], v[196:199], v[44:47]
	v_mfma_f32_16x16x32_bf16 v[36:39], v[180:183], v[196:199], v[36:39]
	v_mfma_f32_16x16x32_bf16 v[28:31], v[172:175], v[204:207], v[28:31]
	v_mfma_f32_16x16x32_bf16 v[20:23], v[180:183], v[204:207], v[20:23]
	v_mfma_f32_16x16x32_bf16 v[12:15], v[172:175], v[212:215], v[12:15]
	v_mfma_f32_16x16x32_bf16 v[4:7], v[180:183], v[212:215], v[4:7]
	s_setprio 0
	s_barrier
	s_add_i32 s69, 0, 0x18000
	v_add_u32_e32 v155, s69, v149
	s_add_i32 s70, 0, 0x1c000
	ds_read_b128 v[144:147], v155
	ds_read_b128 v[156:159], v155 offset:1024
	ds_read_b128 v[160:163], v155 offset:2048
	ds_read_b128 v[164:167], v155 offset:3072
	v_add_u32_e32 v155, s70, v149
	ds_read_b128 v[168:171], v155
	ds_read_b128 v[172:175], v155 offset:1024
	ds_read_b128 v[176:179], v155 offset:2048
	ds_read_b128 v[180:183], v155 offset:3072
	s_add_u32 s56, s56, 0x80000
	s_addc_u32 s57, s57, 0
	s_mov_b32 m0, s51
	v_lshl_add_u64 v[224:225], s[56:57], 0, v[128:129]
	ds_read_b128 v[184:187], v153 offset:32768
	ds_read_b128 v[188:191], v153 offset:33792
	ds_read_b128 v[192:195], v153 offset:34816
	ds_read_b128 v[196:199], v153 offset:35840
	ds_read_b128 v[200:203], v153 offset:36864
	ds_read_b128 v[204:207], v153 offset:37888
	ds_read_b128 v[208:211], v153 offset:38912
	ds_read_b128 v[212:215], v153 offset:39936
	global_load_lds_dwordx4 v[224:225], off
	v_lshl_add_u64 v[224:225], s[56:57], 0, v[132:133]
	s_mov_b32 m0, s60
	s_nop 0
	global_load_lds_dwordx4 v[224:225], off
	s_waitcnt vmcnt(8)
	s_waitcnt lgkmcnt(0)
	s_barrier
	s_setprio 1
	v_mfma_f32_16x16x32_bf16 v[116:119], v[144:147], v[184:187], v[116:119]
	v_mfma_f32_16x16x32_bf16 v[112:115], v[160:163], v[184:187], v[112:115]
	v_mfma_f32_16x16x32_bf16 v[104:107], v[144:147], v[192:195], v[104:107]
	v_mfma_f32_16x16x32_bf16 v[96:99], v[160:163], v[192:195], v[96:99]
	v_mfma_f32_16x16x32_bf16 v[88:91], v[144:147], v[200:203], v[88:91]
	v_mfma_f32_16x16x32_bf16 v[80:83], v[160:163], v[200:203], v[80:83]
	v_mfma_f32_16x16x32_bf16 v[72:75], v[144:147], v[208:211], v[72:75]
	v_mfma_f32_16x16x32_bf16 v[64:67], v[160:163], v[208:211], v[64:67]
	v_mfma_f32_16x16x32_bf16 v[116:119], v[156:159], v[188:191], v[116:119]
	v_mfma_f32_16x16x32_bf16 v[112:115], v[164:167], v[188:191], v[112:115]
	v_mfma_f32_16x16x32_bf16 v[104:107], v[156:159], v[196:199], v[104:107]
	v_mfma_f32_16x16x32_bf16 v[96:99], v[164:167], v[196:199], v[96:99]
	v_mfma_f32_16x16x32_bf16 v[88:91], v[156:159], v[204:207], v[88:91]
	v_mfma_f32_16x16x32_bf16 v[80:83], v[164:167], v[204:207], v[80:83]
	v_mfma_f32_16x16x32_bf16 v[72:75], v[156:159], v[212:215], v[72:75]
	v_mfma_f32_16x16x32_bf16 v[64:67], v[164:167], v[212:215], v[64:67]
	v_mfma_f32_16x16x32_bf16 v[124:127], v[168:171], v[184:187], v[124:127]
	v_mfma_f32_16x16x32_bf16 v[120:123], v[176:179], v[184:187], v[120:123]
	v_mfma_f32_16x16x32_bf16 v[108:111], v[168:171], v[192:195], v[108:111]
	v_mfma_f32_16x16x32_bf16 v[100:103], v[176:179], v[192:195], v[100:103]
	v_mfma_f32_16x16x32_bf16 v[92:95], v[168:171], v[200:203], v[92:95]
	v_mfma_f32_16x16x32_bf16 v[84:87], v[176:179], v[200:203], v[84:87]
	v_mfma_f32_16x16x32_bf16 v[76:79], v[168:171], v[208:211], v[76:79]
	v_mfma_f32_16x16x32_bf16 v[68:71], v[176:179], v[208:211], v[68:71]
	v_mfma_f32_16x16x32_bf16 v[124:127], v[172:175], v[188:191], v[124:127]
	v_mfma_f32_16x16x32_bf16 v[120:123], v[180:183], v[188:191], v[120:123]
	v_mfma_f32_16x16x32_bf16 v[108:111], v[172:175], v[196:199], v[108:111]
	v_mfma_f32_16x16x32_bf16 v[100:103], v[180:183], v[196:199], v[100:103]
	v_mfma_f32_16x16x32_bf16 v[92:95], v[172:175], v[204:207], v[92:95]
	v_mfma_f32_16x16x32_bf16 v[84:87], v[180:183], v[204:207], v[84:87]
	v_mfma_f32_16x16x32_bf16 v[76:79], v[172:175], v[212:215], v[76:79]
	v_mfma_f32_16x16x32_bf16 v[68:71], v[180:183], v[212:215], v[68:71]
	s_setprio 0
	s_barrier
	s_add_i32 s56, s69, s58
	v_lshl_add_u64 v[216:217], v[216:217], 0, s[20:21]
	s_mov_b32 m0, s56
	ds_read_b128 v[184:187], v153 offset:49152
	ds_read_b128 v[188:191], v153 offset:50176
	ds_read_b128 v[192:195], v153 offset:51200
	ds_read_b128 v[196:199], v153 offset:52224
	ds_read_b128 v[200:203], v153 offset:53248
	ds_read_b128 v[204:207], v153 offset:54272
	ds_read_b128 v[208:211], v153 offset:55296
	ds_read_b128 v[212:215], v153 offset:56320
	global_load_lds_dwordx4 v[216:217], off
	s_add_i32 m0, s56, 0x2000
	s_add_u32 s54, s54, 0x80080
	v_lshl_add_u64 v[216:217], v[218:219], 0, s[20:21]
	s_addc_u32 s55, s55, 0
	s_add_i32 s56, s70, s58
	global_load_lds_dwordx4 v[216:217], off
	v_lshl_add_u64 v[216:217], s[54:55], 0, v[130:131]
	s_mov_b32 m0, s56
	s_nop 0
	global_load_lds_dwordx4 v[216:217], off
	v_lshl_add_u64 v[216:217], s[54:55], 0, v[134:135]
	s_add_i32 m0, s56, 0x2000
	s_nop 0
	global_load_lds_dwordx4 v[216:217], off
	v_lshl_add_u64 v[216:217], v[220:221], 0, s[20:21]
	s_mov_b32 m0, s62
	s_nop 0
	global_load_lds_dwordx4 v[216:217], off
	v_lshl_add_u64 v[216:217], v[222:223], 0, s[20:21]
	s_mov_b32 m0, s63
	s_nop 0
	global_load_lds_dwordx4 v[216:217], off
	s_waitcnt vmcnt(8)
	s_waitcnt lgkmcnt(0)
	s_barrier
	s_setprio 1
	v_mfma_f32_16x16x32_bf16 v[56:59], v[144:147], v[184:187], v[56:59]
	v_mfma_f32_16x16x32_bf16 v[48:51], v[160:163], v[184:187], v[48:51]
	v_mfma_f32_16x16x32_bf16 v[40:43], v[144:147], v[192:195], v[40:43]
	v_mfma_f32_16x16x32_bf16 v[32:35], v[160:163], v[192:195], v[32:35]
	v_mfma_f32_16x16x32_bf16 v[24:27], v[144:147], v[200:203], v[24:27]
	v_mfma_f32_16x16x32_bf16 v[16:19], v[160:163], v[200:203], v[16:19]
	v_mfma_f32_16x16x32_bf16 v[8:11], v[144:147], v[208:211], v[8:11]
	v_mfma_f32_16x16x32_bf16 v[0:3], v[160:163], v[208:211], v[0:3]
	v_mfma_f32_16x16x32_bf16 v[56:59], v[156:159], v[188:191], v[56:59]
	v_mfma_f32_16x16x32_bf16 v[48:51], v[164:167], v[188:191], v[48:51]
	v_mfma_f32_16x16x32_bf16 v[40:43], v[156:159], v[196:199], v[40:43]
	v_mfma_f32_16x16x32_bf16 v[32:35], v[164:167], v[196:199], v[32:35]
	v_mfma_f32_16x16x32_bf16 v[24:27], v[156:159], v[204:207], v[24:27]
	v_mfma_f32_16x16x32_bf16 v[16:19], v[164:167], v[204:207], v[16:19]
	v_mfma_f32_16x16x32_bf16 v[8:11], v[156:159], v[212:215], v[8:11]
	v_mfma_f32_16x16x32_bf16 v[0:3], v[164:167], v[212:215], v[0:3]
	v_mfma_f32_16x16x32_bf16 v[60:63], v[168:171], v[184:187], v[60:63]
	v_mfma_f32_16x16x32_bf16 v[52:55], v[176:179], v[184:187], v[52:55]
	v_mfma_f32_16x16x32_bf16 v[44:47], v[168:171], v[192:195], v[44:47]
	v_mfma_f32_16x16x32_bf16 v[36:39], v[176:179], v[192:195], v[36:39]
	v_mfma_f32_16x16x32_bf16 v[28:31], v[168:171], v[200:203], v[28:31]
	v_mfma_f32_16x16x32_bf16 v[20:23], v[176:179], v[200:203], v[20:23]
	v_mfma_f32_16x16x32_bf16 v[12:15], v[168:171], v[208:211], v[12:15]
	v_mfma_f32_16x16x32_bf16 v[4:7], v[176:179], v[208:211], v[4:7]
	v_mfma_f32_16x16x32_bf16 v[60:63], v[172:175], v[188:191], v[60:63]
	v_mfma_f32_16x16x32_bf16 v[52:55], v[180:183], v[188:191], v[52:55]
	v_mfma_f32_16x16x32_bf16 v[44:47], v[172:175], v[196:199], v[44:47]
	v_mfma_f32_16x16x32_bf16 v[36:39], v[180:183], v[196:199], v[36:39]
	v_mfma_f32_16x16x32_bf16 v[28:31], v[172:175], v[204:207], v[28:31]
	v_mfma_f32_16x16x32_bf16 v[20:23], v[180:183], v[204:207], v[20:23]
	v_mfma_f32_16x16x32_bf16 v[12:15], v[172:175], v[212:215], v[12:15]
	v_mfma_f32_16x16x32_bf16 v[4:7], v[180:183], v[212:215], v[4:7]
	s_setprio 0
	s_barrier
	s_add_i32 s68, s68, 2
	s_add_u32 s47, s47, 0x100
	s_addc_u32 s67, s67, 0
	s_add_u32 s52, s52, 0x100
	s_addc_u32 s53, s53, 0
	s_cmp_gt_u32 s68, 29
	s_cbranch_scc0 .LBB0_952
	s_and_b64 vcc, exec, s[22:23]
	s_cbranch_vccz .LBB0_955
	s_barrier

.LBB0_1049:
	ds_read_b128 v[148:151], v222
	ds_read_b128 v[152:155], v222 offset:1024
	ds_read_b128 v[156:159], v222 offset:2048
	ds_read_b128 v[160:163], v222 offset:3072
	ds_read_b128 v[132:135], v223
	ds_read_b128 v[136:139], v223 offset:1024
	ds_read_b128 v[140:143], v223 offset:2048
	ds_read_b128 v[144:147], v223 offset:3072
	s_add_u32 s8, s48, 0xfff80080
	s_addc_u32 s9, s49, -1
	s_cmp_eq_u32 s81, 28
	s_cselect_b32 s53, s23, s9
	s_cselect_b32 s52, s46, s8
	s_cselect_b32 s51, s21, s80
	s_cselect_b32 s50, s47, s79
	v_lshl_add_u64 v[2:3], s[48:49], 0, v[208:209]
	s_add_i32 m0, s35, 0xc000
	s_waitcnt lgkmcnt(0)
	ds_read_b128 v[164:167], v224
	ds_read_b128 v[168:171], v224 offset:1024
	ds_read_b128 v[172:175], v224 offset:2048
	ds_read_b128 v[176:179], v224 offset:3072
	ds_read_b128 v[180:183], v224 offset:4096
	ds_read_b128 v[184:187], v224 offset:5120
	ds_read_b128 v[188:191], v224 offset:6144
	ds_read_b128 v[192:195], v224 offset:7168
	global_load_lds_dwordx4 v[2:3], off
	v_lshl_add_u64 v[2:3], s[48:49], 0, v[206:207]
	s_add_i32 m0, s35, 0xe000
	s_nop 0
	global_load_lds_dwordx4 v[2:3], off
	s_waitcnt vmcnt(8)
	s_waitcnt lgkmcnt(0)
	s_barrier
	s_setprio 1
	v_mfma_f32_16x16x32_bf16 v[124:127], v[148:151], v[164:167], v[124:127]
	v_mfma_f32_16x16x32_bf16 v[120:123], v[156:159], v[164:167], v[120:123]
	v_mfma_f32_16x16x32_bf16 v[104:107], v[148:151], v[172:175], v[104:107]
	v_mfma_f32_16x16x32_bf16 v[100:103], v[156:159], v[172:175], v[100:103]
	v_mfma_f32_16x16x32_bf16 v[88:91], v[148:151], v[180:183], v[88:91]
	v_mfma_f32_16x16x32_bf16 v[84:87], v[156:159], v[180:183], v[84:87]
	v_mfma_f32_16x16x32_bf16 v[76:79], v[148:151], v[188:191], v[76:79]
	v_mfma_f32_16x16x32_bf16 v[72:75], v[156:159], v[188:191], v[72:75]
	v_mfma_f32_16x16x32_bf16 v[124:127], v[152:155], v[168:171], v[124:127]
	v_mfma_f32_16x16x32_bf16 v[120:123], v[160:163], v[168:171], v[120:123]
	v_mfma_f32_16x16x32_bf16 v[104:107], v[152:155], v[176:179], v[104:107]
	v_mfma_f32_16x16x32_bf16 v[100:103], v[160:163], v[176:179], v[100:103]
	v_mfma_f32_16x16x32_bf16 v[88:91], v[152:155], v[184:187], v[88:91]
	v_mfma_f32_16x16x32_bf16 v[84:87], v[160:163], v[184:187], v[84:87]
	v_mfma_f32_16x16x32_bf16 v[76:79], v[152:155], v[192:195], v[76:79]
	v_mfma_f32_16x16x32_bf16 v[72:75], v[160:163], v[192:195], v[72:75]
	v_mfma_f32_16x16x32_bf16 v[128:131], v[132:135], v[164:167], v[128:131]
	v_mfma_f32_16x16x32_bf16 v[116:119], v[140:143], v[164:167], v[116:119]
	v_mfma_f32_16x16x32_bf16 v[112:115], v[132:135], v[172:175], v[112:115]
	v_mfma_f32_16x16x32_bf16 v[108:111], v[140:143], v[172:175], v[108:111]
	v_mfma_f32_16x16x32_bf16 v[96:99], v[132:135], v[180:183], v[96:99]
	v_mfma_f32_16x16x32_bf16 v[92:95], v[140:143], v[180:183], v[92:95]
	v_mfma_f32_16x16x32_bf16 v[80:83], v[132:135], v[188:191], v[80:83]
	v_mfma_f32_16x16x32_bf16 v[68:71], v[140:143], v[188:191], v[68:71]
	v_mfma_f32_16x16x32_bf16 v[128:131], v[136:139], v[168:171], v[128:131]
	v_mfma_f32_16x16x32_bf16 v[116:119], v[144:147], v[168:171], v[116:119]
	v_mfma_f32_16x16x32_bf16 v[112:115], v[136:139], v[176:179], v[112:115]
	v_mfma_f32_16x16x32_bf16 v[108:111], v[144:147], v[176:179], v[108:111]
	v_mfma_f32_16x16x32_bf16 v[96:99], v[136:139], v[184:187], v[96:99]
	v_mfma_f32_16x16x32_bf16 v[92:95], v[144:147], v[184:187], v[92:95]
	v_mfma_f32_16x16x32_bf16 v[80:83], v[136:139], v[192:195], v[80:83]
	v_mfma_f32_16x16x32_bf16 v[68:71], v[144:147], v[192:195], v[68:71]
	s_setprio 0
	s_barrier
	s_add_i32 s8, s65, s56
	v_lshl_add_u64 v[2:3], s[50:51], 0, v[198:199]
	s_mov_b32 m0, s8
	ds_read_b128 v[188:191], v224 offset:16384
	ds_read_b128 v[192:195], v224 offset:17408
	ds_read_b128 v[180:183], v224 offset:18432
	ds_read_b128 v[184:187], v224 offset:19456
	ds_read_b128 v[172:175], v224 offset:20480
	ds_read_b128 v[176:179], v224 offset:21504
	ds_read_b128 v[164:167], v224 offset:22528
	ds_read_b128 v[168:171], v224 offset:23552
	global_load_lds_dwordx4 v[2:3], off
	s_add_i32 m0, s8, 0x2000
	s_add_u32 s8, s50, 0x80000
	v_lshl_add_u64 v[212:213], s[50:51], 0, v[202:203]
	s_addc_u32 s9, s51, 0
	s_add_i32 s78, s66, s56
	global_load_lds_dwordx4 v[212:213], off
	v_lshl_add_u64 v[214:215], s[8:9], 0, v[198:199]
	s_mov_b32 m0, s78
	v_lshl_add_u64 v[216:217], s[52:53], 0, v[200:201]
	global_load_lds_dwordx4 v[214:215], off
	v_lshl_add_u64 v[214:215], s[8:9], 0, v[202:203]
	s_add_i32 m0, s78, 0x2000
	v_cmp_ne_u32_e64 s[8:9], 1, v227
	global_load_lds_dwordx4 v[214:215], off
	v_lshl_add_u64 v[214:215], s[52:53], 0, v[196:197]
	s_mov_b32 m0, s35
	s_andn2_b64 vcc, exec, s[36:37]
	global_load_lds_dwordx4 v[214:215], off
	s_mov_b32 m0, s58
	s_nop 0
	global_load_lds_dwordx4 v[216:217], off
	s_waitcnt vmcnt(8)
	s_waitcnt lgkmcnt(0)
	s_barrier
	s_cbranch_vccnz .LBB0_1051
	s_setprio 1
	v_mfma_f32_16x16x32_bf16 v[56:59], v[148:151], v[188:191], v[56:59]
	v_mfma_f32_16x16x32_bf16 v[52:55], v[156:159], v[188:191], v[52:55]
	v_mfma_f32_16x16x32_bf16 v[40:43], v[148:151], v[180:183], v[40:43]
	v_mfma_f32_16x16x32_bf16 v[36:39], v[156:159], v[180:183], v[36:39]
	v_mfma_f32_16x16x32_bf16 v[24:27], v[148:151], v[172:175], v[24:27]
	v_mfma_f32_16x16x32_bf16 v[20:23], v[156:159], v[172:175], v[20:23]
	v_mfma_f32_16x16x32_bf16 v[8:11], v[148:151], v[164:167], v[8:11]
	v_mfma_f32_16x16x32_bf16 v[4:7], v[156:159], v[164:167], v[4:7]
	v_mfma_f32_16x16x32_bf16 v[56:59], v[152:155], v[192:195], v[56:59]
	v_mfma_f32_16x16x32_bf16 v[52:55], v[160:163], v[192:195], v[52:55]
	v_mfma_f32_16x16x32_bf16 v[40:43], v[152:155], v[184:187], v[40:43]
	v_mfma_f32_16x16x32_bf16 v[36:39], v[160:163], v[184:187], v[36:39]
	v_mfma_f32_16x16x32_bf16 v[24:27], v[152:155], v[176:179], v[24:27]
	v_mfma_f32_16x16x32_bf16 v[20:23], v[160:163], v[176:179], v[20:23]
	v_mfma_f32_16x16x32_bf16 v[8:11], v[152:155], v[168:171], v[8:11]
	v_mfma_f32_16x16x32_bf16 v[4:7], v[160:163], v[168:171], v[4:7]
	v_mfma_f32_16x16x32_bf16 v[64:67], v[132:135], v[188:191], v[64:67]
	v_mfma_f32_16x16x32_bf16 v[60:63], v[140:143], v[188:191], v[60:63]
	v_mfma_f32_16x16x32_bf16 v[48:51], v[132:135], v[180:183], v[48:51]
	v_mfma_f32_16x16x32_bf16 v[44:47], v[140:143], v[180:183], v[44:47]
	v_mfma_f32_16x16x32_bf16 v[32:35], v[132:135], v[172:175], v[32:35]
	v_mfma_f32_16x16x32_bf16 v[28:31], v[140:143], v[172:175], v[28:31]
	v_mfma_f32_16x16x32_bf16 v[16:19], v[132:135], v[164:167], v[16:19]
	v_mfma_f32_16x16x32_bf16 v[12:15], v[140:143], v[164:167], v[12:15]
	v_mfma_f32_16x16x32_bf16 v[64:67], v[136:139], v[192:195], v[64:67]
	v_mfma_f32_16x16x32_bf16 v[60:63], v[144:147], v[192:195], v[60:63]
	v_mfma_f32_16x16x32_bf16 v[48:51], v[136:139], v[184:187], v[48:51]
	v_mfma_f32_16x16x32_bf16 v[44:47], v[144:147], v[184:187], v[44:47]
	v_mfma_f32_16x16x32_bf16 v[32:35], v[136:139], v[176:179], v[32:35]
	v_mfma_f32_16x16x32_bf16 v[28:31], v[144:147], v[176:179], v[28:31]
	v_mfma_f32_16x16x32_bf16 v[16:19], v[136:139], v[168:171], v[16:19]
	v_mfma_f32_16x16x32_bf16 v[12:15], v[144:147], v[168:171], v[12:15]
	s_setprio 0
.LBB0_1051:
	s_barrier
	s_add_i32 s78, 0, 0x18000
	v_add_u32_e32 v1, s78, v220
	s_add_i32 s82, 0, 0x1c000
	ds_read_b128 v[148:151], v1
	ds_read_b128 v[152:155], v1 offset:1024
	ds_read_b128 v[156:159], v1 offset:2048
	ds_read_b128 v[160:163], v1 offset:3072
	v_add_u32_e32 v1, s82, v220
	ds_read_b128 v[132:135], v1
	ds_read_b128 v[136:139], v1 offset:1024
	ds_read_b128 v[140:143], v1 offset:2048
	ds_read_b128 v[144:147], v1 offset:3072
	s_add_u32 s52, s52, 0x80000
	s_addc_u32 s53, s53, 0
	s_mov_b32 m0, s59
	v_lshl_add_u64 v[228:229], s[52:53], 0, v[196:197]
	s_waitcnt lgkmcnt(0)
	ds_read_b128 v[164:167], v224 offset:32768
	ds_read_b128 v[168:171], v224 offset:33792
	ds_read_b128 v[172:175], v224 offset:34816
	ds_read_b128 v[176:179], v224 offset:35840
	ds_read_b128 v[180:183], v224 offset:36864
	ds_read_b128 v[184:187], v224 offset:37888
	ds_read_b128 v[188:191], v224 offset:38912
	ds_read_b128 v[192:195], v224 offset:39936
	global_load_lds_dwordx4 v[228:229], off
	v_lshl_add_u64 v[228:229], s[52:53], 0, v[200:201]
	s_mov_b32 m0, s60
	s_nop 0
	global_load_lds_dwordx4 v[228:229], off
	s_waitcnt vmcnt(8)
	s_waitcnt lgkmcnt(0)
	s_barrier
	s_setprio 1
	v_mfma_f32_16x16x32_bf16 v[124:127], v[148:151], v[164:167], v[124:127]
	v_mfma_f32_16x16x32_bf16 v[120:123], v[156:159], v[164:167], v[120:123]
	v_mfma_f32_16x16x32_bf16 v[104:107], v[148:151], v[172:175], v[104:107]
	v_mfma_f32_16x16x32_bf16 v[100:103], v[156:159], v[172:175], v[100:103]
	v_mfma_f32_16x16x32_bf16 v[88:91], v[148:151], v[180:183], v[88:91]
	v_mfma_f32_16x16x32_bf16 v[84:87], v[156:159], v[180:183], v[84:87]
	v_mfma_f32_16x16x32_bf16 v[76:79], v[148:151], v[188:191], v[76:79]
	v_mfma_f32_16x16x32_bf16 v[72:75], v[156:159], v[188:191], v[72:75]
	v_mfma_f32_16x16x32_bf16 v[124:127], v[152:155], v[168:171], v[124:127]
	v_mfma_f32_16x16x32_bf16 v[120:123], v[160:163], v[168:171], v[120:123]
	v_mfma_f32_16x16x32_bf16 v[104:107], v[152:155], v[176:179], v[104:107]
	v_mfma_f32_16x16x32_bf16 v[100:103], v[160:163], v[176:179], v[100:103]
	v_mfma_f32_16x16x32_bf16 v[88:91], v[152:155], v[184:187], v[88:91]
	v_mfma_f32_16x16x32_bf16 v[84:87], v[160:163], v[184:187], v[84:87]
	v_mfma_f32_16x16x32_bf16 v[76:79], v[152:155], v[192:195], v[76:79]
	v_mfma_f32_16x16x32_bf16 v[72:75], v[160:163], v[192:195], v[72:75]
	v_mfma_f32_16x16x32_bf16 v[128:131], v[132:135], v[164:167], v[128:131]
	v_mfma_f32_16x16x32_bf16 v[116:119], v[140:143], v[164:167], v[116:119]
	v_mfma_f32_16x16x32_bf16 v[112:115], v[132:135], v[172:175], v[112:115]
	v_mfma_f32_16x16x32_bf16 v[108:111], v[140:143], v[172:175], v[108:111]
	v_mfma_f32_16x16x32_bf16 v[96:99], v[132:135], v[180:183], v[96:99]
	v_mfma_f32_16x16x32_bf16 v[92:95], v[140:143], v[180:183], v[92:95]
	v_mfma_f32_16x16x32_bf16 v[80:83], v[132:135], v[188:191], v[80:83]
	v_mfma_f32_16x16x32_bf16 v[68:71], v[140:143], v[188:191], v[68:71]
	v_mfma_f32_16x16x32_bf16 v[128:131], v[136:139], v[168:171], v[128:131]
	v_mfma_f32_16x16x32_bf16 v[116:119], v[144:147], v[168:171], v[116:119]
	v_mfma_f32_16x16x32_bf16 v[112:115], v[136:139], v[176:179], v[112:115]
	v_mfma_f32_16x16x32_bf16 v[108:111], v[144:147], v[176:179], v[108:111]
	v_mfma_f32_16x16x32_bf16 v[96:99], v[136:139], v[184:187], v[96:99]
	v_mfma_f32_16x16x32_bf16 v[92:95], v[144:147], v[184:187], v[92:95]
	v_mfma_f32_16x16x32_bf16 v[80:83], v[136:139], v[192:195], v[80:83]
	v_mfma_f32_16x16x32_bf16 v[68:71], v[144:147], v[192:195], v[68:71]
	s_setprio 0
	s_barrier
	s_add_i32 s52, s78, s56
	v_lshl_add_u64 v[2:3], v[2:3], 0, s[14:15]
	s_mov_b32 m0, s52
	ds_read_b128 v[188:191], v224 offset:49152
	ds_read_b128 v[192:195], v224 offset:50176
	ds_read_b128 v[180:183], v224 offset:51200
	ds_read_b128 v[184:187], v224 offset:52224
	ds_read_b128 v[172:175], v224 offset:53248
	ds_read_b128 v[176:179], v224 offset:54272
	ds_read_b128 v[164:167], v224 offset:55296
	ds_read_b128 v[168:171], v224 offset:56320
	global_load_lds_dwordx4 v[2:3], off
	s_add_i32 m0, s52, 0x2000
	s_add_u32 s50, s50, 0x80080
	v_lshl_add_u64 v[2:3], v[212:213], 0, s[14:15]
	s_addc_u32 s51, s51, 0
	s_add_i32 s52, s82, s56
	global_load_lds_dwordx4 v[2:3], off
	v_lshl_add_u64 v[2:3], s[50:51], 0, v[198:199]
	s_mov_b32 m0, s52
	s_and_b64 vcc, exec, s[8:9]
	global_load_lds_dwordx4 v[2:3], off
	v_lshl_add_u64 v[2:3], s[50:51], 0, v[202:203]
	s_add_i32 m0, s52, 0x2000
	s_nop 0
	global_load_lds_dwordx4 v[2:3], off
	v_lshl_add_u64 v[2:3], v[214:215], 0, s[14:15]
	s_mov_b32 m0, s61
	s_nop 0
	global_load_lds_dwordx4 v[2:3], off
	v_lshl_add_u64 v[2:3], v[216:217], 0, s[14:15]
	s_mov_b32 m0, s62
	s_nop 0
	global_load_lds_dwordx4 v[2:3], off
	s_waitcnt vmcnt(8)
	s_waitcnt lgkmcnt(0)
	s_barrier
	s_cbranch_vccnz .LBB0_1048
	s_setprio 1
	v_mfma_f32_16x16x32_bf16 v[56:59], v[148:151], v[188:191], v[56:59]
	v_mfma_f32_16x16x32_bf16 v[52:55], v[156:159], v[188:191], v[52:55]
	v_mfma_f32_16x16x32_bf16 v[40:43], v[148:151], v[180:183], v[40:43]
	v_mfma_f32_16x16x32_bf16 v[36:39], v[156:159], v[180:183], v[36:39]
	v_mfma_f32_16x16x32_bf16 v[24:27], v[148:151], v[172:175], v[24:27]
	v_mfma_f32_16x16x32_bf16 v[20:23], v[156:159], v[172:175], v[20:23]
	v_mfma_f32_16x16x32_bf16 v[8:11], v[148:151], v[164:167], v[8:11]
	v_mfma_f32_16x16x32_bf16 v[2:5], v[156:159], v[164:167], v[4:7]
	v_mfma_f32_16x16x32_bf16 v[56:59], v[152:155], v[192:195], v[56:59]
	v_mfma_f32_16x16x32_bf16 v[52:55], v[160:163], v[192:195], v[52:55]
	v_mfma_f32_16x16x32_bf16 v[40:43], v[152:155], v[184:187], v[40:43]
	v_mfma_f32_16x16x32_bf16 v[36:39], v[160:163], v[184:187], v[36:39]
	v_mfma_f32_16x16x32_bf16 v[24:27], v[152:155], v[176:179], v[24:27]
	v_mfma_f32_16x16x32_bf16 v[20:23], v[160:163], v[176:179], v[20:23]
	v_mfma_f32_16x16x32_bf16 v[8:11], v[152:155], v[168:171], v[8:11]
	v_mfma_f32_16x16x32_bf16 v[4:7], v[160:163], v[168:171], v[2:5]
	v_mfma_f32_16x16x32_bf16 v[64:67], v[132:135], v[188:191], v[64:67]
	v_mfma_f32_16x16x32_bf16 v[60:63], v[140:143], v[188:191], v[60:63]
	v_mfma_f32_16x16x32_bf16 v[48:51], v[132:135], v[180:183], v[48:51]
	v_mfma_f32_16x16x32_bf16 v[44:47], v[140:143], v[180:183], v[44:47]
	v_mfma_f32_16x16x32_bf16 v[32:35], v[132:135], v[172:175], v[32:35]
	v_mfma_f32_16x16x32_bf16 v[28:31], v[140:143], v[172:175], v[28:31]
	v_mfma_f32_16x16x32_bf16 v[16:19], v[132:135], v[164:167], v[16:19]
	v_mfma_f32_16x16x32_bf16 v[12:15], v[140:143], v[164:167], v[12:15]
	v_mfma_f32_16x16x32_bf16 v[64:67], v[136:139], v[192:195], v[64:67]
	v_mfma_f32_16x16x32_bf16 v[60:63], v[144:147], v[192:195], v[60:63]
	v_mfma_f32_16x16x32_bf16 v[48:51], v[136:139], v[184:187], v[48:51]
	v_mfma_f32_16x16x32_bf16 v[44:47], v[144:147], v[184:187], v[44:47]
	v_mfma_f32_16x16x32_bf16 v[32:35], v[136:139], v[176:179], v[32:35]
	v_mfma_f32_16x16x32_bf16 v[28:31], v[144:147], v[176:179], v[28:31]
	v_mfma_f32_16x16x32_bf16 v[16:19], v[136:139], v[168:171], v[16:19]
	v_mfma_f32_16x16x32_bf16 v[12:15], v[144:147], v[168:171], v[12:15]
	s_setprio 0
	s_branch .LBB0_1048

.LBB0_1137:
	ds_read_b128 v[144:147], v151
	ds_read_b128 v[156:159], v151 offset:1024
	ds_read_b128 v[160:163], v151 offset:2048
	ds_read_b128 v[164:167], v151 offset:3072
	ds_read_b128 v[168:171], v152
	ds_read_b128 v[172:175], v152 offset:1024
	ds_read_b128 v[176:179], v152 offset:2048
	ds_read_b128 v[180:183], v152 offset:3072
	s_add_u32 s34, s30, 0x100
	s_addc_u32 s35, s31, 0
	s_cmpk_eq_i32 s66, 0x54
	s_cselect_b32 s49, s11, s35
	s_cselect_b32 s48, s10, s34
	s_cselect_b32 s37, s27, s47
	s_cselect_b32 s36, s26, s46
	v_lshl_add_u64 v[216:217], s[30:31], 0, v[138:139]
	s_add_i32 m0, s53, 0xc000
	ds_read_b128 v[184:187], v153
	ds_read_b128 v[188:191], v153 offset:1024
	ds_read_b128 v[192:195], v153 offset:2048
	ds_read_b128 v[196:199], v153 offset:3072
	ds_read_b128 v[200:203], v153 offset:4096
	ds_read_b128 v[204:207], v153 offset:5120
	ds_read_b128 v[208:211], v153 offset:6144
	ds_read_b128 v[212:215], v153 offset:7168
	global_load_lds_dwordx4 v[216:217], off
	v_lshl_add_u64 v[216:217], s[30:31], 0, v[136:137]
	s_add_i32 m0, s53, 0xe000
	s_nop 0
	global_load_lds_dwordx4 v[216:217], off
	s_waitcnt vmcnt(8)
	s_waitcnt lgkmcnt(0)
	s_barrier
	s_setprio 1
	v_mfma_f32_16x16x32_bf16 v[124:127], v[144:147], v[184:187], v[124:127]
	v_mfma_f32_16x16x32_bf16 v[120:123], v[160:163], v[184:187], v[120:123]
	v_mfma_f32_16x16x32_bf16 v[108:111], v[144:147], v[192:195], v[108:111]
	v_mfma_f32_16x16x32_bf16 v[104:107], v[160:163], v[192:195], v[104:107]
	v_mfma_f32_16x16x32_bf16 v[92:95], v[144:147], v[200:203], v[92:95]
	v_mfma_f32_16x16x32_bf16 v[88:91], v[160:163], v[200:203], v[88:91]
	v_mfma_f32_16x16x32_bf16 v[76:79], v[144:147], v[208:211], v[76:79]
	v_mfma_f32_16x16x32_bf16 v[72:75], v[160:163], v[208:211], v[72:75]
	v_mfma_f32_16x16x32_bf16 v[124:127], v[156:159], v[188:191], v[124:127]
	v_mfma_f32_16x16x32_bf16 v[120:123], v[164:167], v[188:191], v[120:123]
	v_mfma_f32_16x16x32_bf16 v[108:111], v[156:159], v[196:199], v[108:111]
	v_mfma_f32_16x16x32_bf16 v[104:107], v[164:167], v[196:199], v[104:107]
	v_mfma_f32_16x16x32_bf16 v[92:95], v[156:159], v[204:207], v[92:95]
	v_mfma_f32_16x16x32_bf16 v[88:91], v[164:167], v[204:207], v[88:91]
	v_mfma_f32_16x16x32_bf16 v[76:79], v[156:159], v[212:215], v[76:79]
	v_mfma_f32_16x16x32_bf16 v[72:75], v[164:167], v[212:215], v[72:75]
	v_mfma_f32_16x16x32_bf16 v[116:119], v[168:171], v[184:187], v[116:119]
	v_mfma_f32_16x16x32_bf16 v[112:115], v[176:179], v[184:187], v[112:115]
	v_mfma_f32_16x16x32_bf16 v[100:103], v[168:171], v[192:195], v[100:103]
	v_mfma_f32_16x16x32_bf16 v[96:99], v[176:179], v[192:195], v[96:99]
	v_mfma_f32_16x16x32_bf16 v[84:87], v[168:171], v[200:203], v[84:87]
	v_mfma_f32_16x16x32_bf16 v[80:83], v[176:179], v[200:203], v[80:83]
	v_mfma_f32_16x16x32_bf16 v[68:71], v[168:171], v[208:211], v[68:71]
	v_mfma_f32_16x16x32_bf16 v[64:67], v[176:179], v[208:211], v[64:67]
	v_mfma_f32_16x16x32_bf16 v[116:119], v[172:175], v[188:191], v[116:119]
	v_mfma_f32_16x16x32_bf16 v[112:115], v[180:183], v[188:191], v[112:115]
	v_mfma_f32_16x16x32_bf16 v[100:103], v[172:175], v[196:199], v[100:103]
	v_mfma_f32_16x16x32_bf16 v[96:99], v[180:183], v[196:199], v[96:99]
	v_mfma_f32_16x16x32_bf16 v[84:87], v[172:175], v[204:207], v[84:87]
	v_mfma_f32_16x16x32_bf16 v[80:83], v[180:183], v[204:207], v[80:83]
	v_mfma_f32_16x16x32_bf16 v[68:71], v[172:175], v[212:215], v[68:71]
	v_mfma_f32_16x16x32_bf16 v[64:67], v[180:183], v[212:215], v[64:67]
	s_setprio 0
	s_barrier
	s_add_i32 s30, s60, s52
	v_lshl_add_u64 v[216:217], s[36:37], 0, v[130:131]
	s_mov_b32 m0, s30
	ds_read_b128 v[184:187], v153 offset:16384
	ds_read_b128 v[188:191], v153 offset:17408
	ds_read_b128 v[192:195], v153 offset:18432
	ds_read_b128 v[196:199], v153 offset:19456
	ds_read_b128 v[200:203], v153 offset:20480
	ds_read_b128 v[204:207], v153 offset:21504
	ds_read_b128 v[208:211], v153 offset:22528
	ds_read_b128 v[212:215], v153 offset:23552
	global_load_lds_dwordx4 v[216:217], off
	s_add_i32 m0, s30, 0x2000
	s_add_u32 s30, s36, 0x160000
	v_lshl_add_u64 v[218:219], s[36:37], 0, v[134:135]
	s_addc_u32 s31, s37, 0
	s_add_i32 s67, s61, s52
	global_load_lds_dwordx4 v[218:219], off
	v_lshl_add_u64 v[220:221], s[30:31], 0, v[130:131]
	s_mov_b32 m0, s67
	v_lshl_add_u64 v[222:223], s[48:49], 0, v[132:133]
	global_load_lds_dwordx4 v[220:221], off
	v_lshl_add_u64 v[220:221], s[30:31], 0, v[134:135]
	s_add_i32 m0, s67, 0x2000
	s_nop 0
	global_load_lds_dwordx4 v[220:221], off
	v_lshl_add_u64 v[220:221], s[48:49], 0, v[128:129]
	s_mov_b32 m0, s53
	s_nop 0
	global_load_lds_dwordx4 v[220:221], off
	s_mov_b32 m0, s54
	s_nop 0
	global_load_lds_dwordx4 v[222:223], off
	s_waitcnt vmcnt(8)
	s_waitcnt lgkmcnt(0)
	s_barrier
	s_setprio 1
	v_mfma_f32_16x16x32_bf16 v[60:63], v[144:147], v[184:187], v[60:63]
	v_mfma_f32_16x16x32_bf16 v[56:59], v[160:163], v[184:187], v[56:59]
	v_mfma_f32_16x16x32_bf16 v[44:47], v[144:147], v[192:195], v[44:47]
	v_mfma_f32_16x16x32_bf16 v[40:43], v[160:163], v[192:195], v[40:43]
	v_mfma_f32_16x16x32_bf16 v[28:31], v[144:147], v[200:203], v[28:31]
	v_mfma_f32_16x16x32_bf16 v[24:27], v[160:163], v[200:203], v[24:27]
	v_mfma_f32_16x16x32_bf16 v[12:15], v[144:147], v[208:211], v[12:15]
	v_mfma_f32_16x16x32_bf16 v[8:11], v[160:163], v[208:211], v[8:11]
	v_mfma_f32_16x16x32_bf16 v[60:63], v[156:159], v[188:191], v[60:63]
	v_mfma_f32_16x16x32_bf16 v[56:59], v[164:167], v[188:191], v[56:59]
	v_mfma_f32_16x16x32_bf16 v[44:47], v[156:159], v[196:199], v[44:47]
	v_mfma_f32_16x16x32_bf16 v[40:43], v[164:167], v[196:199], v[40:43]
	v_mfma_f32_16x16x32_bf16 v[28:31], v[156:159], v[204:207], v[28:31]
	v_mfma_f32_16x16x32_bf16 v[24:27], v[164:167], v[204:207], v[24:27]
	v_mfma_f32_16x16x32_bf16 v[12:15], v[156:159], v[212:215], v[12:15]
	v_mfma_f32_16x16x32_bf16 v[8:11], v[164:167], v[212:215], v[8:11]
	v_mfma_f32_16x16x32_bf16 v[52:55], v[168:171], v[184:187], v[52:55]
	v_mfma_f32_16x16x32_bf16 v[48:51], v[176:179], v[184:187], v[48:51]
	v_mfma_f32_16x16x32_bf16 v[36:39], v[168:171], v[192:195], v[36:39]
	v_mfma_f32_16x16x32_bf16 v[32:35], v[176:179], v[192:195], v[32:35]
	v_mfma_f32_16x16x32_bf16 v[20:23], v[168:171], v[200:203], v[20:23]
	v_mfma_f32_16x16x32_bf16 v[16:19], v[176:179], v[200:203], v[16:19]
	v_mfma_f32_16x16x32_bf16 v[4:7], v[168:171], v[208:211], v[4:7]
	v_mfma_f32_16x16x32_bf16 v[0:3], v[176:179], v[208:211], v[0:3]
	v_mfma_f32_16x16x32_bf16 v[52:55], v[172:175], v[188:191], v[52:55]
	v_mfma_f32_16x16x32_bf16 v[48:51], v[180:183], v[188:191], v[48:51]
	v_mfma_f32_16x16x32_bf16 v[36:39], v[172:175], v[196:199], v[36:39]
	v_mfma_f32_16x16x32_bf16 v[32:35], v[180:183], v[196:199], v[32:35]
	v_mfma_f32_16x16x32_bf16 v[20:23], v[172:175], v[204:207], v[20:23]
	v_mfma_f32_16x16x32_bf16 v[16:19], v[180:183], v[204:207], v[16:19]
	v_mfma_f32_16x16x32_bf16 v[4:7], v[172:175], v[212:215], v[4:7]
	v_mfma_f32_16x16x32_bf16 v[0:3], v[180:183], v[212:215], v[0:3]
	s_setprio 0
	s_barrier
	s_add_i32 s67, 0, 0x18000
	v_add_u32_e32 v155, s67, v149
	s_add_i32 s68, 0, 0x1c000
	ds_read_b128 v[144:147], v155
	ds_read_b128 v[156:159], v155 offset:1024
	ds_read_b128 v[160:163], v155 offset:2048
	ds_read_b128 v[164:167], v155 offset:3072
	v_add_u32_e32 v155, s68, v149
	ds_read_b128 v[168:171], v155
	ds_read_b128 v[172:175], v155 offset:1024
	ds_read_b128 v[176:179], v155 offset:2048
	ds_read_b128 v[180:183], v155 offset:3072
	s_add_u32 s30, s48, 0x160000
	s_addc_u32 s31, s49, 0
	s_mov_b32 m0, s55
	v_lshl_add_u64 v[224:225], s[30:31], 0, v[128:129]
	ds_read_b128 v[184:187], v153 offset:32768
	ds_read_b128 v[188:191], v153 offset:33792
	ds_read_b128 v[192:195], v153 offset:34816
	ds_read_b128 v[196:199], v153 offset:35840
	ds_read_b128 v[200:203], v153 offset:36864
	ds_read_b128 v[204:207], v153 offset:37888
	ds_read_b128 v[208:211], v153 offset:38912
	ds_read_b128 v[212:215], v153 offset:39936
	global_load_lds_dwordx4 v[224:225], off
	v_lshl_add_u64 v[224:225], s[30:31], 0, v[132:133]
	s_mov_b32 m0, s56
	s_nop 0
	global_load_lds_dwordx4 v[224:225], off
	s_waitcnt vmcnt(8)
	s_waitcnt lgkmcnt(0)
	s_barrier
	s_setprio 1
	v_mfma_f32_16x16x32_bf16 v[124:127], v[144:147], v[184:187], v[124:127]
	v_mfma_f32_16x16x32_bf16 v[120:123], v[160:163], v[184:187], v[120:123]
	v_mfma_f32_16x16x32_bf16 v[108:111], v[144:147], v[192:195], v[108:111]
	v_mfma_f32_16x16x32_bf16 v[104:107], v[160:163], v[192:195], v[104:107]
	v_mfma_f32_16x16x32_bf16 v[92:95], v[144:147], v[200:203], v[92:95]
	v_mfma_f32_16x16x32_bf16 v[88:91], v[160:163], v[200:203], v[88:91]
	v_mfma_f32_16x16x32_bf16 v[76:79], v[144:147], v[208:211], v[76:79]
	v_mfma_f32_16x16x32_bf16 v[72:75], v[160:163], v[208:211], v[72:75]
	v_mfma_f32_16x16x32_bf16 v[124:127], v[156:159], v[188:191], v[124:127]
	v_mfma_f32_16x16x32_bf16 v[120:123], v[164:167], v[188:191], v[120:123]
	v_mfma_f32_16x16x32_bf16 v[108:111], v[156:159], v[196:199], v[108:111]
	v_mfma_f32_16x16x32_bf16 v[104:107], v[164:167], v[196:199], v[104:107]
	v_mfma_f32_16x16x32_bf16 v[92:95], v[156:159], v[204:207], v[92:95]
	v_mfma_f32_16x16x32_bf16 v[88:91], v[164:167], v[204:207], v[88:91]
	v_mfma_f32_16x16x32_bf16 v[76:79], v[156:159], v[212:215], v[76:79]
	v_mfma_f32_16x16x32_bf16 v[72:75], v[164:167], v[212:215], v[72:75]
	v_mfma_f32_16x16x32_bf16 v[116:119], v[168:171], v[184:187], v[116:119]
	v_mfma_f32_16x16x32_bf16 v[112:115], v[176:179], v[184:187], v[112:115]
	v_mfma_f32_16x16x32_bf16 v[100:103], v[168:171], v[192:195], v[100:103]
	v_mfma_f32_16x16x32_bf16 v[96:99], v[176:179], v[192:195], v[96:99]
	v_mfma_f32_16x16x32_bf16 v[84:87], v[168:171], v[200:203], v[84:87]
	v_mfma_f32_16x16x32_bf16 v[80:83], v[176:179], v[200:203], v[80:83]
	v_mfma_f32_16x16x32_bf16 v[68:71], v[168:171], v[208:211], v[68:71]
	v_mfma_f32_16x16x32_bf16 v[64:67], v[176:179], v[208:211], v[64:67]
	v_mfma_f32_16x16x32_bf16 v[116:119], v[172:175], v[188:191], v[116:119]
	v_mfma_f32_16x16x32_bf16 v[112:115], v[180:183], v[188:191], v[112:115]
	v_mfma_f32_16x16x32_bf16 v[100:103], v[172:175], v[196:199], v[100:103]
	v_mfma_f32_16x16x32_bf16 v[96:99], v[180:183], v[196:199], v[96:99]
	v_mfma_f32_16x16x32_bf16 v[84:87], v[172:175], v[204:207], v[84:87]
	v_mfma_f32_16x16x32_bf16 v[80:83], v[180:183], v[204:207], v[80:83]
	v_mfma_f32_16x16x32_bf16 v[68:71], v[172:175], v[212:215], v[68:71]
	v_mfma_f32_16x16x32_bf16 v[64:67], v[180:183], v[212:215], v[64:67]
	s_setprio 0
	s_barrier
	s_add_i32 s30, s67, s52
	v_lshl_add_u64 v[216:217], v[216:217], 0, s[22:23]
	s_mov_b32 m0, s30
	ds_read_b128 v[184:187], v153 offset:49152
	ds_read_b128 v[188:191], v153 offset:50176
	ds_read_b128 v[192:195], v153 offset:51200
	ds_read_b128 v[196:199], v153 offset:52224
	ds_read_b128 v[200:203], v153 offset:53248
	ds_read_b128 v[204:207], v153 offset:54272
	ds_read_b128 v[208:211], v153 offset:55296
	ds_read_b128 v[212:215], v153 offset:56320
	global_load_lds_dwordx4 v[216:217], off
	s_add_i32 m0, s30, 0x2000
	s_add_u32 s30, s36, 0x160080
	v_lshl_add_u64 v[216:217], v[218:219], 0, s[22:23]
	s_addc_u32 s31, s37, 0
	s_add_i32 s36, s68, s52
	global_load_lds_dwordx4 v[216:217], off
	v_lshl_add_u64 v[216:217], s[30:31], 0, v[130:131]
	s_mov_b32 m0, s36
	s_nop 0
	global_load_lds_dwordx4 v[216:217], off
	v_lshl_add_u64 v[216:217], s[30:31], 0, v[134:135]
	s_add_i32 m0, s36, 0x2000
	s_nop 0
	global_load_lds_dwordx4 v[216:217], off
	v_lshl_add_u64 v[216:217], v[220:221], 0, s[22:23]
	s_mov_b32 m0, s58
	s_nop 0
	global_load_lds_dwordx4 v[216:217], off
	v_lshl_add_u64 v[216:217], v[222:223], 0, s[22:23]
	s_mov_b32 m0, s59
	s_nop 0
	global_load_lds_dwordx4 v[216:217], off
	s_waitcnt vmcnt(8)
	s_waitcnt lgkmcnt(0)
	s_barrier
	s_setprio 1
	v_mfma_f32_16x16x32_bf16 v[60:63], v[144:147], v[184:187], v[60:63]
	v_mfma_f32_16x16x32_bf16 v[56:59], v[160:163], v[184:187], v[56:59]
	v_mfma_f32_16x16x32_bf16 v[44:47], v[144:147], v[192:195], v[44:47]
	v_mfma_f32_16x16x32_bf16 v[40:43], v[160:163], v[192:195], v[40:43]
	v_mfma_f32_16x16x32_bf16 v[28:31], v[144:147], v[200:203], v[28:31]
	v_mfma_f32_16x16x32_bf16 v[24:27], v[160:163], v[200:203], v[24:27]
	v_mfma_f32_16x16x32_bf16 v[12:15], v[144:147], v[208:211], v[12:15]
	v_mfma_f32_16x16x32_bf16 v[8:11], v[160:163], v[208:211], v[8:11]
	v_mfma_f32_16x16x32_bf16 v[60:63], v[156:159], v[188:191], v[60:63]
	v_mfma_f32_16x16x32_bf16 v[56:59], v[164:167], v[188:191], v[56:59]
	v_mfma_f32_16x16x32_bf16 v[44:47], v[156:159], v[196:199], v[44:47]
	v_mfma_f32_16x16x32_bf16 v[40:43], v[164:167], v[196:199], v[40:43]
	v_mfma_f32_16x16x32_bf16 v[28:31], v[156:159], v[204:207], v[28:31]
	v_mfma_f32_16x16x32_bf16 v[24:27], v[164:167], v[204:207], v[24:27]
	v_mfma_f32_16x16x32_bf16 v[12:15], v[156:159], v[212:215], v[12:15]
	v_mfma_f32_16x16x32_bf16 v[8:11], v[164:167], v[212:215], v[8:11]
	v_mfma_f32_16x16x32_bf16 v[52:55], v[168:171], v[184:187], v[52:55]
	v_mfma_f32_16x16x32_bf16 v[48:51], v[176:179], v[184:187], v[48:51]
	v_mfma_f32_16x16x32_bf16 v[36:39], v[168:171], v[192:195], v[36:39]
	v_mfma_f32_16x16x32_bf16 v[32:35], v[176:179], v[192:195], v[32:35]
	v_mfma_f32_16x16x32_bf16 v[20:23], v[168:171], v[200:203], v[20:23]
	v_mfma_f32_16x16x32_bf16 v[16:19], v[176:179], v[200:203], v[16:19]
	v_mfma_f32_16x16x32_bf16 v[4:7], v[168:171], v[208:211], v[4:7]
	v_mfma_f32_16x16x32_bf16 v[0:3], v[176:179], v[208:211], v[0:3]
	v_mfma_f32_16x16x32_bf16 v[52:55], v[172:175], v[188:191], v[52:55]
	v_mfma_f32_16x16x32_bf16 v[48:51], v[180:183], v[188:191], v[48:51]
	v_mfma_f32_16x16x32_bf16 v[36:39], v[172:175], v[196:199], v[36:39]
	v_mfma_f32_16x16x32_bf16 v[32:35], v[180:183], v[196:199], v[32:35]
	v_mfma_f32_16x16x32_bf16 v[20:23], v[172:175], v[204:207], v[20:23]
	v_mfma_f32_16x16x32_bf16 v[16:19], v[180:183], v[204:207], v[16:19]
	v_mfma_f32_16x16x32_bf16 v[4:7], v[172:175], v[212:215], v[4:7]
	v_mfma_f32_16x16x32_bf16 v[0:3], v[180:183], v[212:215], v[0:3]
	s_setprio 0
	s_barrier
	s_add_i32 s66, s66, 2
	s_add_u32 s46, s46, 0x100
	s_addc_u32 s47, s47, 0
	s_cmpk_gt_u32 s66, 0x55
	s_mov_b64 s[30:31], s[34:35]
	s_cbranch_scc0 .LBB0_1137
	s_and_b64 vcc, exec, s[24:25]
	s_cbranch_vccz .LBB0_1140
	s_barrier

.LBB0_1227:
	v_add_u32_e32 v164, s56, v150
	v_add_u32_e32 v180, s57, v150
	s_add_u32 s34, s16, s30
	ds_read_b128 v[152:155], v164
	ds_read_b128 v[156:159], v164 offset:1024
	ds_read_b128 v[160:163], v164 offset:2048
	ds_read_b128 v[164:167], v164 offset:3072
	ds_read_b128 v[168:171], v180
	ds_read_b128 v[172:175], v180 offset:1024
	ds_read_b128 v[176:179], v180 offset:2048
	ds_read_b128 v[180:183], v180 offset:3072
	s_addc_u32 s35, s17, s31
	s_add_u32 s34, s34, 0x100
	s_addc_u32 s35, s35, 0
	s_add_u32 s64, s59, s30
	s_addc_u32 s65, s60, s31
	s_cmpk_eq_i32 s30, 0xf00
	s_cselect_b32 s37, s23, s35
	s_cselect_b32 s36, s61, s34
	s_cselect_b32 s35, s21, s65
	s_cselect_b32 s34, s62, s64
	v_lshl_add_u64 v[216:217], v[146:147], 0, s[30:31]
	s_add_i32 m0, s48, 0xc000
	ds_read_b128 v[184:187], v151
	ds_read_b128 v[188:191], v151 offset:1024
	ds_read_b128 v[192:195], v151 offset:2048
	ds_read_b128 v[196:199], v151 offset:3072
	ds_read_b128 v[200:203], v151 offset:4096
	ds_read_b128 v[204:207], v151 offset:5120
	ds_read_b128 v[208:211], v151 offset:6144
	ds_read_b128 v[212:215], v151 offset:7168
	global_load_lds_dwordx4 v[216:217], off
	v_lshl_add_u64 v[216:217], v[144:145], 0, s[30:31]
	s_add_i32 m0, s48, 0xe000
	s_nop 0
	global_load_lds_dwordx4 v[216:217], off
	s_waitcnt vmcnt(8)
	s_waitcnt lgkmcnt(0)
	s_barrier
	s_setprio 1
	v_mfma_f32_16x16x32_bf16 v[124:127], v[152:155], v[184:187], v[124:127]
	v_mfma_f32_16x16x32_bf16 v[120:123], v[160:163], v[184:187], v[120:123]
	v_mfma_f32_16x16x32_bf16 v[108:111], v[152:155], v[192:195], v[108:111]
	v_mfma_f32_16x16x32_bf16 v[104:107], v[160:163], v[192:195], v[104:107]
	v_mfma_f32_16x16x32_bf16 v[92:95], v[152:155], v[200:203], v[92:95]
	v_mfma_f32_16x16x32_bf16 v[88:91], v[160:163], v[200:203], v[88:91]
	v_mfma_f32_16x16x32_bf16 v[76:79], v[152:155], v[208:211], v[76:79]
	v_mfma_f32_16x16x32_bf16 v[72:75], v[160:163], v[208:211], v[72:75]
	v_mfma_f32_16x16x32_bf16 v[124:127], v[156:159], v[188:191], v[124:127]
	v_mfma_f32_16x16x32_bf16 v[120:123], v[164:167], v[188:191], v[120:123]
	v_mfma_f32_16x16x32_bf16 v[108:111], v[156:159], v[196:199], v[108:111]
	v_mfma_f32_16x16x32_bf16 v[104:107], v[164:167], v[196:199], v[104:107]
	v_mfma_f32_16x16x32_bf16 v[92:95], v[156:159], v[204:207], v[92:95]
	v_mfma_f32_16x16x32_bf16 v[88:91], v[164:167], v[204:207], v[88:91]
	v_mfma_f32_16x16x32_bf16 v[76:79], v[156:159], v[212:215], v[76:79]
	v_mfma_f32_16x16x32_bf16 v[72:75], v[164:167], v[212:215], v[72:75]
	v_mfma_f32_16x16x32_bf16 v[116:119], v[168:171], v[184:187], v[116:119]
	v_mfma_f32_16x16x32_bf16 v[112:115], v[176:179], v[184:187], v[112:115]
	v_mfma_f32_16x16x32_bf16 v[100:103], v[168:171], v[192:195], v[100:103]
	v_mfma_f32_16x16x32_bf16 v[96:99], v[176:179], v[192:195], v[96:99]
	v_mfma_f32_16x16x32_bf16 v[84:87], v[168:171], v[200:203], v[84:87]
	v_mfma_f32_16x16x32_bf16 v[80:83], v[176:179], v[200:203], v[80:83]
	v_mfma_f32_16x16x32_bf16 v[68:71], v[168:171], v[208:211], v[68:71]
	v_mfma_f32_16x16x32_bf16 v[64:67], v[176:179], v[208:211], v[64:67]
	v_mfma_f32_16x16x32_bf16 v[116:119], v[172:175], v[188:191], v[116:119]
	v_mfma_f32_16x16x32_bf16 v[112:115], v[180:183], v[188:191], v[112:115]
	v_mfma_f32_16x16x32_bf16 v[100:103], v[172:175], v[196:199], v[100:103]
	v_mfma_f32_16x16x32_bf16 v[96:99], v[180:183], v[196:199], v[96:99]
	v_mfma_f32_16x16x32_bf16 v[84:87], v[172:175], v[204:207], v[84:87]
	v_mfma_f32_16x16x32_bf16 v[80:83], v[180:183], v[204:207], v[80:83]
	v_mfma_f32_16x16x32_bf16 v[68:71], v[172:175], v[212:215], v[68:71]
	v_mfma_f32_16x16x32_bf16 v[64:67], v[180:183], v[212:215], v[64:67]
	s_setprio 0
	s_barrier
	s_add_i32 s64, s56, s47
	v_lshl_add_u64 v[216:217], s[34:35], 0, v[130:131]
	s_mov_b32 m0, s64
	ds_read_b128 v[184:187], v151 offset:16384
	ds_read_b128 v[188:191], v151 offset:17408
	ds_read_b128 v[192:195], v151 offset:18432
	ds_read_b128 v[196:199], v151 offset:19456
	ds_read_b128 v[200:203], v151 offset:20480
	ds_read_b128 v[204:207], v151 offset:21504
	ds_read_b128 v[208:211], v151 offset:22528
	ds_read_b128 v[212:215], v151 offset:23552
	global_load_lds_dwordx4 v[216:217], off
	s_add_i32 m0, s64, 0x2000
	s_add_u32 s64, s34, 0x80000
	v_lshl_add_u64 v[218:219], s[34:35], 0, v[134:135]
	s_addc_u32 s65, s35, 0
	s_add_i32 s66, s57, s47
	global_load_lds_dwordx4 v[218:219], off
	v_lshl_add_u64 v[220:221], s[64:65], 0, v[130:131]
	s_mov_b32 m0, s66
	v_lshl_add_u64 v[222:223], s[36:37], 0, v[132:133]
	global_load_lds_dwordx4 v[220:221], off
	v_lshl_add_u64 v[220:221], s[64:65], 0, v[134:135]
	s_add_i32 m0, s66, 0x2000
	s_nop 0
	global_load_lds_dwordx4 v[220:221], off
	v_lshl_add_u64 v[220:221], s[36:37], 0, v[128:129]
	s_mov_b32 m0, s48
	s_nop 0
	global_load_lds_dwordx4 v[220:221], off
	s_mov_b32 m0, s49
	s_nop 0
	global_load_lds_dwordx4 v[222:223], off
	s_waitcnt vmcnt(8)
	s_waitcnt lgkmcnt(0)
	s_barrier
	s_setprio 1
	v_mfma_f32_16x16x32_bf16 v[60:63], v[152:155], v[184:187], v[60:63]
	v_mfma_f32_16x16x32_bf16 v[56:59], v[160:163], v[184:187], v[56:59]
	v_mfma_f32_16x16x32_bf16 v[44:47], v[152:155], v[192:195], v[44:47]
	v_mfma_f32_16x16x32_bf16 v[40:43], v[160:163], v[192:195], v[40:43]
	v_mfma_f32_16x16x32_bf16 v[28:31], v[152:155], v[200:203], v[28:31]
	v_mfma_f32_16x16x32_bf16 v[24:27], v[160:163], v[200:203], v[24:27]
	v_mfma_f32_16x16x32_bf16 v[12:15], v[152:155], v[208:211], v[12:15]
	v_mfma_f32_16x16x32_bf16 v[8:11], v[160:163], v[208:211], v[8:11]
	v_mfma_f32_16x16x32_bf16 v[60:63], v[156:159], v[188:191], v[60:63]
	v_mfma_f32_16x16x32_bf16 v[56:59], v[164:167], v[188:191], v[56:59]
	v_mfma_f32_16x16x32_bf16 v[44:47], v[156:159], v[196:199], v[44:47]
	v_mfma_f32_16x16x32_bf16 v[40:43], v[164:167], v[196:199], v[40:43]
	v_mfma_f32_16x16x32_bf16 v[28:31], v[156:159], v[204:207], v[28:31]
	v_mfma_f32_16x16x32_bf16 v[24:27], v[164:167], v[204:207], v[24:27]
	v_mfma_f32_16x16x32_bf16 v[12:15], v[156:159], v[212:215], v[12:15]
	v_mfma_f32_16x16x32_bf16 v[8:11], v[164:167], v[212:215], v[8:11]
	v_mfma_f32_16x16x32_bf16 v[52:55], v[168:171], v[184:187], v[52:55]
	v_mfma_f32_16x16x32_bf16 v[48:51], v[176:179], v[184:187], v[48:51]
	v_mfma_f32_16x16x32_bf16 v[36:39], v[168:171], v[192:195], v[36:39]
	v_mfma_f32_16x16x32_bf16 v[32:35], v[176:179], v[192:195], v[32:35]
	v_mfma_f32_16x16x32_bf16 v[20:23], v[168:171], v[200:203], v[20:23]
	v_mfma_f32_16x16x32_bf16 v[16:19], v[176:179], v[200:203], v[16:19]
	v_mfma_f32_16x16x32_bf16 v[4:7], v[168:171], v[208:211], v[4:7]
	v_mfma_f32_16x16x32_bf16 v[0:3], v[176:179], v[208:211], v[0:3]
	v_mfma_f32_16x16x32_bf16 v[52:55], v[172:175], v[188:191], v[52:55]
	v_mfma_f32_16x16x32_bf16 v[48:51], v[180:183], v[188:191], v[48:51]
	v_mfma_f32_16x16x32_bf16 v[36:39], v[172:175], v[196:199], v[36:39]
	v_mfma_f32_16x16x32_bf16 v[32:35], v[180:183], v[196:199], v[32:35]
	v_mfma_f32_16x16x32_bf16 v[20:23], v[172:175], v[204:207], v[20:23]
	v_mfma_f32_16x16x32_bf16 v[16:19], v[180:183], v[204:207], v[16:19]
	v_mfma_f32_16x16x32_bf16 v[4:7], v[172:175], v[212:215], v[4:7]
	v_mfma_f32_16x16x32_bf16 v[0:3], v[180:183], v[212:215], v[0:3]
	s_setprio 0
	s_barrier
	s_add_i32 s64, 0, 0x18000
	s_add_i32 s65, 0, 0x1c000
	v_add_u32_e32 v164, s64, v150
	v_add_u32_e32 v180, s65, v150
	ds_read_b128 v[152:155], v164
	ds_read_b128 v[156:159], v164 offset:1024
	ds_read_b128 v[160:163], v164 offset:2048
	ds_read_b128 v[164:167], v164 offset:3072
	ds_read_b128 v[168:171], v180
	ds_read_b128 v[172:175], v180 offset:1024
	ds_read_b128 v[176:179], v180 offset:2048
	ds_read_b128 v[180:183], v180 offset:3072
	s_add_u32 s36, s36, 0x80000
	s_addc_u32 s37, s37, 0
	s_mov_b32 m0, s50
	v_lshl_add_u64 v[224:225], s[36:37], 0, v[128:129]
	ds_read_b128 v[184:187], v151 offset:32768
	ds_read_b128 v[188:191], v151 offset:33792
	ds_read_b128 v[192:195], v151 offset:34816
	ds_read_b128 v[196:199], v151 offset:35840
	ds_read_b128 v[200:203], v151 offset:36864
	ds_read_b128 v[204:207], v151 offset:37888
	ds_read_b128 v[208:211], v151 offset:38912
	ds_read_b128 v[212:215], v151 offset:39936
	global_load_lds_dwordx4 v[224:225], off
	v_lshl_add_u64 v[224:225], s[36:37], 0, v[132:133]
	s_mov_b32 m0, s51
	s_nop 0
	global_load_lds_dwordx4 v[224:225], off
	s_waitcnt vmcnt(8)
	s_waitcnt lgkmcnt(0)
	s_barrier
	s_setprio 1
	v_mfma_f32_16x16x32_bf16 v[124:127], v[152:155], v[184:187], v[124:127]
	v_mfma_f32_16x16x32_bf16 v[120:123], v[160:163], v[184:187], v[120:123]
	v_mfma_f32_16x16x32_bf16 v[108:111], v[152:155], v[192:195], v[108:111]
	v_mfma_f32_16x16x32_bf16 v[104:107], v[160:163], v[192:195], v[104:107]
	v_mfma_f32_16x16x32_bf16 v[92:95], v[152:155], v[200:203], v[92:95]
	v_mfma_f32_16x16x32_bf16 v[88:91], v[160:163], v[200:203], v[88:91]
	v_mfma_f32_16x16x32_bf16 v[76:79], v[152:155], v[208:211], v[76:79]
	v_mfma_f32_16x16x32_bf16 v[72:75], v[160:163], v[208:211], v[72:75]
	v_mfma_f32_16x16x32_bf16 v[124:127], v[156:159], v[188:191], v[124:127]
	v_mfma_f32_16x16x32_bf16 v[120:123], v[164:167], v[188:191], v[120:123]
	v_mfma_f32_16x16x32_bf16 v[108:111], v[156:159], v[196:199], v[108:111]
	v_mfma_f32_16x16x32_bf16 v[104:107], v[164:167], v[196:199], v[104:107]
	v_mfma_f32_16x16x32_bf16 v[92:95], v[156:159], v[204:207], v[92:95]
	v_mfma_f32_16x16x32_bf16 v[88:91], v[164:167], v[204:207], v[88:91]
	v_mfma_f32_16x16x32_bf16 v[76:79], v[156:159], v[212:215], v[76:79]
	v_mfma_f32_16x16x32_bf16 v[72:75], v[164:167], v[212:215], v[72:75]
	v_mfma_f32_16x16x32_bf16 v[116:119], v[168:171], v[184:187], v[116:119]
	v_mfma_f32_16x16x32_bf16 v[112:115], v[176:179], v[184:187], v[112:115]
	v_mfma_f32_16x16x32_bf16 v[100:103], v[168:171], v[192:195], v[100:103]
	v_mfma_f32_16x16x32_bf16 v[96:99], v[176:179], v[192:195], v[96:99]
	v_mfma_f32_16x16x32_bf16 v[84:87], v[168:171], v[200:203], v[84:87]
	v_mfma_f32_16x16x32_bf16 v[80:83], v[176:179], v[200:203], v[80:83]
	v_mfma_f32_16x16x32_bf16 v[68:71], v[168:171], v[208:211], v[68:71]
	v_mfma_f32_16x16x32_bf16 v[64:67], v[176:179], v[208:211], v[64:67]
	v_mfma_f32_16x16x32_bf16 v[116:119], v[172:175], v[188:191], v[116:119]
	v_mfma_f32_16x16x32_bf16 v[112:115], v[180:183], v[188:191], v[112:115]
	v_mfma_f32_16x16x32_bf16 v[100:103], v[172:175], v[196:199], v[100:103]
	v_mfma_f32_16x16x32_bf16 v[96:99], v[180:183], v[196:199], v[96:99]
	v_mfma_f32_16x16x32_bf16 v[84:87], v[172:175], v[204:207], v[84:87]
	v_mfma_f32_16x16x32_bf16 v[80:83], v[180:183], v[204:207], v[80:83]
	v_mfma_f32_16x16x32_bf16 v[68:71], v[172:175], v[212:215], v[68:71]
	v_mfma_f32_16x16x32_bf16 v[64:67], v[180:183], v[212:215], v[64:67]
	s_setprio 0
	s_barrier
	s_add_i32 s36, s64, s47
	v_lshl_add_u64 v[216:217], v[216:217], 0, s[18:19]
	s_mov_b32 m0, s36
	ds_read_b128 v[184:187], v151 offset:49152
	ds_read_b128 v[188:191], v151 offset:50176
	ds_read_b128 v[192:195], v151 offset:51200
	ds_read_b128 v[196:199], v151 offset:52224
	ds_read_b128 v[200:203], v151 offset:53248
	ds_read_b128 v[204:207], v151 offset:54272
	ds_read_b128 v[208:211], v151 offset:55296
	ds_read_b128 v[212:215], v151 offset:56320
	global_load_lds_dwordx4 v[216:217], off
	s_add_i32 m0, s36, 0x2000
	s_add_u32 s34, s34, 0x80080
	v_lshl_add_u64 v[216:217], v[218:219], 0, s[18:19]
	s_addc_u32 s35, s35, 0
	s_add_i32 s36, s65, s47
	global_load_lds_dwordx4 v[216:217], off
	v_lshl_add_u64 v[216:217], s[34:35], 0, v[130:131]
	s_mov_b32 m0, s36
	s_nop 0
	global_load_lds_dwordx4 v[216:217], off
	v_lshl_add_u64 v[216:217], s[34:35], 0, v[134:135]
	s_add_i32 m0, s36, 0x2000
	s_nop 0
	global_load_lds_dwordx4 v[216:217], off
	v_lshl_add_u64 v[216:217], v[220:221], 0, s[18:19]
	s_mov_b32 m0, s54
	s_nop 0
	global_load_lds_dwordx4 v[216:217], off
	v_lshl_add_u64 v[216:217], v[222:223], 0, s[18:19]
	s_mov_b32 m0, s55
	s_nop 0
	global_load_lds_dwordx4 v[216:217], off
	s_waitcnt vmcnt(8)
	s_waitcnt lgkmcnt(0)
	s_barrier
	s_setprio 1
	v_mfma_f32_16x16x32_bf16 v[60:63], v[152:155], v[184:187], v[60:63]
	v_mfma_f32_16x16x32_bf16 v[56:59], v[160:163], v[184:187], v[56:59]
	v_mfma_f32_16x16x32_bf16 v[44:47], v[152:155], v[192:195], v[44:47]
	v_mfma_f32_16x16x32_bf16 v[40:43], v[160:163], v[192:195], v[40:43]
	v_mfma_f32_16x16x32_bf16 v[28:31], v[152:155], v[200:203], v[28:31]
	v_mfma_f32_16x16x32_bf16 v[24:27], v[160:163], v[200:203], v[24:27]
	v_mfma_f32_16x16x32_bf16 v[12:15], v[152:155], v[208:211], v[12:15]
	v_mfma_f32_16x16x32_bf16 v[8:11], v[160:163], v[208:211], v[8:11]
	v_mfma_f32_16x16x32_bf16 v[60:63], v[156:159], v[188:191], v[60:63]
	v_mfma_f32_16x16x32_bf16 v[56:59], v[164:167], v[188:191], v[56:59]
	v_mfma_f32_16x16x32_bf16 v[44:47], v[156:159], v[196:199], v[44:47]
	v_mfma_f32_16x16x32_bf16 v[40:43], v[164:167], v[196:199], v[40:43]
	v_mfma_f32_16x16x32_bf16 v[28:31], v[156:159], v[204:207], v[28:31]
	v_mfma_f32_16x16x32_bf16 v[24:27], v[164:167], v[204:207], v[24:27]
	v_mfma_f32_16x16x32_bf16 v[12:15], v[156:159], v[212:215], v[12:15]
	v_mfma_f32_16x16x32_bf16 v[8:11], v[164:167], v[212:215], v[8:11]
	v_mfma_f32_16x16x32_bf16 v[52:55], v[168:171], v[184:187], v[52:55]
	v_mfma_f32_16x16x32_bf16 v[48:51], v[176:179], v[184:187], v[48:51]
	v_mfma_f32_16x16x32_bf16 v[36:39], v[168:171], v[192:195], v[36:39]
	v_mfma_f32_16x16x32_bf16 v[32:35], v[176:179], v[192:195], v[32:35]
	v_mfma_f32_16x16x32_bf16 v[20:23], v[168:171], v[200:203], v[20:23]
	v_mfma_f32_16x16x32_bf16 v[16:19], v[176:179], v[200:203], v[16:19]
	v_mfma_f32_16x16x32_bf16 v[4:7], v[168:171], v[208:211], v[4:7]
	v_mfma_f32_16x16x32_bf16 v[0:3], v[176:179], v[208:211], v[0:3]
	v_mfma_f32_16x16x32_bf16 v[52:55], v[172:175], v[188:191], v[52:55]
	v_mfma_f32_16x16x32_bf16 v[48:51], v[180:183], v[188:191], v[48:51]
	v_mfma_f32_16x16x32_bf16 v[36:39], v[172:175], v[196:199], v[36:39]
	v_mfma_f32_16x16x32_bf16 v[32:35], v[180:183], v[196:199], v[32:35]
	v_mfma_f32_16x16x32_bf16 v[20:23], v[172:175], v[204:207], v[20:23]
	v_mfma_f32_16x16x32_bf16 v[16:19], v[180:183], v[204:207], v[16:19]
	v_mfma_f32_16x16x32_bf16 v[4:7], v[172:175], v[212:215], v[4:7]
	v_mfma_f32_16x16x32_bf16 v[0:3], v[180:183], v[212:215], v[0:3]
	s_setprio 0
	s_barrier
	s_add_i32 s63, s63, 2
	s_add_u32 s30, s30, 0x100
	s_addc_u32 s31, s31, 0
	s_cmp_gt_u32 s63, 29
	s_cbranch_scc0 .LBB0_1227
	s_add_u32 s30, s59, 0xffffff00
	s_addc_u32 s31, s60, -1
	s_andn2_b64 vcc, exec, s[4:5]
	s_cbranch_vccnz .LBB0_1230
	v_mov_b32_e32 v0, 0
	s_mov_b32 s15, s20
	s_mov_b32 s14, s22
	s_mov_b64 s[16:17], s[26:27]
	s_mov_b32 s53, s58
	v_mov_b32_e32 v1, v0
	v_mov_b32_e32 v2, v0
	v_mov_b32_e32 v3, v0
	v_mov_b32_e32 v4, v0
	v_mov_b32_e32 v5, v0
	v_mov_b32_e32 v6, v0
	v_mov_b32_e32 v7, v0
	v_mov_b32_e32 v16, v0
	v_mov_b32_e32 v17, v0
	v_mov_b32_e32 v18, v0
	v_mov_b32_e32 v19, v0
	v_mov_b32_e32 v20, v0
	v_mov_b32_e32 v21, v0
	v_mov_b32_e32 v22, v0
	v_mov_b32_e32 v23, v0
	v_mov_b32_e32 v32, v0
	v_mov_b32_e32 v33, v0
	v_mov_b32_e32 v34, v0
	v_mov_b32_e32 v35, v0
	v_mov_b32_e32 v36, v0
	v_mov_b32_e32 v37, v0
	v_mov_b32_e32 v38, v0
	v_mov_b32_e32 v39, v0
	v_mov_b32_e32 v48, v0
	v_mov_b32_e32 v49, v0
	v_mov_b32_e32 v50, v0
	v_mov_b32_e32 v51, v0
	v_mov_b32_e32 v52, v0
	v_mov_b32_e32 v53, v0
	v_mov_b32_e32 v54, v0
	v_mov_b32_e32 v55, v0
	v_mov_b32_e32 v8, v0
	v_mov_b32_e32 v9, v0
	v_mov_b32_e32 v10, v0
	v_mov_b32_e32 v11, v0
	v_mov_b32_e32 v12, v0
	v_mov_b32_e32 v13, v0
	v_mov_b32_e32 v14, v0
	v_mov_b32_e32 v15, v0
	v_mov_b32_e32 v24, v0
	v_mov_b32_e32 v25, v0
	v_mov_b32_e32 v26, v0
	v_mov_b32_e32 v27, v0
	v_mov_b32_e32 v28, v0
	v_mov_b32_e32 v29, v0
	v_mov_b32_e32 v30, v0
	v_mov_b32_e32 v31, v0
	v_mov_b32_e32 v40, v0
	v_mov_b32_e32 v41, v0
	v_mov_b32_e32 v42, v0
	v_mov_b32_e32 v43, v0
	v_mov_b32_e32 v44, v0
	v_mov_b32_e32 v45, v0
	v_mov_b32_e32 v46, v0
	v_mov_b32_e32 v47, v0
	v_mov_b32_e32 v56, v0
	v_mov_b32_e32 v57, v0
	v_mov_b32_e32 v58, v0
	v_mov_b32_e32 v59, v0
	v_mov_b32_e32 v60, v0
	v_mov_b32_e32 v61, v0
	v_mov_b32_e32 v62, v0
	v_mov_b32_e32 v63, v0
	v_mov_b32_e32 v64, v0
	v_mov_b32_e32 v65, v0
	v_mov_b32_e32 v66, v0
	v_mov_b32_e32 v67, v0
	v_mov_b32_e32 v68, v0
	v_mov_b32_e32 v69, v0
	v_mov_b32_e32 v70, v0
	v_mov_b32_e32 v71, v0
	v_mov_b32_e32 v80, v0
	v_mov_b32_e32 v81, v0
	v_mov_b32_e32 v82, v0
	v_mov_b32_e32 v83, v0
	v_mov_b32_e32 v84, v0
	v_mov_b32_e32 v85, v0
	v_mov_b32_e32 v86, v0
	v_mov_b32_e32 v87, v0
	v_mov_b32_e32 v96, v0
	v_mov_b32_e32 v97, v0
	v_mov_b32_e32 v98, v0
	v_mov_b32_e32 v99, v0
	v_mov_b32_e32 v100, v0
	v_mov_b32_e32 v101, v0
	v_mov_b32_e32 v102, v0
	v_mov_b32_e32 v103, v0
	v_mov_b32_e32 v112, v0
	v_mov_b32_e32 v113, v0
	v_mov_b32_e32 v114, v0
	v_mov_b32_e32 v115, v0
	v_mov_b32_e32 v116, v0
	v_mov_b32_e32 v117, v0
	v_mov_b32_e32 v118, v0
	v_mov_b32_e32 v119, v0
	v_mov_b32_e32 v72, v0
	v_mov_b32_e32 v73, v0
	v_mov_b32_e32 v74, v0
	v_mov_b32_e32 v75, v0
	v_mov_b32_e32 v76, v0
	v_mov_b32_e32 v77, v0
	v_mov_b32_e32 v78, v0
	v_mov_b32_e32 v79, v0
	v_mov_b32_e32 v88, v0
	v_mov_b32_e32 v89, v0
	v_mov_b32_e32 v90, v0
	v_mov_b32_e32 v91, v0
	v_mov_b32_e32 v92, v0
	v_mov_b32_e32 v93, v0
	v_mov_b32_e32 v94, v0
	v_mov_b32_e32 v95, v0
	v_mov_b32_e32 v104, v0
	v_mov_b32_e32 v105, v0
	v_mov_b32_e32 v106, v0
	v_mov_b32_e32 v107, v0
	v_mov_b32_e32 v108, v0
	v_mov_b32_e32 v109, v0
	v_mov_b32_e32 v110, v0
	v_mov_b32_e32 v111, v0
	v_mov_b32_e32 v120, v0
	v_mov_b32_e32 v121, v0
	v_mov_b32_e32 v122, v0
	v_mov_b32_e32 v123, v0
	v_mov_b32_e32 v124, v0
	v_mov_b32_e32 v125, v0
	v_mov_b32_e32 v126, v0
	v_mov_b32_e32 v127, v0
	s_andn2_b64 vcc, exec, s[0:1]
	s_cbranch_vccnz .LBB0_1231
	s_branch .LBB0_1232
